# nosig_rbacc3
# baseline (speedup 1.0000x reference)
; __device__ __forceinline__ float bf_lo(unsigned w) { return __uint_as_float(w << 16); }
; __device__ __forceinline__ float bf_hi(unsigned w) { return __uint_as_float(w & 0xffff0000u); }
;     __device__ __forceinline__ void operator()(const f32x4 (&acc)[2][2][4][2], const Unit& u, int wr, int wc, int fr, int fq) const {
;     ...
;                 for (int bj = 0; bj < 2; ++bj) { const int row = row0 + ai * HALF + m * 16, col = col0 + bj * HALF;
;                     gv[m][bj] = *(const u32x4*)(G + (size_t)row * NGATE + br * 2048 + col);
;                     if (br > 0) { bf16_t* mp = Mg + (size_t)row * DM + col;
;                         q0[m][bj] = __hip_atomic_load((unsigned long long*)mp, __ATOMIC_RELAXED, __HIP_MEMORY_SCOPE_AGENT);
;                         q1[m][bj] = __hip_atomic_load((unsigned long long*)mp + 1, __ATOMIC_RELAXED, __HIP_MEMORY_SCOPE_AGENT); } }
; #pragma unroll
;             for (int m = 0; m < 4; ++m)
; #pragma unroll
;                 for (int bj = 0; bj < 2; ++bj) { const int row = row0 + ai * HALF + m * 16, col = col0 + bj * HALF; const u32x4 g4 = gv[m][bj];
;                     const f32x4 a0 = acc[ai][bj][m][0], a1 = acc[ai][bj][m][1];
;                     float f0 = a0[0] * bf_lo(g4.x), f1 = a0[1] * bf_hi(g4.x), f2 = a0[2] * bf_lo(g4.y), f3 = a0[3] * bf_hi(g4.y);
;                     float f4 = a1[0] * bf_lo(g4.z), f5 = a1[1] * bf_hi(g4.z), f6 = a1[2] * bf_lo(g4.w), f7 = a1[3] * bf_hi(g4.w);
;                     if (br > 0) {
;                         const unsigned p0 = (unsigned)q0[m][bj], p1 = (unsigned)(q0[m][bj] >> 32), p2 = (unsigned)q1[m][bj], p3 = (unsigned)(q1[m][bj] >> 32);
;                         f0 += bf_lo(p0); f1 += bf_hi(p0); f2 += bf_lo(p1); f3 += bf_hi(p1); f4 += bf_lo(p2); f5 += bf_hi(p2); f6 += bf_lo(p3); f7 += bf_hi(p3);
.LBB0_89:
	s_lshl_b32 s8, s8, 8
	s_lshl_b32 s9, s42, 8
	s_and_b32 s8, s8, 0x700
	v_mov_b32_e32 v130, v171
	v_mov_b32_e32 v131, v239
	s_ashr_i32 s27, s42, 6
	s_and_b32 s9, s9, 0x3f00
	s_or_b32 s8, s8, s73
	s_add_i32 s9, s9, s67
	v_lshl_add_u32 v218, v131, 3, s8
	s_lshl_b32 s8, s27, 11
	v_add_u32_e32 v220, s9, v130
	s_ashr_i32 s9, s8, 31
	s_cmp_gt_i32 s27, 0
	s_cselect_b64 s[44:45], -1, 0
	s_lshl_b64 s[8:9], s[8:9], 1
	s_add_u32 s42, s63, s8
	s_addc_u32 s43, s66, s9
	v_mov_b64_e32 v[130:131], s[42:43]
	s_movk_i32 s8, 0x3000
	v_mad_i64_i32 v[130:131], s[8:9], v220, s8, v[130:131]
	v_ashrrev_i32_e32 v219, 31, v218
	v_lshl_add_u64 v[130:131], v[218:219], 1, v[130:131]
	v_ashrrev_i32_e32 v221, 31, v220
	v_lshlrev_b64 v[226:227], 12, v[220:221]
	v_lshl_add_u64 v[226:227], s[14:15], 0, v[226:227]
	v_lshl_add_u64 v[226:227], v[218:219], 1, v[226:227]
	v_mov_b32_e32 v222, v130
	v_mov_b32_e32 v223, v131
	v_mov_b32_e32 v228, 0x1000
	v_mov_b32_e32 v229, 0
	v_lshl_add_u64 v[224:225], v[222:223], 0, v[228:229]
	s_mov_b32 s8, 0x30000
	s_mov_b32 s9, 0
	s_mov_b32 s46, 0x10000
	s_mov_b32 s47, 0
	s_mov_b32 s44, 0xf0000
	s_mov_b32 s45, 0
	s_mov_b32 s42, 0x50000
	s_mov_b32 s43, 0
	s_cmp_eq_u32 s27, 2
	s_cbranch_scc1 .Lrb_final
	s_mov_b32 s44, 0x180000
	v_lshl_add_u64 v[226:227], v[222:223], 0, s[44:45]
	v_lshl_add_u64 v[228:229], v[224:225], 0, s[44:45]
	global_load_dwordx4 v[130:133], v[222:223], off
	global_load_dwordx4 v[186:189], v[224:225], off
	global_load_dwordx4 v[134:137], v[222:223], off offset:256
	global_load_dwordx4 v[190:193], v[224:225], off offset:256
	v_lshl_add_u64 v[222:223], v[222:223], 0, s[8:9]
	v_lshl_add_u64 v[224:225], v[224:225], 0, s[8:9]
	global_load_dwordx4 v[138:141], v[222:223], off
	global_load_dwordx4 v[194:197], v[224:225], off
	global_load_dwordx4 v[142:145], v[222:223], off offset:256
	global_load_dwordx4 v[198:201], v[224:225], off offset:256
	v_lshl_add_u64 v[222:223], v[222:223], 0, s[8:9]
	v_lshl_add_u64 v[224:225], v[224:225], 0, s[8:9]
	global_load_dwordx4 v[146:149], v[222:223], off
	global_load_dwordx4 v[202:205], v[224:225], off
	global_load_dwordx4 v[150:153], v[222:223], off offset:256
	global_load_dwordx4 v[206:209], v[224:225], off offset:256
	v_lshl_add_u64 v[222:223], v[222:223], 0, s[8:9]
	v_lshl_add_u64 v[224:225], v[224:225], 0, s[8:9]
	global_load_dwordx4 v[154:157], v[222:223], off
	global_load_dwordx4 v[210:213], v[224:225], off
	global_load_dwordx4 v[158:161], v[222:223], off offset:256
	global_load_dwordx4 v[214:217], v[224:225], off offset:256
	s_waitcnt vmcnt(12)
	v_lshlrev_b32_e32 v218, 16, v130
	v_and_b32_e32 v219, 0xffff0000, v130
	v_lshlrev_b32_e32 v220, 16, v186
	v_and_b32_e32 v221, 0xffff0000, v186
	v_max_f32_e32 v218, 0xc2700000, v218
	v_max_f32_e32 v219, 0xc2700000, v219
	v_max_f32_e32 v220, 0xc2700000, v220
	v_max_f32_e32 v221, 0xc2700000, v221
	v_mul_f32_e32 v218, 0xbfb8aa3b, v218
	v_mul_f32_e32 v219, 0xbfb8aa3b, v219
	v_mul_f32_e32 v220, 0xbfb8aa3b, v220
	v_mul_f32_e32 v221, 0xbfb8aa3b, v221
	v_exp_f32_e32 v218, v218
	v_exp_f32_e32 v219, v219
	v_exp_f32_e32 v220, v220
	v_exp_f32_e32 v221, v221
	v_add_f32_e32 v218, 1.0, v218
	v_add_f32_e32 v219, 1.0, v219
	v_add_f32_e32 v220, 1.0, v220
	v_add_f32_e32 v221, 1.0, v221
	v_rcp_f32_e32 v218, v218
	v_rcp_f32_e32 v219, v219
	v_mul_f32_e32 v218, v218, v220
	v_mul_f32_e32 v219, v219, v221
	v_pk_mul_f32 v[126:127], v[126:127], v[218:219]
	v_lshlrev_b32_e32 v242, 16, v131
	v_and_b32_e32 v243, 0xffff0000, v131
	v_lshlrev_b32_e32 v246, 16, v187
	v_and_b32_e32 v247, 0xffff0000, v187
	v_max_f32_e32 v242, 0xc2700000, v242
	v_max_f32_e32 v243, 0xc2700000, v243
	v_max_f32_e32 v246, 0xc2700000, v246
	v_max_f32_e32 v247, 0xc2700000, v247
	v_mul_f32_e32 v242, 0xbfb8aa3b, v242
	v_mul_f32_e32 v243, 0xbfb8aa3b, v243
	v_mul_f32_e32 v246, 0xbfb8aa3b, v246
	v_mul_f32_e32 v247, 0xbfb8aa3b, v247
	v_exp_f32_e32 v242, v242
	v_exp_f32_e32 v243, v243
	v_exp_f32_e32 v246, v246
	v_exp_f32_e32 v247, v247
	v_add_f32_e32 v242, 1.0, v242
	v_add_f32_e32 v243, 1.0, v243
	v_add_f32_e32 v246, 1.0, v246
	v_add_f32_e32 v247, 1.0, v247
	v_rcp_f32_e32 v242, v242
	v_rcp_f32_e32 v243, v243
	v_mul_f32_e32 v242, v242, v246
	v_mul_f32_e32 v243, v243, v247
	v_pk_mul_f32 v[128:129], v[128:129], v[242:243]
	v_lshlrev_b32_e32 v218, 16, v132
	v_and_b32_e32 v219, 0xffff0000, v132
	v_lshlrev_b32_e32 v220, 16, v188
	v_and_b32_e32 v221, 0xffff0000, v188
	v_max_f32_e32 v218, 0xc2700000, v218
	v_max_f32_e32 v219, 0xc2700000, v219
	v_max_f32_e32 v220, 0xc2700000, v220
	v_max_f32_e32 v221, 0xc2700000, v221
	v_mul_f32_e32 v218, 0xbfb8aa3b, v218
	v_mul_f32_e32 v219, 0xbfb8aa3b, v219
	v_mul_f32_e32 v220, 0xbfb8aa3b, v220
	v_mul_f32_e32 v221, 0xbfb8aa3b, v221
	v_exp_f32_e32 v218, v218
	v_exp_f32_e32 v219, v219
	v_exp_f32_e32 v220, v220
	v_exp_f32_e32 v221, v221
	v_add_f32_e32 v218, 1.0, v218
	v_add_f32_e32 v219, 1.0, v219
	v_add_f32_e32 v220, 1.0, v220
	v_add_f32_e32 v221, 1.0, v221
	v_rcp_f32_e32 v218, v218
	v_rcp_f32_e32 v219, v219
	v_mul_f32_e32 v218, v218, v220
	v_mul_f32_e32 v219, v219, v221
	v_pk_mul_f32 v[122:123], v[122:123], v[218:219]
	v_lshlrev_b32_e32 v242, 16, v133
	v_and_b32_e32 v243, 0xffff0000, v133
	v_lshlrev_b32_e32 v246, 16, v189
	v_and_b32_e32 v247, 0xffff0000, v189
	v_max_f32_e32 v242, 0xc2700000, v242
	v_max_f32_e32 v243, 0xc2700000, v243
	v_max_f32_e32 v246, 0xc2700000, v246
	v_max_f32_e32 v247, 0xc2700000, v247
	v_mul_f32_e32 v242, 0xbfb8aa3b, v242
	v_mul_f32_e32 v243, 0xbfb8aa3b, v243
	v_mul_f32_e32 v246, 0xbfb8aa3b, v246
	v_mul_f32_e32 v247, 0xbfb8aa3b, v247
	v_exp_f32_e32 v242, v242
	v_exp_f32_e32 v243, v243
	v_exp_f32_e32 v246, v246
	v_exp_f32_e32 v247, v247
	v_add_f32_e32 v242, 1.0, v242
; __device__ __forceinline__ float bf_lo(unsigned w) { return __uint_as_float(w << 16); }
; __device__ __forceinline__ float bf_hi(unsigned w) { return __uint_as_float(w & 0xffff0000u); }
;     __device__ __forceinline__ void operator()(const f32x4 (&acc)[2][2][4][2], const Unit& u, int wr, int wc, int fr, int fq) const {
;     ...
;                 for (int bj = 0; bj < 2; ++bj) { const int row = row0 + ai * HALF + m * 16, col = col0 + bj * HALF;
;                     gv[m][bj] = *(const u32x4*)(G + (size_t)row * NGATE + br * 2048 + col);
;                     if (br > 0) { bf16_t* mp = Mg + (size_t)row * DM + col;
;                         q0[m][bj] = __hip_atomic_load((unsigned long long*)mp, __ATOMIC_RELAXED, __HIP_MEMORY_SCOPE_AGENT);
;                         q1[m][bj] = __hip_atomic_load((unsigned long long*)mp + 1, __ATOMIC_RELAXED, __HIP_MEMORY_SCOPE_AGENT); } }
; #pragma unroll
;             for (int m = 0; m < 4; ++m)
; #pragma unroll
;                 for (int bj = 0; bj < 2; ++bj) { const int row = row0 + ai * HALF + m * 16, col = col0 + bj * HALF; const u32x4 g4 = gv[m][bj];
;                     const f32x4 a0 = acc[ai][bj][m][0], a1 = acc[ai][bj][m][1];
;                     float f0 = a0[0] * bf_lo(g4.x), f1 = a0[1] * bf_hi(g4.x), f2 = a0[2] * bf_lo(g4.y), f3 = a0[3] * bf_hi(g4.y);
;                     float f4 = a1[0] * bf_lo(g4.z), f5 = a1[1] * bf_hi(g4.z), f6 = a1[2] * bf_lo(g4.w), f7 = a1[3] * bf_hi(g4.w);
;                     if (br > 0) {
;                         const unsigned p0 = (unsigned)q0[m][bj], p1 = (unsigned)(q0[m][bj] >> 32), p2 = (unsigned)q1[m][bj], p3 = (unsigned)(q1[m][bj] >> 32);
;                         f0 += bf_lo(p0); f1 += bf_hi(p0); f2 += bf_lo(p1); f3 += bf_hi(p1); f4 += bf_lo(p2); f5 += bf_hi(p2); f6 += bf_lo(p3); f7 += bf_hi(p3);
	v_add_f32_e32 v243, 1.0, v243
	v_add_f32_e32 v246, 1.0, v246
	v_add_f32_e32 v247, 1.0, v247
	v_rcp_f32_e32 v242, v242
	v_rcp_f32_e32 v243, v243
	v_mul_f32_e32 v242, v242, v246
	v_mul_f32_e32 v243, v243, v247
	v_pk_mul_f32 v[124:125], v[124:125], v[242:243]
	v_lshlrev_b32_e32 v218, 16, v134
	v_and_b32_e32 v219, 0xffff0000, v134
	v_lshlrev_b32_e32 v220, 16, v190
	v_and_b32_e32 v221, 0xffff0000, v190
	v_max_f32_e32 v218, 0xc2700000, v218
	v_max_f32_e32 v219, 0xc2700000, v219
	v_max_f32_e32 v220, 0xc2700000, v220
	v_max_f32_e32 v221, 0xc2700000, v221
	v_mul_f32_e32 v218, 0xbfb8aa3b, v218
	v_mul_f32_e32 v219, 0xbfb8aa3b, v219
	v_mul_f32_e32 v220, 0xbfb8aa3b, v220
	v_mul_f32_e32 v221, 0xbfb8aa3b, v221
	v_exp_f32_e32 v218, v218
	v_exp_f32_e32 v219, v219
	v_exp_f32_e32 v220, v220
	v_exp_f32_e32 v221, v221
	v_add_f32_e32 v218, 1.0, v218
	v_add_f32_e32 v219, 1.0, v219
	v_add_f32_e32 v220, 1.0, v220
	v_add_f32_e32 v221, 1.0, v221
	v_rcp_f32_e32 v218, v218
	v_rcp_f32_e32 v219, v219
	v_mul_f32_e32 v218, v218, v220
	v_mul_f32_e32 v219, v219, v221
	v_pk_mul_f32 v[118:119], v[118:119], v[218:219]
	v_lshlrev_b32_e32 v242, 16, v135
	v_and_b32_e32 v243, 0xffff0000, v135
	v_lshlrev_b32_e32 v246, 16, v191
	v_and_b32_e32 v247, 0xffff0000, v191
	v_max_f32_e32 v242, 0xc2700000, v242
	v_max_f32_e32 v243, 0xc2700000, v243
	v_max_f32_e32 v246, 0xc2700000, v246
	v_max_f32_e32 v247, 0xc2700000, v247
	v_mul_f32_e32 v242, 0xbfb8aa3b, v242
	v_mul_f32_e32 v243, 0xbfb8aa3b, v243
	v_mul_f32_e32 v246, 0xbfb8aa3b, v246
	v_mul_f32_e32 v247, 0xbfb8aa3b, v247
	v_exp_f32_e32 v242, v242
	v_exp_f32_e32 v243, v243
	v_exp_f32_e32 v246, v246
	v_exp_f32_e32 v247, v247
	v_add_f32_e32 v242, 1.0, v242
	v_add_f32_e32 v243, 1.0, v243
	v_add_f32_e32 v246, 1.0, v246
	v_add_f32_e32 v247, 1.0, v247
	v_rcp_f32_e32 v242, v242
	v_rcp_f32_e32 v243, v243
	v_mul_f32_e32 v242, v242, v246
	v_mul_f32_e32 v243, v243, v247
	v_pk_mul_f32 v[120:121], v[120:121], v[242:243]
	v_lshlrev_b32_e32 v218, 16, v136
	v_and_b32_e32 v219, 0xffff0000, v136
	v_lshlrev_b32_e32 v220, 16, v192
	v_and_b32_e32 v221, 0xffff0000, v192
	v_max_f32_e32 v218, 0xc2700000, v218
	v_max_f32_e32 v219, 0xc2700000, v219
	v_max_f32_e32 v220, 0xc2700000, v220
	v_max_f32_e32 v221, 0xc2700000, v221
	v_mul_f32_e32 v218, 0xbfb8aa3b, v218
	v_mul_f32_e32 v219, 0xbfb8aa3b, v219
	v_mul_f32_e32 v220, 0xbfb8aa3b, v220
	v_mul_f32_e32 v221, 0xbfb8aa3b, v221
	v_exp_f32_e32 v218, v218
	v_exp_f32_e32 v219, v219
	v_exp_f32_e32 v220, v220
	v_exp_f32_e32 v221, v221
	v_add_f32_e32 v218, 1.0, v218
	v_add_f32_e32 v219, 1.0, v219
	v_add_f32_e32 v220, 1.0, v220
	v_add_f32_e32 v221, 1.0, v221
	v_rcp_f32_e32 v218, v218
	v_rcp_f32_e32 v219, v219
	v_mul_f32_e32 v218, v218, v220
	v_mul_f32_e32 v219, v219, v221
	v_pk_mul_f32 v[114:115], v[114:115], v[218:219]
	v_lshlrev_b32_e32 v242, 16, v137
	v_and_b32_e32 v243, 0xffff0000, v137
	v_lshlrev_b32_e32 v246, 16, v193
	v_and_b32_e32 v247, 0xffff0000, v193
	v_max_f32_e32 v242, 0xc2700000, v242
	v_max_f32_e32 v243, 0xc2700000, v243
	v_max_f32_e32 v246, 0xc2700000, v246
	v_max_f32_e32 v247, 0xc2700000, v247
	v_mul_f32_e32 v242, 0xbfb8aa3b, v242
	v_mul_f32_e32 v243, 0xbfb8aa3b, v243
	v_mul_f32_e32 v246, 0xbfb8aa3b, v246
	v_mul_f32_e32 v247, 0xbfb8aa3b, v247
	v_exp_f32_e32 v242, v242
	v_exp_f32_e32 v243, v243
	v_exp_f32_e32 v246, v246
	v_exp_f32_e32 v247, v247
	v_add_f32_e32 v242, 1.0, v242
	v_add_f32_e32 v243, 1.0, v243
	v_add_f32_e32 v246, 1.0, v246
	v_add_f32_e32 v247, 1.0, v247
	v_rcp_f32_e32 v242, v242
	v_rcp_f32_e32 v243, v243
	v_mul_f32_e32 v242, v242, v246
	v_mul_f32_e32 v243, v243, v247
	v_pk_mul_f32 v[116:117], v[116:117], v[242:243]
	global_load_dwordx4 v[130:133], v[226:227], off
	global_load_dwordx4 v[186:189], v[228:229], off
	global_load_dwordx4 v[134:137], v[226:227], off offset:256
	global_load_dwordx4 v[190:193], v[228:229], off offset:256
	s_waitcnt vmcnt(12)
	v_lshlrev_b32_e32 v218, 16, v138
	v_and_b32_e32 v219, 0xffff0000, v138
	v_lshlrev_b32_e32 v220, 16, v194
	v_and_b32_e32 v221, 0xffff0000, v194
	v_max_f32_e32 v218, 0xc2700000, v218
	v_max_f32_e32 v219, 0xc2700000, v219
	v_max_f32_e32 v220, 0xc2700000, v220
	v_max_f32_e32 v221, 0xc2700000, v221
	v_mul_f32_e32 v218, 0xbfb8aa3b, v218
	v_mul_f32_e32 v219, 0xbfb8aa3b, v219
	v_mul_f32_e32 v220, 0xbfb8aa3b, v220
	v_mul_f32_e32 v221, 0xbfb8aa3b, v221
	v_exp_f32_e32 v218, v218
	v_exp_f32_e32 v219, v219
	v_exp_f32_e32 v220, v220
	v_exp_f32_e32 v221, v221
	v_add_f32_e32 v218, 1.0, v218
	v_add_f32_e32 v219, 1.0, v219
	v_add_f32_e32 v220, 1.0, v220
	v_add_f32_e32 v221, 1.0, v221
	v_rcp_f32_e32 v218, v218
	v_rcp_f32_e32 v219, v219
	v_mul_f32_e32 v218, v218, v220
	v_mul_f32_e32 v219, v219, v221
	v_pk_mul_f32 v[110:111], v[110:111], v[218:219]
	v_lshlrev_b32_e32 v242, 16, v139
	v_and_b32_e32 v243, 0xffff0000, v139
	v_lshlrev_b32_e32 v246, 16, v195
	v_and_b32_e32 v247, 0xffff0000, v195
	v_max_f32_e32 v242, 0xc2700000, v242
	v_max_f32_e32 v243, 0xc2700000, v243
	v_max_f32_e32 v246, 0xc2700000, v246
	v_max_f32_e32 v247, 0xc2700000, v247
	v_mul_f32_e32 v242, 0xbfb8aa3b, v242
	v_mul_f32_e32 v243, 0xbfb8aa3b, v243
	v_mul_f32_e32 v246, 0xbfb8aa3b, v246
	v_mul_f32_e32 v247, 0xbfb8aa3b, v247
	v_exp_f32_e32 v242, v242
	v_exp_f32_e32 v243, v243
	v_exp_f32_e32 v246, v246
	v_exp_f32_e32 v247, v247
	v_add_f32_e32 v242, 1.0, v242
	v_add_f32_e32 v243, 1.0, v243
	v_add_f32_e32 v246, 1.0, v246
	v_add_f32_e32 v247, 1.0, v247
	v_rcp_f32_e32 v242, v242
	v_rcp_f32_e32 v243, v243
	v_mul_f32_e32 v242, v242, v246
	v_mul_f32_e32 v243, v243, v247
	v_pk_mul_f32 v[112:113], v[112:113], v[242:243]
	v_lshlrev_b32_e32 v218, 16, v140
	v_and_b32_e32 v219, 0xffff0000, v140
	v_lshlrev_b32_e32 v220, 16, v196
; __device__ __forceinline__ float bf_lo(unsigned w) { return __uint_as_float(w << 16); }
; __device__ __forceinline__ float bf_hi(unsigned w) { return __uint_as_float(w & 0xffff0000u); }
;     __device__ __forceinline__ void operator()(const f32x4 (&acc)[2][2][4][2], const Unit& u, int wr, int wc, int fr, int fq) const {
;     ...
;                 for (int bj = 0; bj < 2; ++bj) { const int row = row0 + ai * HALF + m * 16, col = col0 + bj * HALF;
;                     gv[m][bj] = *(const u32x4*)(G + (size_t)row * NGATE + br * 2048 + col);
;                     if (br > 0) { bf16_t* mp = Mg + (size_t)row * DM + col;
;                         q0[m][bj] = __hip_atomic_load((unsigned long long*)mp, __ATOMIC_RELAXED, __HIP_MEMORY_SCOPE_AGENT);
;                         q1[m][bj] = __hip_atomic_load((unsigned long long*)mp + 1, __ATOMIC_RELAXED, __HIP_MEMORY_SCOPE_AGENT); } }
; #pragma unroll
;             for (int m = 0; m < 4; ++m)
; #pragma unroll
;                 for (int bj = 0; bj < 2; ++bj) { const int row = row0 + ai * HALF + m * 16, col = col0 + bj * HALF; const u32x4 g4 = gv[m][bj];
;                     const f32x4 a0 = acc[ai][bj][m][0], a1 = acc[ai][bj][m][1];
;                     float f0 = a0[0] * bf_lo(g4.x), f1 = a0[1] * bf_hi(g4.x), f2 = a0[2] * bf_lo(g4.y), f3 = a0[3] * bf_hi(g4.y);
;                     float f4 = a1[0] * bf_lo(g4.z), f5 = a1[1] * bf_hi(g4.z), f6 = a1[2] * bf_lo(g4.w), f7 = a1[3] * bf_hi(g4.w);
;                     if (br > 0) {
;                         const unsigned p0 = (unsigned)q0[m][bj], p1 = (unsigned)(q0[m][bj] >> 32), p2 = (unsigned)q1[m][bj], p3 = (unsigned)(q1[m][bj] >> 32);
;                         f0 += bf_lo(p0); f1 += bf_hi(p0); f2 += bf_lo(p1); f3 += bf_hi(p1); f4 += bf_lo(p2); f5 += bf_hi(p2); f6 += bf_lo(p3); f7 += bf_hi(p3);
	v_and_b32_e32 v221, 0xffff0000, v196
	v_max_f32_e32 v218, 0xc2700000, v218
	v_max_f32_e32 v219, 0xc2700000, v219
	v_max_f32_e32 v220, 0xc2700000, v220
	v_max_f32_e32 v221, 0xc2700000, v221
	v_mul_f32_e32 v218, 0xbfb8aa3b, v218
	v_mul_f32_e32 v219, 0xbfb8aa3b, v219
	v_mul_f32_e32 v220, 0xbfb8aa3b, v220
	v_mul_f32_e32 v221, 0xbfb8aa3b, v221
	v_exp_f32_e32 v218, v218
	v_exp_f32_e32 v219, v219
	v_exp_f32_e32 v220, v220
	v_exp_f32_e32 v221, v221
	v_add_f32_e32 v218, 1.0, v218
	v_add_f32_e32 v219, 1.0, v219
	v_add_f32_e32 v220, 1.0, v220
	v_add_f32_e32 v221, 1.0, v221
	v_rcp_f32_e32 v218, v218
	v_rcp_f32_e32 v219, v219
	v_mul_f32_e32 v218, v218, v220
	v_mul_f32_e32 v219, v219, v221
	v_pk_mul_f32 v[106:107], v[106:107], v[218:219]
	v_lshlrev_b32_e32 v242, 16, v141
	v_and_b32_e32 v243, 0xffff0000, v141
	v_lshlrev_b32_e32 v246, 16, v197
	v_and_b32_e32 v247, 0xffff0000, v197
	v_max_f32_e32 v242, 0xc2700000, v242
	v_max_f32_e32 v243, 0xc2700000, v243
	v_max_f32_e32 v246, 0xc2700000, v246
	v_max_f32_e32 v247, 0xc2700000, v247
	v_mul_f32_e32 v242, 0xbfb8aa3b, v242
	v_mul_f32_e32 v243, 0xbfb8aa3b, v243
	v_mul_f32_e32 v246, 0xbfb8aa3b, v246
	v_mul_f32_e32 v247, 0xbfb8aa3b, v247
	v_exp_f32_e32 v242, v242
	v_exp_f32_e32 v243, v243
	v_exp_f32_e32 v246, v246
	v_exp_f32_e32 v247, v247
	v_add_f32_e32 v242, 1.0, v242
	v_add_f32_e32 v243, 1.0, v243
	v_add_f32_e32 v246, 1.0, v246
	v_add_f32_e32 v247, 1.0, v247
	v_rcp_f32_e32 v242, v242
	v_rcp_f32_e32 v243, v243
	v_mul_f32_e32 v242, v242, v246
	v_mul_f32_e32 v243, v243, v247
	v_pk_mul_f32 v[108:109], v[108:109], v[242:243]
	v_lshlrev_b32_e32 v218, 16, v142
	v_and_b32_e32 v219, 0xffff0000, v142
	v_lshlrev_b32_e32 v220, 16, v198
	v_and_b32_e32 v221, 0xffff0000, v198
	v_max_f32_e32 v218, 0xc2700000, v218
	v_max_f32_e32 v219, 0xc2700000, v219
	v_max_f32_e32 v220, 0xc2700000, v220
	v_max_f32_e32 v221, 0xc2700000, v221
	v_mul_f32_e32 v218, 0xbfb8aa3b, v218
	v_mul_f32_e32 v219, 0xbfb8aa3b, v219
	v_mul_f32_e32 v220, 0xbfb8aa3b, v220
	v_mul_f32_e32 v221, 0xbfb8aa3b, v221
	v_exp_f32_e32 v218, v218
	v_exp_f32_e32 v219, v219
	v_exp_f32_e32 v220, v220
	v_exp_f32_e32 v221, v221
	v_add_f32_e32 v218, 1.0, v218
	v_add_f32_e32 v219, 1.0, v219
	v_add_f32_e32 v220, 1.0, v220
	v_add_f32_e32 v221, 1.0, v221
	v_rcp_f32_e32 v218, v218
	v_rcp_f32_e32 v219, v219
	v_mul_f32_e32 v218, v218, v220
	v_mul_f32_e32 v219, v219, v221
	v_pk_mul_f32 v[102:103], v[102:103], v[218:219]
	v_lshlrev_b32_e32 v242, 16, v143
	v_and_b32_e32 v243, 0xffff0000, v143
	v_lshlrev_b32_e32 v246, 16, v199
	v_and_b32_e32 v247, 0xffff0000, v199
	v_max_f32_e32 v242, 0xc2700000, v242
	v_max_f32_e32 v243, 0xc2700000, v243
	v_max_f32_e32 v246, 0xc2700000, v246
	v_max_f32_e32 v247, 0xc2700000, v247
	v_mul_f32_e32 v242, 0xbfb8aa3b, v242
	v_mul_f32_e32 v243, 0xbfb8aa3b, v243
	v_mul_f32_e32 v246, 0xbfb8aa3b, v246
	v_mul_f32_e32 v247, 0xbfb8aa3b, v247
	v_exp_f32_e32 v242, v242
	v_exp_f32_e32 v243, v243
	v_exp_f32_e32 v246, v246
	v_exp_f32_e32 v247, v247
	v_add_f32_e32 v242, 1.0, v242
	v_add_f32_e32 v243, 1.0, v243
	v_add_f32_e32 v246, 1.0, v246
	v_add_f32_e32 v247, 1.0, v247
	v_rcp_f32_e32 v242, v242
	v_rcp_f32_e32 v243, v243
	v_mul_f32_e32 v242, v242, v246
	v_mul_f32_e32 v243, v243, v247
	v_pk_mul_f32 v[104:105], v[104:105], v[242:243]
	v_lshlrev_b32_e32 v218, 16, v144
	v_and_b32_e32 v219, 0xffff0000, v144
	v_lshlrev_b32_e32 v220, 16, v200
	v_and_b32_e32 v221, 0xffff0000, v200
	v_max_f32_e32 v218, 0xc2700000, v218
	v_max_f32_e32 v219, 0xc2700000, v219
	v_max_f32_e32 v220, 0xc2700000, v220
	v_max_f32_e32 v221, 0xc2700000, v221
	v_mul_f32_e32 v218, 0xbfb8aa3b, v218
	v_mul_f32_e32 v219, 0xbfb8aa3b, v219
	v_mul_f32_e32 v220, 0xbfb8aa3b, v220
	v_mul_f32_e32 v221, 0xbfb8aa3b, v221
	v_exp_f32_e32 v218, v218
	v_exp_f32_e32 v219, v219
	v_exp_f32_e32 v220, v220
	v_exp_f32_e32 v221, v221
	v_add_f32_e32 v218, 1.0, v218
	v_add_f32_e32 v219, 1.0, v219
	v_add_f32_e32 v220, 1.0, v220
	v_add_f32_e32 v221, 1.0, v221
	v_rcp_f32_e32 v218, v218
	v_rcp_f32_e32 v219, v219
	v_mul_f32_e32 v218, v218, v220
	v_mul_f32_e32 v219, v219, v221
	v_pk_mul_f32 v[98:99], v[98:99], v[218:219]
	v_lshlrev_b32_e32 v242, 16, v145
	v_and_b32_e32 v243, 0xffff0000, v145
	v_lshlrev_b32_e32 v246, 16, v201
	v_and_b32_e32 v247, 0xffff0000, v201
	v_max_f32_e32 v242, 0xc2700000, v242
	v_max_f32_e32 v243, 0xc2700000, v243
	v_max_f32_e32 v246, 0xc2700000, v246
	v_max_f32_e32 v247, 0xc2700000, v247
	v_mul_f32_e32 v242, 0xbfb8aa3b, v242
	v_mul_f32_e32 v243, 0xbfb8aa3b, v243
	v_mul_f32_e32 v246, 0xbfb8aa3b, v246
	v_mul_f32_e32 v247, 0xbfb8aa3b, v247
	v_exp_f32_e32 v242, v242
	v_exp_f32_e32 v243, v243
	v_exp_f32_e32 v246, v246
	v_exp_f32_e32 v247, v247
	v_add_f32_e32 v242, 1.0, v242
	v_add_f32_e32 v243, 1.0, v243
	v_add_f32_e32 v246, 1.0, v246
	v_add_f32_e32 v247, 1.0, v247
	v_rcp_f32_e32 v242, v242
	v_rcp_f32_e32 v243, v243
	v_mul_f32_e32 v242, v242, v246
	v_mul_f32_e32 v243, v243, v247
	v_pk_mul_f32 v[100:101], v[100:101], v[242:243]
	v_lshl_add_u64 v[226:227], v[226:227], 0, s[8:9]
	v_lshl_add_u64 v[228:229], v[228:229], 0, s[8:9]
	global_load_dwordx4 v[138:141], v[226:227], off
	global_load_dwordx4 v[194:197], v[228:229], off
	global_load_dwordx4 v[142:145], v[226:227], off offset:256
	global_load_dwordx4 v[198:201], v[228:229], off offset:256
	s_waitcnt vmcnt(12)
; __device__ __forceinline__ float bf_lo(unsigned w) { return __uint_as_float(w << 16); }
; __device__ __forceinline__ float bf_hi(unsigned w) { return __uint_as_float(w & 0xffff0000u); }
; __device__ __forceinline__ float sigm(float x) { return __builtin_amdgcn_rcpf(1.f + __builtin_amdgcn_exp2f(-1.4426950408889634f * x)); }
;     __device__ __forceinline__ void operator()(const f32x4 (&acc)[2][2][4][2], const Unit& u, int wr, int wc, int fr, int fq) const {
;     ...
;                 for (int bj = 0; bj < 2; ++bj) { const int row = row0 + ai * HALF + m * 16, col = col0 + bj * HALF; const u32x4 g4 = gv[m][bj];
;                     const f32x4 a0 = acc[ai][bj][m][0], a1 = acc[ai][bj][m][1];
;                     float f0 = a0[0] * bf_lo(g4.x), f1 = a0[1] * bf_hi(g4.x), f2 = a0[2] * bf_lo(g4.y), f3 = a0[3] * bf_hi(g4.y);
;                     float f4 = a1[0] * bf_lo(g4.z), f5 = a1[1] * bf_hi(g4.z), f6 = a1[2] * bf_lo(g4.w), f7 = a1[3] * bf_hi(g4.w);
;                     if (br > 0) {
;                         const unsigned p0 = (unsigned)q0[m][bj], p1 = (unsigned)(q0[m][bj] >> 32), p2 = (unsigned)q1[m][bj], p3 = (unsigned)(q1[m][bj] >> 32);
;                         f0 += bf_lo(p0); f1 += bf_hi(p0); f2 += bf_lo(p1); f3 += bf_hi(p1); f4 += bf_lo(p2); f5 += bf_hi(p2); f6 += bf_lo(p3); f7 += bf_hi(p3);
;                     }
	v_lshlrev_b32_e32 v218, 16, v146
	v_and_b32_e32 v219, 0xffff0000, v146
	v_lshlrev_b32_e32 v220, 16, v202
	v_and_b32_e32 v221, 0xffff0000, v202
	v_max_f32_e32 v218, 0xc2700000, v218
	v_max_f32_e32 v219, 0xc2700000, v219
	v_max_f32_e32 v220, 0xc2700000, v220
	v_max_f32_e32 v221, 0xc2700000, v221
	v_mul_f32_e32 v218, 0xbfb8aa3b, v218
	v_mul_f32_e32 v219, 0xbfb8aa3b, v219
	v_mul_f32_e32 v220, 0xbfb8aa3b, v220
	v_mul_f32_e32 v221, 0xbfb8aa3b, v221
	v_exp_f32_e32 v218, v218
	v_exp_f32_e32 v219, v219
	v_exp_f32_e32 v220, v220
	v_exp_f32_e32 v221, v221
	v_add_f32_e32 v218, 1.0, v218
	v_add_f32_e32 v219, 1.0, v219
	v_add_f32_e32 v220, 1.0, v220
	v_add_f32_e32 v221, 1.0, v221
	v_rcp_f32_e32 v218, v218
	v_rcp_f32_e32 v219, v219
	v_mul_f32_e32 v218, v218, v220
	v_mul_f32_e32 v219, v219, v221
	v_pk_mul_f32 v[94:95], v[94:95], v[218:219]
	v_lshlrev_b32_e32 v242, 16, v147
	v_and_b32_e32 v243, 0xffff0000, v147
	v_lshlrev_b32_e32 v246, 16, v203
	v_and_b32_e32 v247, 0xffff0000, v203
	v_max_f32_e32 v242, 0xc2700000, v242
	v_max_f32_e32 v243, 0xc2700000, v243
	v_max_f32_e32 v246, 0xc2700000, v246
	v_max_f32_e32 v247, 0xc2700000, v247
	v_mul_f32_e32 v242, 0xbfb8aa3b, v242
	v_mul_f32_e32 v243, 0xbfb8aa3b, v243
	v_mul_f32_e32 v246, 0xbfb8aa3b, v246
	v_mul_f32_e32 v247, 0xbfb8aa3b, v247
	v_exp_f32_e32 v242, v242
	v_exp_f32_e32 v243, v243
	v_exp_f32_e32 v246, v246
	v_exp_f32_e32 v247, v247
	v_add_f32_e32 v242, 1.0, v242
	v_add_f32_e32 v243, 1.0, v243
	v_add_f32_e32 v246, 1.0, v246
	v_add_f32_e32 v247, 1.0, v247
	v_rcp_f32_e32 v242, v242
	v_rcp_f32_e32 v243, v243
	v_mul_f32_e32 v242, v242, v246
	v_mul_f32_e32 v243, v243, v247
	v_pk_mul_f32 v[96:97], v[96:97], v[242:243]
	v_lshlrev_b32_e32 v218, 16, v148
	v_and_b32_e32 v219, 0xffff0000, v148
	v_lshlrev_b32_e32 v220, 16, v204
	v_and_b32_e32 v221, 0xffff0000, v204
	v_max_f32_e32 v218, 0xc2700000, v218
	v_max_f32_e32 v219, 0xc2700000, v219
	v_max_f32_e32 v220, 0xc2700000, v220
	v_max_f32_e32 v221, 0xc2700000, v221
	v_mul_f32_e32 v218, 0xbfb8aa3b, v218
	v_mul_f32_e32 v219, 0xbfb8aa3b, v219
	v_mul_f32_e32 v220, 0xbfb8aa3b, v220
	v_mul_f32_e32 v221, 0xbfb8aa3b, v221
	v_exp_f32_e32 v218, v218
	v_exp_f32_e32 v219, v219
	v_exp_f32_e32 v220, v220
	v_exp_f32_e32 v221, v221
	v_add_f32_e32 v218, 1.0, v218
	v_add_f32_e32 v219, 1.0, v219
	v_add_f32_e32 v220, 1.0, v220
	v_add_f32_e32 v221, 1.0, v221
	v_rcp_f32_e32 v218, v218
	v_rcp_f32_e32 v219, v219
	v_mul_f32_e32 v218, v218, v220
	v_mul_f32_e32 v219, v219, v221
	v_pk_mul_f32 v[90:91], v[90:91], v[218:219]
	v_lshlrev_b32_e32 v242, 16, v149
	v_and_b32_e32 v243, 0xffff0000, v149
	v_lshlrev_b32_e32 v246, 16, v205
	v_and_b32_e32 v247, 0xffff0000, v205
	v_max_f32_e32 v242, 0xc2700000, v242
	v_max_f32_e32 v243, 0xc2700000, v243
	v_max_f32_e32 v246, 0xc2700000, v246
	v_max_f32_e32 v247, 0xc2700000, v247
	v_mul_f32_e32 v242, 0xbfb8aa3b, v242
	v_mul_f32_e32 v243, 0xbfb8aa3b, v243
	v_mul_f32_e32 v246, 0xbfb8aa3b, v246
	v_mul_f32_e32 v247, 0xbfb8aa3b, v247
	v_exp_f32_e32 v242, v242
	v_exp_f32_e32 v243, v243
	v_exp_f32_e32 v246, v246
	v_exp_f32_e32 v247, v247
	v_add_f32_e32 v242, 1.0, v242
	v_add_f32_e32 v243, 1.0, v243
	v_add_f32_e32 v246, 1.0, v246
	v_add_f32_e32 v247, 1.0, v247
	v_rcp_f32_e32 v242, v242
	v_rcp_f32_e32 v243, v243
	v_mul_f32_e32 v242, v242, v246
	v_mul_f32_e32 v243, v243, v247
	v_pk_mul_f32 v[92:93], v[92:93], v[242:243]
	v_lshlrev_b32_e32 v218, 16, v150
	v_and_b32_e32 v219, 0xffff0000, v150
	v_lshlrev_b32_e32 v220, 16, v206
	v_and_b32_e32 v221, 0xffff0000, v206
	v_max_f32_e32 v218, 0xc2700000, v218
	v_max_f32_e32 v219, 0xc2700000, v219
	v_max_f32_e32 v220, 0xc2700000, v220
	v_max_f32_e32 v221, 0xc2700000, v221
	v_mul_f32_e32 v218, 0xbfb8aa3b, v218
	v_mul_f32_e32 v219, 0xbfb8aa3b, v219
	v_mul_f32_e32 v220, 0xbfb8aa3b, v220
	v_mul_f32_e32 v221, 0xbfb8aa3b, v221
	v_exp_f32_e32 v218, v218
	v_exp_f32_e32 v219, v219
	v_exp_f32_e32 v220, v220
	v_exp_f32_e32 v221, v221
	v_add_f32_e32 v218, 1.0, v218
	v_add_f32_e32 v219, 1.0, v219
	v_add_f32_e32 v220, 1.0, v220
	v_add_f32_e32 v221, 1.0, v221
	v_rcp_f32_e32 v218, v218
	v_rcp_f32_e32 v219, v219
	v_mul_f32_e32 v218, v218, v220
	v_mul_f32_e32 v219, v219, v221
	v_pk_mul_f32 v[86:87], v[86:87], v[218:219]
	v_lshlrev_b32_e32 v242, 16, v151
	v_and_b32_e32 v243, 0xffff0000, v151
	v_lshlrev_b32_e32 v246, 16, v207
	v_and_b32_e32 v247, 0xffff0000, v207
	v_max_f32_e32 v242, 0xc2700000, v242
	v_max_f32_e32 v243, 0xc2700000, v243
	v_max_f32_e32 v246, 0xc2700000, v246
	v_max_f32_e32 v247, 0xc2700000, v247
	v_mul_f32_e32 v242, 0xbfb8aa3b, v242
	v_mul_f32_e32 v243, 0xbfb8aa3b, v243
	v_mul_f32_e32 v246, 0xbfb8aa3b, v246
	v_mul_f32_e32 v247, 0xbfb8aa3b, v247
	v_exp_f32_e32 v242, v242
	v_exp_f32_e32 v243, v243
	v_exp_f32_e32 v246, v246
	v_exp_f32_e32 v247, v247
	v_add_f32_e32 v242, 1.0, v242
	v_add_f32_e32 v243, 1.0, v243
	v_add_f32_e32 v246, 1.0, v246
	v_add_f32_e32 v247, 1.0, v247
	v_rcp_f32_e32 v242, v242
	v_rcp_f32_e32 v243, v243
	v_mul_f32_e32 v242, v242, v246
	v_mul_f32_e32 v243, v243, v247
	v_pk_mul_f32 v[88:89], v[88:89], v[242:243]
	v_lshlrev_b32_e32 v218, 16, v152
	v_and_b32_e32 v219, 0xffff0000, v152
	v_lshlrev_b32_e32 v220, 16, v208
	v_and_b32_e32 v221, 0xffff0000, v208
	v_max_f32_e32 v218, 0xc2700000, v218
	v_max_f32_e32 v219, 0xc2700000, v219
	v_max_f32_e32 v220, 0xc2700000, v220
	v_max_f32_e32 v221, 0xc2700000, v221
	v_mul_f32_e32 v218, 0xbfb8aa3b, v218
	v_mul_f32_e32 v219, 0xbfb8aa3b, v219
	v_mul_f32_e32 v220, 0xbfb8aa3b, v220
	v_mul_f32_e32 v221, 0xbfb8aa3b, v221
	v_exp_f32_e32 v218, v218
	v_exp_f32_e32 v219, v219
	v_exp_f32_e32 v220, v220
	v_exp_f32_e32 v221, v221
	v_add_f32_e32 v218, 1.0, v218
	v_add_f32_e32 v219, 1.0, v219
	v_add_f32_e32 v220, 1.0, v220
	v_add_f32_e32 v221, 1.0, v221
	v_rcp_f32_e32 v218, v218
	v_rcp_f32_e32 v219, v219
	v_mul_f32_e32 v218, v218, v220
	v_mul_f32_e32 v219, v219, v221
	v_pk_mul_f32 v[82:83], v[82:83], v[218:219]
	v_lshlrev_b32_e32 v242, 16, v153
	v_and_b32_e32 v243, 0xffff0000, v153
	v_lshlrev_b32_e32 v246, 16, v209
	v_and_b32_e32 v247, 0xffff0000, v209
	v_max_f32_e32 v242, 0xc2700000, v242
	v_max_f32_e32 v243, 0xc2700000, v243
	v_max_f32_e32 v246, 0xc2700000, v246
	v_max_f32_e32 v247, 0xc2700000, v247
	v_mul_f32_e32 v242, 0xbfb8aa3b, v242
	v_mul_f32_e32 v243, 0xbfb8aa3b, v243
	v_mul_f32_e32 v246, 0xbfb8aa3b, v246
	v_mul_f32_e32 v247, 0xbfb8aa3b, v247
	v_exp_f32_e32 v242, v242
	v_exp_f32_e32 v243, v243
	v_exp_f32_e32 v246, v246
	v_exp_f32_e32 v247, v247
	v_add_f32_e32 v242, 1.0, v242
	v_add_f32_e32 v243, 1.0, v243
	v_add_f32_e32 v246, 1.0, v246
	v_add_f32_e32 v247, 1.0, v247
	v_rcp_f32_e32 v242, v242
	v_rcp_f32_e32 v243, v243
	v_mul_f32_e32 v242, v242, v246
	v_mul_f32_e32 v243, v243, v247
	v_pk_mul_f32 v[84:85], v[84:85], v[242:243]
	v_lshl_add_u64 v[226:227], v[226:227], 0, s[8:9]
	v_lshl_add_u64 v[228:229], v[228:229], 0, s[8:9]
	global_load_dwordx4 v[146:149], v[226:227], off
	global_load_dwordx4 v[202:205], v[228:229], off
	global_load_dwordx4 v[150:153], v[226:227], off offset:256
	global_load_dwordx4 v[206:209], v[228:229], off offset:256
	s_waitcnt vmcnt(12)
; __device__ __forceinline__ float bf_lo(unsigned w) { return __uint_as_float(w << 16); }
; __device__ __forceinline__ float bf_hi(unsigned w) { return __uint_as_float(w & 0xffff0000u); }
; __device__ __forceinline__ float sigm(float x) { return __builtin_amdgcn_rcpf(1.f + __builtin_amdgcn_exp2f(-1.4426950408889634f * x)); }
;     __device__ __forceinline__ void operator()(const f32x4 (&acc)[2][2][4][2], const Unit& u, int wr, int wc, int fr, int fq) const {
;     ...
;                 for (int bj = 0; bj < 2; ++bj) { const int row = row0 + ai * HALF + m * 16, col = col0 + bj * HALF; const u32x4 g4 = gv[m][bj];
;                     const f32x4 a0 = acc[ai][bj][m][0], a1 = acc[ai][bj][m][1];
;                     float f0 = a0[0] * bf_lo(g4.x), f1 = a0[1] * bf_hi(g4.x), f2 = a0[2] * bf_lo(g4.y), f3 = a0[3] * bf_hi(g4.y);
;                     float f4 = a1[0] * bf_lo(g4.z), f5 = a1[1] * bf_hi(g4.z), f6 = a1[2] * bf_lo(g4.w), f7 = a1[3] * bf_hi(g4.w);
;                     if (br > 0) {
;                         const unsigned p0 = (unsigned)q0[m][bj], p1 = (unsigned)(q0[m][bj] >> 32), p2 = (unsigned)q1[m][bj], p3 = (unsigned)(q1[m][bj] >> 32);
;                         f0 += bf_lo(p0); f1 += bf_hi(p0); f2 += bf_lo(p1); f3 += bf_hi(p1); f4 += bf_lo(p2); f5 += bf_hi(p2); f6 += bf_lo(p3); f7 += bf_hi(p3);
;                     }
	v_lshlrev_b32_e32 v218, 16, v154
	v_and_b32_e32 v219, 0xffff0000, v154
	v_lshlrev_b32_e32 v220, 16, v210
	v_and_b32_e32 v221, 0xffff0000, v210
	v_max_f32_e32 v218, 0xc2700000, v218
	v_max_f32_e32 v219, 0xc2700000, v219
	v_max_f32_e32 v220, 0xc2700000, v220
	v_max_f32_e32 v221, 0xc2700000, v221
	v_mul_f32_e32 v218, 0xbfb8aa3b, v218
	v_mul_f32_e32 v219, 0xbfb8aa3b, v219
	v_mul_f32_e32 v220, 0xbfb8aa3b, v220
	v_mul_f32_e32 v221, 0xbfb8aa3b, v221
	v_exp_f32_e32 v218, v218
	v_exp_f32_e32 v219, v219
	v_exp_f32_e32 v220, v220
	v_exp_f32_e32 v221, v221
	v_add_f32_e32 v218, 1.0, v218
	v_add_f32_e32 v219, 1.0, v219
	v_add_f32_e32 v220, 1.0, v220
	v_add_f32_e32 v221, 1.0, v221
	v_rcp_f32_e32 v218, v218
	v_rcp_f32_e32 v219, v219
	v_mul_f32_e32 v218, v218, v220
	v_mul_f32_e32 v219, v219, v221
	v_pk_mul_f32 v[78:79], v[78:79], v[218:219]
	v_lshlrev_b32_e32 v242, 16, v155
	v_and_b32_e32 v243, 0xffff0000, v155
	v_lshlrev_b32_e32 v246, 16, v211
	v_and_b32_e32 v247, 0xffff0000, v211
	v_max_f32_e32 v242, 0xc2700000, v242
	v_max_f32_e32 v243, 0xc2700000, v243
	v_max_f32_e32 v246, 0xc2700000, v246
	v_max_f32_e32 v247, 0xc2700000, v247
	v_mul_f32_e32 v242, 0xbfb8aa3b, v242
	v_mul_f32_e32 v243, 0xbfb8aa3b, v243
	v_mul_f32_e32 v246, 0xbfb8aa3b, v246
	v_mul_f32_e32 v247, 0xbfb8aa3b, v247
	v_exp_f32_e32 v242, v242
	v_exp_f32_e32 v243, v243
	v_exp_f32_e32 v246, v246
	v_exp_f32_e32 v247, v247
	v_add_f32_e32 v242, 1.0, v242
	v_add_f32_e32 v243, 1.0, v243
	v_add_f32_e32 v246, 1.0, v246
	v_add_f32_e32 v247, 1.0, v247
	v_rcp_f32_e32 v242, v242
	v_rcp_f32_e32 v243, v243
	v_mul_f32_e32 v242, v242, v246
	v_mul_f32_e32 v243, v243, v247
	v_pk_mul_f32 v[80:81], v[80:81], v[242:243]
	v_lshlrev_b32_e32 v218, 16, v156
	v_and_b32_e32 v219, 0xffff0000, v156
	v_lshlrev_b32_e32 v220, 16, v212
	v_and_b32_e32 v221, 0xffff0000, v212
	v_max_f32_e32 v218, 0xc2700000, v218
	v_max_f32_e32 v219, 0xc2700000, v219
	v_max_f32_e32 v220, 0xc2700000, v220
	v_max_f32_e32 v221, 0xc2700000, v221
	v_mul_f32_e32 v218, 0xbfb8aa3b, v218
	v_mul_f32_e32 v219, 0xbfb8aa3b, v219
	v_mul_f32_e32 v220, 0xbfb8aa3b, v220
	v_mul_f32_e32 v221, 0xbfb8aa3b, v221
	v_exp_f32_e32 v218, v218
	v_exp_f32_e32 v219, v219
	v_exp_f32_e32 v220, v220
	v_exp_f32_e32 v221, v221
	v_add_f32_e32 v218, 1.0, v218
	v_add_f32_e32 v219, 1.0, v219
	v_add_f32_e32 v220, 1.0, v220
	v_add_f32_e32 v221, 1.0, v221
	v_rcp_f32_e32 v218, v218
	v_rcp_f32_e32 v219, v219
	v_mul_f32_e32 v218, v218, v220
	v_mul_f32_e32 v219, v219, v221
	v_pk_mul_f32 v[74:75], v[74:75], v[218:219]
	v_lshlrev_b32_e32 v242, 16, v157
	v_and_b32_e32 v243, 0xffff0000, v157
	v_lshlrev_b32_e32 v246, 16, v213
	v_and_b32_e32 v247, 0xffff0000, v213
	v_max_f32_e32 v242, 0xc2700000, v242
	v_max_f32_e32 v243, 0xc2700000, v243
	v_max_f32_e32 v246, 0xc2700000, v246
	v_max_f32_e32 v247, 0xc2700000, v247
	v_mul_f32_e32 v242, 0xbfb8aa3b, v242
	v_mul_f32_e32 v243, 0xbfb8aa3b, v243
	v_mul_f32_e32 v246, 0xbfb8aa3b, v246
	v_mul_f32_e32 v247, 0xbfb8aa3b, v247
	v_exp_f32_e32 v242, v242
	v_exp_f32_e32 v243, v243
	v_exp_f32_e32 v246, v246
	v_exp_f32_e32 v247, v247
	v_add_f32_e32 v242, 1.0, v242
	v_add_f32_e32 v243, 1.0, v243
	v_add_f32_e32 v246, 1.0, v246
	v_add_f32_e32 v247, 1.0, v247
	v_rcp_f32_e32 v242, v242
	v_rcp_f32_e32 v243, v243
	v_mul_f32_e32 v242, v242, v246
	v_mul_f32_e32 v243, v243, v247
	v_pk_mul_f32 v[76:77], v[76:77], v[242:243]
	v_lshlrev_b32_e32 v218, 16, v158
	v_and_b32_e32 v219, 0xffff0000, v158
	v_lshlrev_b32_e32 v220, 16, v214
	v_and_b32_e32 v221, 0xffff0000, v214
	v_max_f32_e32 v218, 0xc2700000, v218
	v_max_f32_e32 v219, 0xc2700000, v219
	v_max_f32_e32 v220, 0xc2700000, v220
	v_max_f32_e32 v221, 0xc2700000, v221
	v_mul_f32_e32 v218, 0xbfb8aa3b, v218
	v_mul_f32_e32 v219, 0xbfb8aa3b, v219
	v_mul_f32_e32 v220, 0xbfb8aa3b, v220
	v_mul_f32_e32 v221, 0xbfb8aa3b, v221
	v_exp_f32_e32 v218, v218
	v_exp_f32_e32 v219, v219
	v_exp_f32_e32 v220, v220
	v_exp_f32_e32 v221, v221
	v_add_f32_e32 v218, 1.0, v218
	v_add_f32_e32 v219, 1.0, v219
	v_add_f32_e32 v220, 1.0, v220
	v_add_f32_e32 v221, 1.0, v221
	v_rcp_f32_e32 v218, v218
	v_rcp_f32_e32 v219, v219
	v_mul_f32_e32 v218, v218, v220
	v_mul_f32_e32 v219, v219, v221
	v_pk_mul_f32 v[70:71], v[70:71], v[218:219]
	v_lshlrev_b32_e32 v242, 16, v159
	v_and_b32_e32 v243, 0xffff0000, v159
	v_lshlrev_b32_e32 v246, 16, v215
	v_and_b32_e32 v247, 0xffff0000, v215
	v_max_f32_e32 v242, 0xc2700000, v242
	v_max_f32_e32 v243, 0xc2700000, v243
	v_max_f32_e32 v246, 0xc2700000, v246
	v_max_f32_e32 v247, 0xc2700000, v247
	v_mul_f32_e32 v242, 0xbfb8aa3b, v242
	v_mul_f32_e32 v243, 0xbfb8aa3b, v243
	v_mul_f32_e32 v246, 0xbfb8aa3b, v246
	v_mul_f32_e32 v247, 0xbfb8aa3b, v247
	v_exp_f32_e32 v242, v242
	v_exp_f32_e32 v243, v243
	v_exp_f32_e32 v246, v246
	v_exp_f32_e32 v247, v247
	v_add_f32_e32 v242, 1.0, v242
	v_add_f32_e32 v243, 1.0, v243
	v_add_f32_e32 v246, 1.0, v246
	v_add_f32_e32 v247, 1.0, v247
	v_rcp_f32_e32 v242, v242
	v_rcp_f32_e32 v243, v243
	v_mul_f32_e32 v242, v242, v246
	v_mul_f32_e32 v243, v243, v247
	v_pk_mul_f32 v[72:73], v[72:73], v[242:243]
	v_lshlrev_b32_e32 v218, 16, v160
	v_and_b32_e32 v219, 0xffff0000, v160
	v_lshlrev_b32_e32 v220, 16, v216
	v_and_b32_e32 v221, 0xffff0000, v216
	v_max_f32_e32 v218, 0xc2700000, v218
	v_max_f32_e32 v219, 0xc2700000, v219
	v_max_f32_e32 v220, 0xc2700000, v220
	v_max_f32_e32 v221, 0xc2700000, v221
	v_mul_f32_e32 v218, 0xbfb8aa3b, v218
	v_mul_f32_e32 v219, 0xbfb8aa3b, v219
	v_mul_f32_e32 v220, 0xbfb8aa3b, v220
	v_mul_f32_e32 v221, 0xbfb8aa3b, v221
	v_exp_f32_e32 v218, v218
	v_exp_f32_e32 v219, v219
	v_exp_f32_e32 v220, v220
	v_exp_f32_e32 v221, v221
	v_add_f32_e32 v218, 1.0, v218
	v_add_f32_e32 v219, 1.0, v219
	v_add_f32_e32 v220, 1.0, v220
	v_add_f32_e32 v221, 1.0, v221
	v_rcp_f32_e32 v218, v218
	v_rcp_f32_e32 v219, v219
	v_mul_f32_e32 v218, v218, v220
	v_mul_f32_e32 v219, v219, v221
	v_pk_mul_f32 v[66:67], v[66:67], v[218:219]
	v_lshlrev_b32_e32 v242, 16, v161
	v_and_b32_e32 v243, 0xffff0000, v161
	v_lshlrev_b32_e32 v246, 16, v217
	v_and_b32_e32 v247, 0xffff0000, v217
	v_max_f32_e32 v242, 0xc2700000, v242
	v_max_f32_e32 v243, 0xc2700000, v243
	v_max_f32_e32 v246, 0xc2700000, v246
	v_max_f32_e32 v247, 0xc2700000, v247
	v_mul_f32_e32 v242, 0xbfb8aa3b, v242
	v_mul_f32_e32 v243, 0xbfb8aa3b, v243
	v_mul_f32_e32 v246, 0xbfb8aa3b, v246
	v_mul_f32_e32 v247, 0xbfb8aa3b, v247
	v_exp_f32_e32 v242, v242
	v_exp_f32_e32 v243, v243
	v_exp_f32_e32 v246, v246
	v_exp_f32_e32 v247, v247
	v_add_f32_e32 v242, 1.0, v242
	v_add_f32_e32 v243, 1.0, v243
	v_add_f32_e32 v246, 1.0, v246
	v_add_f32_e32 v247, 1.0, v247
	v_rcp_f32_e32 v242, v242
	v_rcp_f32_e32 v243, v243
	v_mul_f32_e32 v242, v242, v246
	v_mul_f32_e32 v243, v243, v247
	v_pk_mul_f32 v[68:69], v[68:69], v[242:243]
	v_lshl_add_u64 v[226:227], v[226:227], 0, s[8:9]
	v_lshl_add_u64 v[228:229], v[228:229], 0, s[8:9]
	global_load_dwordx4 v[154:157], v[226:227], off
	global_load_dwordx4 v[210:213], v[228:229], off
	global_load_dwordx4 v[158:161], v[226:227], off offset:256
	global_load_dwordx4 v[214:217], v[228:229], off offset:256
	s_waitcnt vmcnt(12)
; __device__ __forceinline__ float bf_lo(unsigned w) { return __uint_as_float(w << 16); }
; __device__ __forceinline__ float bf_hi(unsigned w) { return __uint_as_float(w & 0xffff0000u); }
; __device__ __forceinline__ float sigm(float x) { return __builtin_amdgcn_rcpf(1.f + __builtin_amdgcn_exp2f(-1.4426950408889634f * x)); }
;     __device__ __forceinline__ void operator()(const f32x4 (&acc)[2][2][4][2], const Unit& u, int wr, int wc, int fr, int fq) const {
;     ...
;                 for (int bj = 0; bj < 2; ++bj) { const int row = row0 + ai * HALF + m * 16, col = col0 + bj * HALF; const u32x4 g4 = gv[m][bj];
;                     const f32x4 a0 = acc[ai][bj][m][0], a1 = acc[ai][bj][m][1];
;                     float f0 = a0[0] * bf_lo(g4.x), f1 = a0[1] * bf_hi(g4.x), f2 = a0[2] * bf_lo(g4.y), f3 = a0[3] * bf_hi(g4.y);
;                     float f4 = a1[0] * bf_lo(g4.z), f5 = a1[1] * bf_hi(g4.z), f6 = a1[2] * bf_lo(g4.w), f7 = a1[3] * bf_hi(g4.w);
;                     if (br > 0) {
;                         const unsigned p0 = (unsigned)q0[m][bj], p1 = (unsigned)(q0[m][bj] >> 32), p2 = (unsigned)q1[m][bj], p3 = (unsigned)(q1[m][bj] >> 32);
;                         f0 += bf_lo(p0); f1 += bf_hi(p0); f2 += bf_lo(p1); f3 += bf_hi(p1); f4 += bf_lo(p2); f5 += bf_hi(p2); f6 += bf_lo(p3); f7 += bf_hi(p3);
;                     }
	v_lshlrev_b32_e32 v218, 16, v130
	v_and_b32_e32 v219, 0xffff0000, v130
	v_lshlrev_b32_e32 v220, 16, v186
	v_and_b32_e32 v221, 0xffff0000, v186
	v_max_f32_e32 v218, 0xc2700000, v218
	v_max_f32_e32 v219, 0xc2700000, v219
	v_max_f32_e32 v220, 0xc2700000, v220
	v_max_f32_e32 v221, 0xc2700000, v221
	v_mul_f32_e32 v218, 0xbfb8aa3b, v218
	v_mul_f32_e32 v219, 0xbfb8aa3b, v219
	v_mul_f32_e32 v220, 0xbfb8aa3b, v220
	v_mul_f32_e32 v221, 0xbfb8aa3b, v221
	v_exp_f32_e32 v218, v218
	v_exp_f32_e32 v219, v219
	v_exp_f32_e32 v220, v220
	v_exp_f32_e32 v221, v221
	v_add_f32_e32 v218, 1.0, v218
	v_add_f32_e32 v219, 1.0, v219
	v_add_f32_e32 v220, 1.0, v220
	v_add_f32_e32 v221, 1.0, v221
	v_rcp_f32_e32 v218, v218
	v_rcp_f32_e32 v219, v219
	v_mul_f32_e32 v218, v218, v220
	v_mul_f32_e32 v219, v219, v221
	v_pk_mul_f32 v[62:63], v[62:63], v[218:219]
	v_lshlrev_b32_e32 v242, 16, v131
	v_and_b32_e32 v243, 0xffff0000, v131
	v_lshlrev_b32_e32 v246, 16, v187
	v_and_b32_e32 v247, 0xffff0000, v187
	v_max_f32_e32 v242, 0xc2700000, v242
	v_max_f32_e32 v243, 0xc2700000, v243
	v_max_f32_e32 v246, 0xc2700000, v246
	v_max_f32_e32 v247, 0xc2700000, v247
	v_mul_f32_e32 v242, 0xbfb8aa3b, v242
	v_mul_f32_e32 v243, 0xbfb8aa3b, v243
	v_mul_f32_e32 v246, 0xbfb8aa3b, v246
	v_mul_f32_e32 v247, 0xbfb8aa3b, v247
	v_exp_f32_e32 v242, v242
	v_exp_f32_e32 v243, v243
	v_exp_f32_e32 v246, v246
	v_exp_f32_e32 v247, v247
	v_add_f32_e32 v242, 1.0, v242
	v_add_f32_e32 v243, 1.0, v243
	v_add_f32_e32 v246, 1.0, v246
	v_add_f32_e32 v247, 1.0, v247
	v_rcp_f32_e32 v242, v242
	v_rcp_f32_e32 v243, v243
	v_mul_f32_e32 v242, v242, v246
	v_mul_f32_e32 v243, v243, v247
	v_pk_mul_f32 v[64:65], v[64:65], v[242:243]
	v_lshlrev_b32_e32 v218, 16, v132
	v_and_b32_e32 v219, 0xffff0000, v132
	v_lshlrev_b32_e32 v220, 16, v188
	v_and_b32_e32 v221, 0xffff0000, v188
	v_max_f32_e32 v218, 0xc2700000, v218
	v_max_f32_e32 v219, 0xc2700000, v219
	v_max_f32_e32 v220, 0xc2700000, v220
	v_max_f32_e32 v221, 0xc2700000, v221
	v_mul_f32_e32 v218, 0xbfb8aa3b, v218
	v_mul_f32_e32 v219, 0xbfb8aa3b, v219
	v_mul_f32_e32 v220, 0xbfb8aa3b, v220
	v_mul_f32_e32 v221, 0xbfb8aa3b, v221
	v_exp_f32_e32 v218, v218
	v_exp_f32_e32 v219, v219
	v_exp_f32_e32 v220, v220
	v_exp_f32_e32 v221, v221
	v_add_f32_e32 v218, 1.0, v218
	v_add_f32_e32 v219, 1.0, v219
	v_add_f32_e32 v220, 1.0, v220
	v_add_f32_e32 v221, 1.0, v221
	v_rcp_f32_e32 v218, v218
	v_rcp_f32_e32 v219, v219
	v_mul_f32_e32 v218, v218, v220
	v_mul_f32_e32 v219, v219, v221
	v_pk_mul_f32 v[58:59], v[58:59], v[218:219]
	v_lshlrev_b32_e32 v242, 16, v133
	v_and_b32_e32 v243, 0xffff0000, v133
	v_lshlrev_b32_e32 v246, 16, v189
	v_and_b32_e32 v247, 0xffff0000, v189
	v_max_f32_e32 v242, 0xc2700000, v242
	v_max_f32_e32 v243, 0xc2700000, v243
	v_max_f32_e32 v246, 0xc2700000, v246
	v_max_f32_e32 v247, 0xc2700000, v247
	v_mul_f32_e32 v242, 0xbfb8aa3b, v242
	v_mul_f32_e32 v243, 0xbfb8aa3b, v243
	v_mul_f32_e32 v246, 0xbfb8aa3b, v246
	v_mul_f32_e32 v247, 0xbfb8aa3b, v247
	v_exp_f32_e32 v242, v242
	v_exp_f32_e32 v243, v243
	v_exp_f32_e32 v246, v246
	v_exp_f32_e32 v247, v247
	v_add_f32_e32 v242, 1.0, v242
	v_add_f32_e32 v243, 1.0, v243
	v_add_f32_e32 v246, 1.0, v246
	v_add_f32_e32 v247, 1.0, v247
	v_rcp_f32_e32 v242, v242
	v_rcp_f32_e32 v243, v243
	v_mul_f32_e32 v242, v242, v246
	v_mul_f32_e32 v243, v243, v247
	v_pk_mul_f32 v[60:61], v[60:61], v[242:243]
	v_lshlrev_b32_e32 v218, 16, v134
	v_and_b32_e32 v219, 0xffff0000, v134
	v_lshlrev_b32_e32 v220, 16, v190
	v_and_b32_e32 v221, 0xffff0000, v190
	v_max_f32_e32 v218, 0xc2700000, v218
	v_max_f32_e32 v219, 0xc2700000, v219
	v_max_f32_e32 v220, 0xc2700000, v220
	v_max_f32_e32 v221, 0xc2700000, v221
	v_mul_f32_e32 v218, 0xbfb8aa3b, v218
	v_mul_f32_e32 v219, 0xbfb8aa3b, v219
	v_mul_f32_e32 v220, 0xbfb8aa3b, v220
	v_mul_f32_e32 v221, 0xbfb8aa3b, v221
	v_exp_f32_e32 v218, v218
	v_exp_f32_e32 v219, v219
	v_exp_f32_e32 v220, v220
	v_exp_f32_e32 v221, v221
	v_add_f32_e32 v218, 1.0, v218
	v_add_f32_e32 v219, 1.0, v219
	v_add_f32_e32 v220, 1.0, v220
	v_add_f32_e32 v221, 1.0, v221
	v_rcp_f32_e32 v218, v218
	v_rcp_f32_e32 v219, v219
	v_mul_f32_e32 v218, v218, v220
	v_mul_f32_e32 v219, v219, v221
	v_pk_mul_f32 v[54:55], v[54:55], v[218:219]
	v_lshlrev_b32_e32 v242, 16, v135
	v_and_b32_e32 v243, 0xffff0000, v135
	v_lshlrev_b32_e32 v246, 16, v191
	v_and_b32_e32 v247, 0xffff0000, v191
	v_max_f32_e32 v242, 0xc2700000, v242
	v_max_f32_e32 v243, 0xc2700000, v243
	v_max_f32_e32 v246, 0xc2700000, v246
	v_max_f32_e32 v247, 0xc2700000, v247
	v_mul_f32_e32 v242, 0xbfb8aa3b, v242
	v_mul_f32_e32 v243, 0xbfb8aa3b, v243
	v_mul_f32_e32 v246, 0xbfb8aa3b, v246
	v_mul_f32_e32 v247, 0xbfb8aa3b, v247
	v_exp_f32_e32 v242, v242
	v_exp_f32_e32 v243, v243
	v_exp_f32_e32 v246, v246
	v_exp_f32_e32 v247, v247
	v_add_f32_e32 v242, 1.0, v242
	v_add_f32_e32 v243, 1.0, v243
	v_add_f32_e32 v246, 1.0, v246
	v_add_f32_e32 v247, 1.0, v247
	v_rcp_f32_e32 v242, v242
	v_rcp_f32_e32 v243, v243
	v_mul_f32_e32 v242, v242, v246
	v_mul_f32_e32 v243, v243, v247
	v_pk_mul_f32 v[56:57], v[56:57], v[242:243]
	v_lshlrev_b32_e32 v218, 16, v136
	v_and_b32_e32 v219, 0xffff0000, v136
	v_lshlrev_b32_e32 v220, 16, v192
	v_and_b32_e32 v221, 0xffff0000, v192
	v_max_f32_e32 v218, 0xc2700000, v218
	v_max_f32_e32 v219, 0xc2700000, v219
	v_max_f32_e32 v220, 0xc2700000, v220
	v_max_f32_e32 v221, 0xc2700000, v221
	v_mul_f32_e32 v218, 0xbfb8aa3b, v218
	v_mul_f32_e32 v219, 0xbfb8aa3b, v219
	v_mul_f32_e32 v220, 0xbfb8aa3b, v220
	v_mul_f32_e32 v221, 0xbfb8aa3b, v221
	v_exp_f32_e32 v218, v218
	v_exp_f32_e32 v219, v219
	v_exp_f32_e32 v220, v220
	v_exp_f32_e32 v221, v221
	v_add_f32_e32 v218, 1.0, v218
	v_add_f32_e32 v219, 1.0, v219
	v_add_f32_e32 v220, 1.0, v220
	v_add_f32_e32 v221, 1.0, v221
	v_rcp_f32_e32 v218, v218
	v_rcp_f32_e32 v219, v219
	v_mul_f32_e32 v218, v218, v220
	v_mul_f32_e32 v219, v219, v221
	v_pk_mul_f32 v[50:51], v[50:51], v[218:219]
	v_lshlrev_b32_e32 v242, 16, v137
	v_and_b32_e32 v243, 0xffff0000, v137
	v_lshlrev_b32_e32 v246, 16, v193
	v_and_b32_e32 v247, 0xffff0000, v193
	v_max_f32_e32 v242, 0xc2700000, v242
	v_max_f32_e32 v243, 0xc2700000, v243
	v_max_f32_e32 v246, 0xc2700000, v246
	v_max_f32_e32 v247, 0xc2700000, v247
	v_mul_f32_e32 v242, 0xbfb8aa3b, v242
	v_mul_f32_e32 v243, 0xbfb8aa3b, v243
	v_mul_f32_e32 v246, 0xbfb8aa3b, v246
	v_mul_f32_e32 v247, 0xbfb8aa3b, v247
	v_exp_f32_e32 v242, v242
	v_exp_f32_e32 v243, v243
	v_exp_f32_e32 v246, v246
	v_exp_f32_e32 v247, v247
	v_add_f32_e32 v242, 1.0, v242
	v_add_f32_e32 v243, 1.0, v243
	v_add_f32_e32 v246, 1.0, v246
	v_add_f32_e32 v247, 1.0, v247
	v_rcp_f32_e32 v242, v242
	v_rcp_f32_e32 v243, v243
	v_mul_f32_e32 v242, v242, v246
	v_mul_f32_e32 v243, v243, v247
	v_pk_mul_f32 v[52:53], v[52:53], v[242:243]
	s_waitcnt vmcnt(8)
; __device__ __forceinline__ float bf_lo(unsigned w) { return __uint_as_float(w << 16); }
; __device__ __forceinline__ float bf_hi(unsigned w) { return __uint_as_float(w & 0xffff0000u); }
; __device__ __forceinline__ float sigm(float x) { return __builtin_amdgcn_rcpf(1.f + __builtin_amdgcn_exp2f(-1.4426950408889634f * x)); }
;     __device__ __forceinline__ void operator()(const f32x4 (&acc)[2][2][4][2], const Unit& u, int wr, int wc, int fr, int fq) const {
;     ...
;                 for (int bj = 0; bj < 2; ++bj) { const int row = row0 + ai * HALF + m * 16, col = col0 + bj * HALF; const u32x4 g4 = gv[m][bj];
;                     const f32x4 a0 = acc[ai][bj][m][0], a1 = acc[ai][bj][m][1];
;                     float f0 = a0[0] * bf_lo(g4.x), f1 = a0[1] * bf_hi(g4.x), f2 = a0[2] * bf_lo(g4.y), f3 = a0[3] * bf_hi(g4.y);
;                     float f4 = a1[0] * bf_lo(g4.z), f5 = a1[1] * bf_hi(g4.z), f6 = a1[2] * bf_lo(g4.w), f7 = a1[3] * bf_hi(g4.w);
;                     if (br > 0) {
;                         const unsigned p0 = (unsigned)q0[m][bj], p1 = (unsigned)(q0[m][bj] >> 32), p2 = (unsigned)q1[m][bj], p3 = (unsigned)(q1[m][bj] >> 32);
;                         f0 += bf_lo(p0); f1 += bf_hi(p0); f2 += bf_lo(p1); f3 += bf_hi(p1); f4 += bf_lo(p2); f5 += bf_hi(p2); f6 += bf_lo(p3); f7 += bf_hi(p3);
;                     }
	v_lshlrev_b32_e32 v218, 16, v138
	v_and_b32_e32 v219, 0xffff0000, v138
	v_lshlrev_b32_e32 v220, 16, v194
	v_and_b32_e32 v221, 0xffff0000, v194
	v_max_f32_e32 v218, 0xc2700000, v218
	v_max_f32_e32 v219, 0xc2700000, v219
	v_max_f32_e32 v220, 0xc2700000, v220
	v_max_f32_e32 v221, 0xc2700000, v221
	v_mul_f32_e32 v218, 0xbfb8aa3b, v218
	v_mul_f32_e32 v219, 0xbfb8aa3b, v219
	v_mul_f32_e32 v220, 0xbfb8aa3b, v220
	v_mul_f32_e32 v221, 0xbfb8aa3b, v221
	v_exp_f32_e32 v218, v218
	v_exp_f32_e32 v219, v219
	v_exp_f32_e32 v220, v220
	v_exp_f32_e32 v221, v221
	v_add_f32_e32 v218, 1.0, v218
	v_add_f32_e32 v219, 1.0, v219
	v_add_f32_e32 v220, 1.0, v220
	v_add_f32_e32 v221, 1.0, v221
	v_rcp_f32_e32 v218, v218
	v_rcp_f32_e32 v219, v219
	v_mul_f32_e32 v218, v218, v220
	v_mul_f32_e32 v219, v219, v221
	v_pk_mul_f32 v[46:47], v[46:47], v[218:219]
	v_lshlrev_b32_e32 v242, 16, v139
	v_and_b32_e32 v243, 0xffff0000, v139
	v_lshlrev_b32_e32 v246, 16, v195
	v_and_b32_e32 v247, 0xffff0000, v195
	v_max_f32_e32 v242, 0xc2700000, v242
	v_max_f32_e32 v243, 0xc2700000, v243
	v_max_f32_e32 v246, 0xc2700000, v246
	v_max_f32_e32 v247, 0xc2700000, v247
	v_mul_f32_e32 v242, 0xbfb8aa3b, v242
	v_mul_f32_e32 v243, 0xbfb8aa3b, v243
	v_mul_f32_e32 v246, 0xbfb8aa3b, v246
	v_mul_f32_e32 v247, 0xbfb8aa3b, v247
	v_exp_f32_e32 v242, v242
	v_exp_f32_e32 v243, v243
	v_exp_f32_e32 v246, v246
	v_exp_f32_e32 v247, v247
	v_add_f32_e32 v242, 1.0, v242
	v_add_f32_e32 v243, 1.0, v243
	v_add_f32_e32 v246, 1.0, v246
	v_add_f32_e32 v247, 1.0, v247
	v_rcp_f32_e32 v242, v242
	v_rcp_f32_e32 v243, v243
	v_mul_f32_e32 v242, v242, v246
	v_mul_f32_e32 v243, v243, v247
	v_pk_mul_f32 v[48:49], v[48:49], v[242:243]
	v_lshlrev_b32_e32 v218, 16, v140
	v_and_b32_e32 v219, 0xffff0000, v140
	v_lshlrev_b32_e32 v220, 16, v196
	v_and_b32_e32 v221, 0xffff0000, v196
	v_max_f32_e32 v218, 0xc2700000, v218
	v_max_f32_e32 v219, 0xc2700000, v219
	v_max_f32_e32 v220, 0xc2700000, v220
	v_max_f32_e32 v221, 0xc2700000, v221
	v_mul_f32_e32 v218, 0xbfb8aa3b, v218
	v_mul_f32_e32 v219, 0xbfb8aa3b, v219
	v_mul_f32_e32 v220, 0xbfb8aa3b, v220
	v_mul_f32_e32 v221, 0xbfb8aa3b, v221
	v_exp_f32_e32 v218, v218
	v_exp_f32_e32 v219, v219
	v_exp_f32_e32 v220, v220
	v_exp_f32_e32 v221, v221
	v_add_f32_e32 v218, 1.0, v218
	v_add_f32_e32 v219, 1.0, v219
	v_add_f32_e32 v220, 1.0, v220
	v_add_f32_e32 v221, 1.0, v221
	v_rcp_f32_e32 v218, v218
	v_rcp_f32_e32 v219, v219
	v_mul_f32_e32 v218, v218, v220
	v_mul_f32_e32 v219, v219, v221
	v_pk_mul_f32 v[42:43], v[42:43], v[218:219]
	v_lshlrev_b32_e32 v242, 16, v141
	v_and_b32_e32 v243, 0xffff0000, v141
	v_lshlrev_b32_e32 v246, 16, v197
	v_and_b32_e32 v247, 0xffff0000, v197
	v_max_f32_e32 v242, 0xc2700000, v242
	v_max_f32_e32 v243, 0xc2700000, v243
	v_max_f32_e32 v246, 0xc2700000, v246
	v_max_f32_e32 v247, 0xc2700000, v247
	v_mul_f32_e32 v242, 0xbfb8aa3b, v242
	v_mul_f32_e32 v243, 0xbfb8aa3b, v243
	v_mul_f32_e32 v246, 0xbfb8aa3b, v246
	v_mul_f32_e32 v247, 0xbfb8aa3b, v247
	v_exp_f32_e32 v242, v242
	v_exp_f32_e32 v243, v243
	v_exp_f32_e32 v246, v246
	v_exp_f32_e32 v247, v247
	v_add_f32_e32 v242, 1.0, v242
	v_add_f32_e32 v243, 1.0, v243
	v_add_f32_e32 v246, 1.0, v246
	v_add_f32_e32 v247, 1.0, v247
	v_rcp_f32_e32 v242, v242
	v_rcp_f32_e32 v243, v243
	v_mul_f32_e32 v242, v242, v246
	v_mul_f32_e32 v243, v243, v247
	v_pk_mul_f32 v[44:45], v[44:45], v[242:243]
	v_lshlrev_b32_e32 v218, 16, v142
	v_and_b32_e32 v219, 0xffff0000, v142
	v_lshlrev_b32_e32 v220, 16, v198
	v_and_b32_e32 v221, 0xffff0000, v198
	v_max_f32_e32 v218, 0xc2700000, v218
	v_max_f32_e32 v219, 0xc2700000, v219
	v_max_f32_e32 v220, 0xc2700000, v220
	v_max_f32_e32 v221, 0xc2700000, v221
	v_mul_f32_e32 v218, 0xbfb8aa3b, v218
	v_mul_f32_e32 v219, 0xbfb8aa3b, v219
	v_mul_f32_e32 v220, 0xbfb8aa3b, v220
	v_mul_f32_e32 v221, 0xbfb8aa3b, v221
	v_exp_f32_e32 v218, v218
	v_exp_f32_e32 v219, v219
	v_exp_f32_e32 v220, v220
	v_exp_f32_e32 v221, v221
	v_add_f32_e32 v218, 1.0, v218
	v_add_f32_e32 v219, 1.0, v219
	v_add_f32_e32 v220, 1.0, v220
	v_add_f32_e32 v221, 1.0, v221
	v_rcp_f32_e32 v218, v218
	v_rcp_f32_e32 v219, v219
	v_mul_f32_e32 v218, v218, v220
	v_mul_f32_e32 v219, v219, v221
	v_pk_mul_f32 v[38:39], v[38:39], v[218:219]
	v_lshlrev_b32_e32 v242, 16, v143
	v_and_b32_e32 v243, 0xffff0000, v143
	v_lshlrev_b32_e32 v246, 16, v199
	v_and_b32_e32 v247, 0xffff0000, v199
	v_max_f32_e32 v242, 0xc2700000, v242
	v_max_f32_e32 v243, 0xc2700000, v243
	v_max_f32_e32 v246, 0xc2700000, v246
	v_max_f32_e32 v247, 0xc2700000, v247
	v_mul_f32_e32 v242, 0xbfb8aa3b, v242
	v_mul_f32_e32 v243, 0xbfb8aa3b, v243
	v_mul_f32_e32 v246, 0xbfb8aa3b, v246
	v_mul_f32_e32 v247, 0xbfb8aa3b, v247
	v_exp_f32_e32 v242, v242
	v_exp_f32_e32 v243, v243
	v_exp_f32_e32 v246, v246
	v_exp_f32_e32 v247, v247
	v_add_f32_e32 v242, 1.0, v242
	v_add_f32_e32 v243, 1.0, v243
	v_add_f32_e32 v246, 1.0, v246
	v_add_f32_e32 v247, 1.0, v247
	v_rcp_f32_e32 v242, v242
	v_rcp_f32_e32 v243, v243
	v_mul_f32_e32 v242, v242, v246
	v_mul_f32_e32 v243, v243, v247
	v_pk_mul_f32 v[40:41], v[40:41], v[242:243]
	v_lshlrev_b32_e32 v218, 16, v144
	v_and_b32_e32 v219, 0xffff0000, v144
	v_lshlrev_b32_e32 v220, 16, v200
	v_and_b32_e32 v221, 0xffff0000, v200
	v_max_f32_e32 v218, 0xc2700000, v218
	v_max_f32_e32 v219, 0xc2700000, v219
	v_max_f32_e32 v220, 0xc2700000, v220
	v_max_f32_e32 v221, 0xc2700000, v221
	v_mul_f32_e32 v218, 0xbfb8aa3b, v218
	v_mul_f32_e32 v219, 0xbfb8aa3b, v219
	v_mul_f32_e32 v220, 0xbfb8aa3b, v220
	v_mul_f32_e32 v221, 0xbfb8aa3b, v221
	v_exp_f32_e32 v218, v218
	v_exp_f32_e32 v219, v219
	v_exp_f32_e32 v220, v220
	v_exp_f32_e32 v221, v221
	v_add_f32_e32 v218, 1.0, v218
	v_add_f32_e32 v219, 1.0, v219
	v_add_f32_e32 v220, 1.0, v220
	v_add_f32_e32 v221, 1.0, v221
	v_rcp_f32_e32 v218, v218
	v_rcp_f32_e32 v219, v219
	v_mul_f32_e32 v218, v218, v220
	v_mul_f32_e32 v219, v219, v221
	v_pk_mul_f32 v[34:35], v[34:35], v[218:219]
	v_lshlrev_b32_e32 v242, 16, v145
	v_and_b32_e32 v243, 0xffff0000, v145
	v_lshlrev_b32_e32 v246, 16, v201
	v_and_b32_e32 v247, 0xffff0000, v201
	v_max_f32_e32 v242, 0xc2700000, v242
	v_max_f32_e32 v243, 0xc2700000, v243
	v_max_f32_e32 v246, 0xc2700000, v246
	v_max_f32_e32 v247, 0xc2700000, v247
	v_mul_f32_e32 v242, 0xbfb8aa3b, v242
	v_mul_f32_e32 v243, 0xbfb8aa3b, v243
	v_mul_f32_e32 v246, 0xbfb8aa3b, v246
	v_mul_f32_e32 v247, 0xbfb8aa3b, v247
	v_exp_f32_e32 v242, v242
	v_exp_f32_e32 v243, v243
	v_exp_f32_e32 v246, v246
	v_exp_f32_e32 v247, v247
	v_add_f32_e32 v242, 1.0, v242
	v_add_f32_e32 v243, 1.0, v243
	v_add_f32_e32 v246, 1.0, v246
	v_add_f32_e32 v247, 1.0, v247
	v_rcp_f32_e32 v242, v242
	v_rcp_f32_e32 v243, v243
	v_mul_f32_e32 v242, v242, v246
	v_mul_f32_e32 v243, v243, v247
	v_pk_mul_f32 v[36:37], v[36:37], v[242:243]
	s_waitcnt vmcnt(4)
; __device__ __forceinline__ float bf_lo(unsigned w) { return __uint_as_float(w << 16); }
; __device__ __forceinline__ float bf_hi(unsigned w) { return __uint_as_float(w & 0xffff0000u); }
; __device__ __forceinline__ float sigm(float x) { return __builtin_amdgcn_rcpf(1.f + __builtin_amdgcn_exp2f(-1.4426950408889634f * x)); }
;     __device__ __forceinline__ void operator()(const f32x4 (&acc)[2][2][4][2], const Unit& u, int wr, int wc, int fr, int fq) const {
;     ...
;                 for (int bj = 0; bj < 2; ++bj) { const int row = row0 + ai * HALF + m * 16, col = col0 + bj * HALF; const u32x4 g4 = gv[m][bj];
;                     const f32x4 a0 = acc[ai][bj][m][0], a1 = acc[ai][bj][m][1];
;                     float f0 = a0[0] * bf_lo(g4.x), f1 = a0[1] * bf_hi(g4.x), f2 = a0[2] * bf_lo(g4.y), f3 = a0[3] * bf_hi(g4.y);
;                     float f4 = a1[0] * bf_lo(g4.z), f5 = a1[1] * bf_hi(g4.z), f6 = a1[2] * bf_lo(g4.w), f7 = a1[3] * bf_hi(g4.w);
;                     if (br > 0) {
;                         const unsigned p0 = (unsigned)q0[m][bj], p1 = (unsigned)(q0[m][bj] >> 32), p2 = (unsigned)q1[m][bj], p3 = (unsigned)(q1[m][bj] >> 32);
;                         f0 += bf_lo(p0); f1 += bf_hi(p0); f2 += bf_lo(p1); f3 += bf_hi(p1); f4 += bf_lo(p2); f5 += bf_hi(p2); f6 += bf_lo(p3); f7 += bf_hi(p3);
;                     }
	v_lshlrev_b32_e32 v218, 16, v146
	v_and_b32_e32 v219, 0xffff0000, v146
	v_lshlrev_b32_e32 v220, 16, v202
	v_and_b32_e32 v221, 0xffff0000, v202
	v_max_f32_e32 v218, 0xc2700000, v218
	v_max_f32_e32 v219, 0xc2700000, v219
	v_max_f32_e32 v220, 0xc2700000, v220
	v_max_f32_e32 v221, 0xc2700000, v221
	v_mul_f32_e32 v218, 0xbfb8aa3b, v218
	v_mul_f32_e32 v219, 0xbfb8aa3b, v219
	v_mul_f32_e32 v220, 0xbfb8aa3b, v220
	v_mul_f32_e32 v221, 0xbfb8aa3b, v221
	v_exp_f32_e32 v218, v218
	v_exp_f32_e32 v219, v219
	v_exp_f32_e32 v220, v220
	v_exp_f32_e32 v221, v221
	v_add_f32_e32 v218, 1.0, v218
	v_add_f32_e32 v219, 1.0, v219
	v_add_f32_e32 v220, 1.0, v220
	v_add_f32_e32 v221, 1.0, v221
	v_rcp_f32_e32 v218, v218
	v_rcp_f32_e32 v219, v219
	v_mul_f32_e32 v218, v218, v220
	v_mul_f32_e32 v219, v219, v221
	v_pk_mul_f32 v[30:31], v[30:31], v[218:219]
	v_lshlrev_b32_e32 v242, 16, v147
	v_and_b32_e32 v243, 0xffff0000, v147
	v_lshlrev_b32_e32 v246, 16, v203
	v_and_b32_e32 v247, 0xffff0000, v203
	v_max_f32_e32 v242, 0xc2700000, v242
	v_max_f32_e32 v243, 0xc2700000, v243
	v_max_f32_e32 v246, 0xc2700000, v246
	v_max_f32_e32 v247, 0xc2700000, v247
	v_mul_f32_e32 v242, 0xbfb8aa3b, v242
	v_mul_f32_e32 v243, 0xbfb8aa3b, v243
	v_mul_f32_e32 v246, 0xbfb8aa3b, v246
	v_mul_f32_e32 v247, 0xbfb8aa3b, v247
	v_exp_f32_e32 v242, v242
	v_exp_f32_e32 v243, v243
	v_exp_f32_e32 v246, v246
	v_exp_f32_e32 v247, v247
	v_add_f32_e32 v242, 1.0, v242
	v_add_f32_e32 v243, 1.0, v243
	v_add_f32_e32 v246, 1.0, v246
	v_add_f32_e32 v247, 1.0, v247
	v_rcp_f32_e32 v242, v242
	v_rcp_f32_e32 v243, v243
	v_mul_f32_e32 v242, v242, v246
	v_mul_f32_e32 v243, v243, v247
	v_pk_mul_f32 v[32:33], v[32:33], v[242:243]
	v_lshlrev_b32_e32 v218, 16, v148
	v_and_b32_e32 v219, 0xffff0000, v148
	v_lshlrev_b32_e32 v220, 16, v204
	v_and_b32_e32 v221, 0xffff0000, v204
	v_max_f32_e32 v218, 0xc2700000, v218
	v_max_f32_e32 v219, 0xc2700000, v219
	v_max_f32_e32 v220, 0xc2700000, v220
	v_max_f32_e32 v221, 0xc2700000, v221
	v_mul_f32_e32 v218, 0xbfb8aa3b, v218
	v_mul_f32_e32 v219, 0xbfb8aa3b, v219
	v_mul_f32_e32 v220, 0xbfb8aa3b, v220
	v_mul_f32_e32 v221, 0xbfb8aa3b, v221
	v_exp_f32_e32 v218, v218
	v_exp_f32_e32 v219, v219
	v_exp_f32_e32 v220, v220
	v_exp_f32_e32 v221, v221
	v_add_f32_e32 v218, 1.0, v218
	v_add_f32_e32 v219, 1.0, v219
	v_add_f32_e32 v220, 1.0, v220
	v_add_f32_e32 v221, 1.0, v221
	v_rcp_f32_e32 v218, v218
	v_rcp_f32_e32 v219, v219
	v_mul_f32_e32 v218, v218, v220
	v_mul_f32_e32 v219, v219, v221
	v_pk_mul_f32 v[26:27], v[26:27], v[218:219]
	v_lshlrev_b32_e32 v242, 16, v149
	v_and_b32_e32 v243, 0xffff0000, v149
	v_lshlrev_b32_e32 v246, 16, v205
	v_and_b32_e32 v247, 0xffff0000, v205
	v_max_f32_e32 v242, 0xc2700000, v242
	v_max_f32_e32 v243, 0xc2700000, v243
	v_max_f32_e32 v246, 0xc2700000, v246
	v_max_f32_e32 v247, 0xc2700000, v247
	v_mul_f32_e32 v242, 0xbfb8aa3b, v242
	v_mul_f32_e32 v243, 0xbfb8aa3b, v243
	v_mul_f32_e32 v246, 0xbfb8aa3b, v246
	v_mul_f32_e32 v247, 0xbfb8aa3b, v247
	v_exp_f32_e32 v242, v242
	v_exp_f32_e32 v243, v243
	v_exp_f32_e32 v246, v246
	v_exp_f32_e32 v247, v247
	v_add_f32_e32 v242, 1.0, v242
	v_add_f32_e32 v243, 1.0, v243
	v_add_f32_e32 v246, 1.0, v246
	v_add_f32_e32 v247, 1.0, v247
	v_rcp_f32_e32 v242, v242
	v_rcp_f32_e32 v243, v243
	v_mul_f32_e32 v242, v242, v246
	v_mul_f32_e32 v243, v243, v247
	v_pk_mul_f32 v[28:29], v[28:29], v[242:243]
	v_lshlrev_b32_e32 v218, 16, v150
	v_and_b32_e32 v219, 0xffff0000, v150
	v_lshlrev_b32_e32 v220, 16, v206
	v_and_b32_e32 v221, 0xffff0000, v206
	v_max_f32_e32 v218, 0xc2700000, v218
	v_max_f32_e32 v219, 0xc2700000, v219
	v_max_f32_e32 v220, 0xc2700000, v220
	v_max_f32_e32 v221, 0xc2700000, v221
	v_mul_f32_e32 v218, 0xbfb8aa3b, v218
	v_mul_f32_e32 v219, 0xbfb8aa3b, v219
	v_mul_f32_e32 v220, 0xbfb8aa3b, v220
	v_mul_f32_e32 v221, 0xbfb8aa3b, v221
	v_exp_f32_e32 v218, v218
	v_exp_f32_e32 v219, v219
	v_exp_f32_e32 v220, v220
	v_exp_f32_e32 v221, v221
	v_add_f32_e32 v218, 1.0, v218
	v_add_f32_e32 v219, 1.0, v219
	v_add_f32_e32 v220, 1.0, v220
	v_add_f32_e32 v221, 1.0, v221
	v_rcp_f32_e32 v218, v218
	v_rcp_f32_e32 v219, v219
	v_mul_f32_e32 v218, v218, v220
	v_mul_f32_e32 v219, v219, v221
	v_pk_mul_f32 v[22:23], v[22:23], v[218:219]
	v_lshlrev_b32_e32 v242, 16, v151
	v_and_b32_e32 v243, 0xffff0000, v151
	v_lshlrev_b32_e32 v246, 16, v207
	v_and_b32_e32 v247, 0xffff0000, v207
	v_max_f32_e32 v242, 0xc2700000, v242
	v_max_f32_e32 v243, 0xc2700000, v243
	v_max_f32_e32 v246, 0xc2700000, v246
	v_max_f32_e32 v247, 0xc2700000, v247
	v_mul_f32_e32 v242, 0xbfb8aa3b, v242
	v_mul_f32_e32 v243, 0xbfb8aa3b, v243
	v_mul_f32_e32 v246, 0xbfb8aa3b, v246
	v_mul_f32_e32 v247, 0xbfb8aa3b, v247
	v_exp_f32_e32 v242, v242
	v_exp_f32_e32 v243, v243
	v_exp_f32_e32 v246, v246
	v_exp_f32_e32 v247, v247
	v_add_f32_e32 v242, 1.0, v242
	v_add_f32_e32 v243, 1.0, v243
	v_add_f32_e32 v246, 1.0, v246
	v_add_f32_e32 v247, 1.0, v247
	v_rcp_f32_e32 v242, v242
	v_rcp_f32_e32 v243, v243
	v_mul_f32_e32 v242, v242, v246
	v_mul_f32_e32 v243, v243, v247
	v_pk_mul_f32 v[24:25], v[24:25], v[242:243]
	v_lshlrev_b32_e32 v218, 16, v152
	v_and_b32_e32 v219, 0xffff0000, v152
	v_lshlrev_b32_e32 v220, 16, v208
	v_and_b32_e32 v221, 0xffff0000, v208
	v_max_f32_e32 v218, 0xc2700000, v218
	v_max_f32_e32 v219, 0xc2700000, v219
	v_max_f32_e32 v220, 0xc2700000, v220
	v_max_f32_e32 v221, 0xc2700000, v221
	v_mul_f32_e32 v218, 0xbfb8aa3b, v218
	v_mul_f32_e32 v219, 0xbfb8aa3b, v219
	v_mul_f32_e32 v220, 0xbfb8aa3b, v220
	v_mul_f32_e32 v221, 0xbfb8aa3b, v221
	v_exp_f32_e32 v218, v218
	v_exp_f32_e32 v219, v219
	v_exp_f32_e32 v220, v220
	v_exp_f32_e32 v221, v221
	v_add_f32_e32 v218, 1.0, v218
	v_add_f32_e32 v219, 1.0, v219
	v_add_f32_e32 v220, 1.0, v220
	v_add_f32_e32 v221, 1.0, v221
	v_rcp_f32_e32 v218, v218
	v_rcp_f32_e32 v219, v219
	v_mul_f32_e32 v218, v218, v220
	v_mul_f32_e32 v219, v219, v221
	v_pk_mul_f32 v[18:19], v[18:19], v[218:219]
	v_lshlrev_b32_e32 v242, 16, v153
	v_and_b32_e32 v243, 0xffff0000, v153
	v_lshlrev_b32_e32 v246, 16, v209
	v_and_b32_e32 v247, 0xffff0000, v209
	v_max_f32_e32 v242, 0xc2700000, v242
	v_max_f32_e32 v243, 0xc2700000, v243
	v_max_f32_e32 v246, 0xc2700000, v246
	v_max_f32_e32 v247, 0xc2700000, v247
	v_mul_f32_e32 v242, 0xbfb8aa3b, v242
	v_mul_f32_e32 v243, 0xbfb8aa3b, v243
	v_mul_f32_e32 v246, 0xbfb8aa3b, v246
	v_mul_f32_e32 v247, 0xbfb8aa3b, v247
	v_exp_f32_e32 v242, v242
	v_exp_f32_e32 v243, v243
	v_exp_f32_e32 v246, v246
	v_exp_f32_e32 v247, v247
	v_add_f32_e32 v242, 1.0, v242
	v_add_f32_e32 v243, 1.0, v243
	v_add_f32_e32 v246, 1.0, v246
	v_add_f32_e32 v247, 1.0, v247
	v_rcp_f32_e32 v242, v242
	v_rcp_f32_e32 v243, v243
	v_mul_f32_e32 v242, v242, v246
	v_mul_f32_e32 v243, v243, v247
	v_pk_mul_f32 v[20:21], v[20:21], v[242:243]
	s_waitcnt vmcnt(0)
; __device__ __forceinline__ float bf_lo(unsigned w) { return __uint_as_float(w << 16); }
; __device__ __forceinline__ float bf_hi(unsigned w) { return __uint_as_float(w & 0xffff0000u); }
; __device__ __forceinline__ float sigm(float x) { return __builtin_amdgcn_rcpf(1.f + __builtin_amdgcn_exp2f(-1.4426950408889634f * x)); }
;     __device__ __forceinline__ void operator()(const f32x4 (&acc)[2][2][4][2], const Unit& u, int wr, int wc, int fr, int fq) const {
;     ...
;                 for (int bj = 0; bj < 2; ++bj) { const int row = row0 + ai * HALF + m * 16, col = col0 + bj * HALF; const u32x4 g4 = gv[m][bj];
;                     const f32x4 a0 = acc[ai][bj][m][0], a1 = acc[ai][bj][m][1];
;                     float f0 = a0[0] * bf_lo(g4.x), f1 = a0[1] * bf_hi(g4.x), f2 = a0[2] * bf_lo(g4.y), f3 = a0[3] * bf_hi(g4.y);
;                     float f4 = a1[0] * bf_lo(g4.z), f5 = a1[1] * bf_hi(g4.z), f6 = a1[2] * bf_lo(g4.w), f7 = a1[3] * bf_hi(g4.w);
;                     if (br > 0) {
;                         const unsigned p0 = (unsigned)q0[m][bj], p1 = (unsigned)(q0[m][bj] >> 32), p2 = (unsigned)q1[m][bj], p3 = (unsigned)(q1[m][bj] >> 32);
;                         f0 += bf_lo(p0); f1 += bf_hi(p0); f2 += bf_lo(p1); f3 += bf_hi(p1); f4 += bf_lo(p2); f5 += bf_hi(p2); f6 += bf_lo(p3); f7 += bf_hi(p3);
;                     }
	v_lshlrev_b32_e32 v218, 16, v154
	v_and_b32_e32 v219, 0xffff0000, v154
	v_lshlrev_b32_e32 v220, 16, v210
	v_and_b32_e32 v221, 0xffff0000, v210
	v_max_f32_e32 v218, 0xc2700000, v218
	v_max_f32_e32 v219, 0xc2700000, v219
	v_max_f32_e32 v220, 0xc2700000, v220
	v_max_f32_e32 v221, 0xc2700000, v221
	v_mul_f32_e32 v218, 0xbfb8aa3b, v218
	v_mul_f32_e32 v219, 0xbfb8aa3b, v219
	v_mul_f32_e32 v220, 0xbfb8aa3b, v220
	v_mul_f32_e32 v221, 0xbfb8aa3b, v221
	v_exp_f32_e32 v218, v218
	v_exp_f32_e32 v219, v219
	v_exp_f32_e32 v220, v220
	v_exp_f32_e32 v221, v221
	v_add_f32_e32 v218, 1.0, v218
	v_add_f32_e32 v219, 1.0, v219
	v_add_f32_e32 v220, 1.0, v220
	v_add_f32_e32 v221, 1.0, v221
	v_rcp_f32_e32 v218, v218
	v_rcp_f32_e32 v219, v219
	v_mul_f32_e32 v218, v218, v220
	v_mul_f32_e32 v219, v219, v221
	v_pk_mul_f32 v[14:15], v[14:15], v[218:219]
	v_lshlrev_b32_e32 v242, 16, v155
	v_and_b32_e32 v243, 0xffff0000, v155
	v_lshlrev_b32_e32 v246, 16, v211
	v_and_b32_e32 v247, 0xffff0000, v211
	v_max_f32_e32 v242, 0xc2700000, v242
	v_max_f32_e32 v243, 0xc2700000, v243
	v_max_f32_e32 v246, 0xc2700000, v246
	v_max_f32_e32 v247, 0xc2700000, v247
	v_mul_f32_e32 v242, 0xbfb8aa3b, v242
	v_mul_f32_e32 v243, 0xbfb8aa3b, v243
	v_mul_f32_e32 v246, 0xbfb8aa3b, v246
	v_mul_f32_e32 v247, 0xbfb8aa3b, v247
	v_exp_f32_e32 v242, v242
	v_exp_f32_e32 v243, v243
	v_exp_f32_e32 v246, v246
	v_exp_f32_e32 v247, v247
	v_add_f32_e32 v242, 1.0, v242
	v_add_f32_e32 v243, 1.0, v243
	v_add_f32_e32 v246, 1.0, v246
	v_add_f32_e32 v247, 1.0, v247
	v_rcp_f32_e32 v242, v242
	v_rcp_f32_e32 v243, v243
	v_mul_f32_e32 v242, v242, v246
	v_mul_f32_e32 v243, v243, v247
	v_pk_mul_f32 v[16:17], v[16:17], v[242:243]
	v_lshlrev_b32_e32 v218, 16, v156
	v_and_b32_e32 v219, 0xffff0000, v156
	v_lshlrev_b32_e32 v220, 16, v212
	v_and_b32_e32 v221, 0xffff0000, v212
	v_max_f32_e32 v218, 0xc2700000, v218
	v_max_f32_e32 v219, 0xc2700000, v219
	v_max_f32_e32 v220, 0xc2700000, v220
	v_max_f32_e32 v221, 0xc2700000, v221
	v_mul_f32_e32 v218, 0xbfb8aa3b, v218
	v_mul_f32_e32 v219, 0xbfb8aa3b, v219
	v_mul_f32_e32 v220, 0xbfb8aa3b, v220
	v_mul_f32_e32 v221, 0xbfb8aa3b, v221
	v_exp_f32_e32 v218, v218
	v_exp_f32_e32 v219, v219
	v_exp_f32_e32 v220, v220
	v_exp_f32_e32 v221, v221
	v_add_f32_e32 v218, 1.0, v218
	v_add_f32_e32 v219, 1.0, v219
	v_add_f32_e32 v220, 1.0, v220
	v_add_f32_e32 v221, 1.0, v221
	v_rcp_f32_e32 v218, v218
	v_rcp_f32_e32 v219, v219
	v_mul_f32_e32 v218, v218, v220
	v_mul_f32_e32 v219, v219, v221
	v_pk_mul_f32 v[10:11], v[10:11], v[218:219]
	v_lshlrev_b32_e32 v242, 16, v157
	v_and_b32_e32 v243, 0xffff0000, v157
	v_lshlrev_b32_e32 v246, 16, v213
	v_and_b32_e32 v247, 0xffff0000, v213
	v_max_f32_e32 v242, 0xc2700000, v242
	v_max_f32_e32 v243, 0xc2700000, v243
	v_max_f32_e32 v246, 0xc2700000, v246
	v_max_f32_e32 v247, 0xc2700000, v247
	v_mul_f32_e32 v242, 0xbfb8aa3b, v242
	v_mul_f32_e32 v243, 0xbfb8aa3b, v243
	v_mul_f32_e32 v246, 0xbfb8aa3b, v246
	v_mul_f32_e32 v247, 0xbfb8aa3b, v247
	v_exp_f32_e32 v242, v242
	v_exp_f32_e32 v243, v243
	v_exp_f32_e32 v246, v246
	v_exp_f32_e32 v247, v247
	v_add_f32_e32 v242, 1.0, v242
	v_add_f32_e32 v243, 1.0, v243
	v_add_f32_e32 v246, 1.0, v246
	v_add_f32_e32 v247, 1.0, v247
	v_rcp_f32_e32 v242, v242
	v_rcp_f32_e32 v243, v243
	v_mul_f32_e32 v242, v242, v246
	v_mul_f32_e32 v243, v243, v247
	v_pk_mul_f32 v[12:13], v[12:13], v[242:243]
	v_lshlrev_b32_e32 v218, 16, v158
	v_and_b32_e32 v219, 0xffff0000, v158
	v_lshlrev_b32_e32 v220, 16, v214
	v_and_b32_e32 v221, 0xffff0000, v214
	v_max_f32_e32 v218, 0xc2700000, v218
	v_max_f32_e32 v219, 0xc2700000, v219
	v_max_f32_e32 v220, 0xc2700000, v220
	v_max_f32_e32 v221, 0xc2700000, v221
	v_mul_f32_e32 v218, 0xbfb8aa3b, v218
	v_mul_f32_e32 v219, 0xbfb8aa3b, v219
	v_mul_f32_e32 v220, 0xbfb8aa3b, v220
	v_mul_f32_e32 v221, 0xbfb8aa3b, v221
	v_exp_f32_e32 v218, v218
	v_exp_f32_e32 v219, v219
	v_exp_f32_e32 v220, v220
	v_exp_f32_e32 v221, v221
	v_add_f32_e32 v218, 1.0, v218
	v_add_f32_e32 v219, 1.0, v219
	v_add_f32_e32 v220, 1.0, v220
	v_add_f32_e32 v221, 1.0, v221
	v_rcp_f32_e32 v218, v218
	v_rcp_f32_e32 v219, v219
	v_mul_f32_e32 v218, v218, v220
	v_mul_f32_e32 v219, v219, v221
	v_pk_mul_f32 v[6:7], v[6:7], v[218:219]
	v_lshlrev_b32_e32 v242, 16, v159
	v_and_b32_e32 v243, 0xffff0000, v159
	v_lshlrev_b32_e32 v246, 16, v215
	v_and_b32_e32 v247, 0xffff0000, v215
	v_max_f32_e32 v242, 0xc2700000, v242
	v_max_f32_e32 v243, 0xc2700000, v243
	v_max_f32_e32 v246, 0xc2700000, v246
	v_max_f32_e32 v247, 0xc2700000, v247
	v_mul_f32_e32 v242, 0xbfb8aa3b, v242
	v_mul_f32_e32 v243, 0xbfb8aa3b, v243
	v_mul_f32_e32 v246, 0xbfb8aa3b, v246
	v_mul_f32_e32 v247, 0xbfb8aa3b, v247
	v_exp_f32_e32 v242, v242
	v_exp_f32_e32 v243, v243
	v_exp_f32_e32 v246, v246
	v_exp_f32_e32 v247, v247
	v_add_f32_e32 v242, 1.0, v242
	v_add_f32_e32 v243, 1.0, v243
	v_add_f32_e32 v246, 1.0, v246
	v_add_f32_e32 v247, 1.0, v247
	v_rcp_f32_e32 v242, v242
	v_rcp_f32_e32 v243, v243
	v_mul_f32_e32 v242, v242, v246
	v_mul_f32_e32 v243, v243, v247
	v_pk_mul_f32 v[8:9], v[8:9], v[242:243]
	v_lshlrev_b32_e32 v218, 16, v160
	v_and_b32_e32 v219, 0xffff0000, v160
	v_lshlrev_b32_e32 v220, 16, v216
	v_and_b32_e32 v221, 0xffff0000, v216
	v_max_f32_e32 v218, 0xc2700000, v218
	v_max_f32_e32 v219, 0xc2700000, v219
	v_max_f32_e32 v220, 0xc2700000, v220
	v_max_f32_e32 v221, 0xc2700000, v221
	v_mul_f32_e32 v218, 0xbfb8aa3b, v218
	v_mul_f32_e32 v219, 0xbfb8aa3b, v219
	v_mul_f32_e32 v220, 0xbfb8aa3b, v220
	v_mul_f32_e32 v221, 0xbfb8aa3b, v221
	v_exp_f32_e32 v218, v218
	v_exp_f32_e32 v219, v219
	v_exp_f32_e32 v220, v220
	v_exp_f32_e32 v221, v221
	v_add_f32_e32 v218, 1.0, v218
	v_add_f32_e32 v219, 1.0, v219
	v_add_f32_e32 v220, 1.0, v220
	v_add_f32_e32 v221, 1.0, v221
	v_rcp_f32_e32 v218, v218
	v_rcp_f32_e32 v219, v219
	v_mul_f32_e32 v218, v218, v220
	v_mul_f32_e32 v219, v219, v221
	v_pk_mul_f32 v[2:3], v[2:3], v[218:219]
	v_lshlrev_b32_e32 v242, 16, v161
	v_and_b32_e32 v243, 0xffff0000, v161
	v_lshlrev_b32_e32 v246, 16, v217
	v_and_b32_e32 v247, 0xffff0000, v217
	v_max_f32_e32 v242, 0xc2700000, v242
	v_max_f32_e32 v243, 0xc2700000, v243
	v_max_f32_e32 v246, 0xc2700000, v246
	v_max_f32_e32 v247, 0xc2700000, v247
	v_mul_f32_e32 v242, 0xbfb8aa3b, v242
	v_mul_f32_e32 v243, 0xbfb8aa3b, v243
	v_mul_f32_e32 v246, 0xbfb8aa3b, v246
	v_mul_f32_e32 v247, 0xbfb8aa3b, v247
	v_exp_f32_e32 v242, v242
	v_exp_f32_e32 v243, v243
	v_exp_f32_e32 v246, v246
	v_exp_f32_e32 v247, v247
	v_add_f32_e32 v242, 1.0, v242
	v_add_f32_e32 v243, 1.0, v243
	v_add_f32_e32 v246, 1.0, v246
	v_add_f32_e32 v247, 1.0, v247
	v_rcp_f32_e32 v242, v242
	v_rcp_f32_e32 v243, v243
	v_mul_f32_e32 v242, v242, v246
	v_mul_f32_e32 v243, v243, v247
	v_pk_mul_f32 v[4:5], v[4:5], v[242:243]
	s_branch .Lrb_tail
; __device__ __forceinline__ unsigned cvt_pk_bf16(float lo, float hi) { unsigned r; asm volatile("v_cvt_pk_bf16_f32 %0, %1, %2" : "=v"(r) : "v"(lo), "v"(hi)); return r; }
; __device__ __forceinline__ float bf_lo(unsigned w) { return __uint_as_float(w << 16); }
; __device__ __forceinline__ float bf_hi(unsigned w) { return __uint_as_float(w & 0xffff0000u); }
; __device__ __forceinline__ float sigm(float x) { return __builtin_amdgcn_rcpf(1.f + __builtin_amdgcn_exp2f(-1.4426950408889634f * x)); }
;     __device__ __forceinline__ void operator()(const f32x4 (&acc)[2][2][4][2], const Unit& u, int wr, int wc, int fr, int fq) const {
;     ...
;                 for (int bj = 0; bj < 2; ++bj) { const int row = row0 + ai * HALF + m * 16, col = col0 + bj * HALF; const u32x4 g4 = gv[m][bj];
;                     const f32x4 a0 = acc[ai][bj][m][0], a1 = acc[ai][bj][m][1];
;                     float f0 = a0[0] * bf_lo(g4.x), f1 = a0[1] * bf_hi(g4.x), f2 = a0[2] * bf_lo(g4.y), f3 = a0[3] * bf_hi(g4.y);
;                     float f4 = a1[0] * bf_lo(g4.z), f5 = a1[1] * bf_hi(g4.z), f6 = a1[2] * bf_lo(g4.w), f7 = a1[3] * bf_hi(g4.w);
;                     if (br > 0) {
;                         const unsigned p0 = (unsigned)q0[m][bj], p1 = (unsigned)(q0[m][bj] >> 32), p2 = (unsigned)q1[m][bj], p3 = (unsigned)(q1[m][bj] >> 32);
;                         f0 += bf_lo(p0); f1 += bf_hi(p0); f2 += bf_lo(p1); f3 += bf_hi(p1); f4 += bf_lo(p2); f5 += bf_hi(p2); f6 += bf_lo(p3); f7 += bf_hi(p3);
;                     }
;                     u32x4 w; w.x = cvt_pk_bf16(f0, f1); w.y = cvt_pk_bf16(f2, f3); w.z = cvt_pk_bf16(f4, f5); w.w = cvt_pk_bf16(f6, f7);
;                     *(u32x4*)(Mg + (size_t)row * DM + col) = w; }
;             asm volatile("" ::: "memory"); }
.Lrb_final:
	global_load_dwordx4 v[130:133], v[222:223], off
	global_load_dwordx4 v[134:137], v[222:223], off offset:256
	v_lshl_add_u64 v[222:223], v[222:223], 0, s[8:9]
	global_load_dwordx4 v[138:141], v[222:223], off
	global_load_dwordx4 v[142:145], v[222:223], off offset:256
	v_lshl_add_u64 v[222:223], v[222:223], 0, s[8:9]
	global_load_dwordx4 v[146:149], v[222:223], off
	global_load_dwordx4 v[150:153], v[222:223], off offset:256
	v_lshl_add_u64 v[222:223], v[222:223], 0, s[8:9]
	global_load_dwordx4 v[154:157], v[222:223], off
	global_load_dwordx4 v[158:161], v[222:223], off offset:256
	v_lshl_add_u64 v[222:223], v[222:223], 0, s[44:45]
	global_load_dwordx4 v[186:189], v[222:223], off
	global_load_dwordx4 v[190:193], v[222:223], off offset:256
	v_lshl_add_u64 v[222:223], v[222:223], 0, s[8:9]
	global_load_dwordx4 v[194:197], v[222:223], off
	global_load_dwordx4 v[198:201], v[222:223], off offset:256
	v_lshl_add_u64 v[222:223], v[222:223], 0, s[8:9]
	global_load_dwordx4 v[202:205], v[222:223], off
	global_load_dwordx4 v[206:209], v[222:223], off offset:256
	v_lshl_add_u64 v[222:223], v[222:223], 0, s[8:9]
	global_load_dwordx4 v[210:213], v[222:223], off
	global_load_dwordx4 v[214:217], v[222:223], off offset:256
	s_waitcnt vmcnt(15)
	v_lshlrev_b32_e32 v218, 16, v130
	v_and_b32_e32 v219, 0xffff0000, v130
	v_max_f32_e32 v218, 0xc2700000, v218
	v_max_f32_e32 v219, 0xc2700000, v219
	v_mul_f32_e32 v218, 0xbfb8aa3b, v218
	v_mul_f32_e32 v219, 0xbfb8aa3b, v219
	v_exp_f32_e32 v218, v218
	v_exp_f32_e32 v219, v219
	v_add_f32_e32 v218, 1.0, v218
	v_add_f32_e32 v219, 1.0, v219
	v_rcp_f32_e32 v218, v218
	v_rcp_f32_e32 v219, v219
	s_nop 0
	v_pk_mul_f32 v[126:127], v[126:127], v[218:219]
	v_lshlrev_b32_e32 v242, 16, v131
	v_and_b32_e32 v243, 0xffff0000, v131
	v_max_f32_e32 v242, 0xc2700000, v242
	v_max_f32_e32 v243, 0xc2700000, v243
	v_mul_f32_e32 v242, 0xbfb8aa3b, v242
	v_mul_f32_e32 v243, 0xbfb8aa3b, v243
	v_exp_f32_e32 v242, v242
	v_exp_f32_e32 v243, v243
	v_add_f32_e32 v242, 1.0, v242
	v_add_f32_e32 v243, 1.0, v243
	v_rcp_f32_e32 v242, v242
	v_rcp_f32_e32 v243, v243
	s_nop 0
	v_pk_mul_f32 v[128:129], v[128:129], v[242:243]
	v_lshlrev_b32_e32 v218, 16, v132
	v_and_b32_e32 v219, 0xffff0000, v132
	v_max_f32_e32 v218, 0xc2700000, v218
	v_max_f32_e32 v219, 0xc2700000, v219
	v_mul_f32_e32 v218, 0xbfb8aa3b, v218
	v_mul_f32_e32 v219, 0xbfb8aa3b, v219
	v_exp_f32_e32 v218, v218
	v_exp_f32_e32 v219, v219
	v_add_f32_e32 v218, 1.0, v218
	v_add_f32_e32 v219, 1.0, v219
	v_rcp_f32_e32 v218, v218
	v_rcp_f32_e32 v219, v219
	s_nop 0
	v_pk_mul_f32 v[122:123], v[122:123], v[218:219]
	v_lshlrev_b32_e32 v242, 16, v133
	v_and_b32_e32 v243, 0xffff0000, v133
	v_max_f32_e32 v242, 0xc2700000, v242
	v_max_f32_e32 v243, 0xc2700000, v243
	v_mul_f32_e32 v242, 0xbfb8aa3b, v242
	v_mul_f32_e32 v243, 0xbfb8aa3b, v243
	v_exp_f32_e32 v242, v242
	v_exp_f32_e32 v243, v243
	v_add_f32_e32 v242, 1.0, v242
	v_add_f32_e32 v243, 1.0, v243
	v_rcp_f32_e32 v242, v242
	v_rcp_f32_e32 v243, v243
	s_nop 0
	v_pk_mul_f32 v[124:125], v[124:125], v[242:243]
	v_cvt_pk_bf16_f32 v126, v126, v127
	v_cvt_pk_bf16_f32 v127, v128, v129
	v_cvt_pk_bf16_f32 v128, v122, v123
	v_cvt_pk_bf16_f32 v129, v124, v125
	global_store_dwordx4 v[226:227], v[126:129], off
	s_waitcnt vmcnt(15)
	v_lshlrev_b32_e32 v218, 16, v134
	v_and_b32_e32 v219, 0xffff0000, v134
	v_max_f32_e32 v218, 0xc2700000, v218
	v_max_f32_e32 v219, 0xc2700000, v219
	v_mul_f32_e32 v218, 0xbfb8aa3b, v218
	v_mul_f32_e32 v219, 0xbfb8aa3b, v219
	v_exp_f32_e32 v218, v218
	v_exp_f32_e32 v219, v219
	v_add_f32_e32 v218, 1.0, v218
	v_add_f32_e32 v219, 1.0, v219
	v_rcp_f32_e32 v218, v218
	v_rcp_f32_e32 v219, v219
	s_nop 0
	v_pk_mul_f32 v[118:119], v[118:119], v[218:219]
	v_lshlrev_b32_e32 v242, 16, v135
	v_and_b32_e32 v243, 0xffff0000, v135
	v_max_f32_e32 v242, 0xc2700000, v242
	v_max_f32_e32 v243, 0xc2700000, v243
	v_mul_f32_e32 v242, 0xbfb8aa3b, v242
	v_mul_f32_e32 v243, 0xbfb8aa3b, v243
	v_exp_f32_e32 v242, v242
	v_exp_f32_e32 v243, v243
	v_add_f32_e32 v242, 1.0, v242
	v_add_f32_e32 v243, 1.0, v243
	v_rcp_f32_e32 v242, v242
	v_rcp_f32_e32 v243, v243
	s_nop 0
	v_pk_mul_f32 v[120:121], v[120:121], v[242:243]
	v_lshlrev_b32_e32 v218, 16, v136
	v_and_b32_e32 v219, 0xffff0000, v136
	v_max_f32_e32 v218, 0xc2700000, v218
	v_max_f32_e32 v219, 0xc2700000, v219
	v_mul_f32_e32 v218, 0xbfb8aa3b, v218
	v_mul_f32_e32 v219, 0xbfb8aa3b, v219
	v_exp_f32_e32 v218, v218
	v_exp_f32_e32 v219, v219
	v_add_f32_e32 v218, 1.0, v218
	v_add_f32_e32 v219, 1.0, v219
	v_rcp_f32_e32 v218, v218
	v_rcp_f32_e32 v219, v219
	s_nop 0
	v_pk_mul_f32 v[114:115], v[114:115], v[218:219]
	v_lshlrev_b32_e32 v242, 16, v137
	v_and_b32_e32 v243, 0xffff0000, v137
	v_max_f32_e32 v242, 0xc2700000, v242
	v_max_f32_e32 v243, 0xc2700000, v243
	v_mul_f32_e32 v242, 0xbfb8aa3b, v242
	v_mul_f32_e32 v243, 0xbfb8aa3b, v243
	v_exp_f32_e32 v242, v242
	v_exp_f32_e32 v243, v243
	v_add_f32_e32 v242, 1.0, v242
	v_add_f32_e32 v243, 1.0, v243
	v_rcp_f32_e32 v242, v242
	v_rcp_f32_e32 v243, v243
	s_nop 0
	v_pk_mul_f32 v[116:117], v[116:117], v[242:243]
	v_cvt_pk_bf16_f32 v118, v118, v119
	v_cvt_pk_bf16_f32 v119, v120, v121
	v_cvt_pk_bf16_f32 v120, v114, v115
	v_cvt_pk_bf16_f32 v121, v116, v117
	global_store_dwordx4 v[226:227], v[118:121], off offset:256
	s_waitcnt vmcnt(15)
; __device__ __forceinline__ unsigned cvt_pk_bf16(float lo, float hi) { unsigned r; asm volatile("v_cvt_pk_bf16_f32 %0, %1, %2" : "=v"(r) : "v"(lo), "v"(hi)); return r; }
; __device__ __forceinline__ float bf_lo(unsigned w) { return __uint_as_float(w << 16); }
; __device__ __forceinline__ float bf_hi(unsigned w) { return __uint_as_float(w & 0xffff0000u); }
; __device__ __forceinline__ float sigm(float x) { return __builtin_amdgcn_rcpf(1.f + __builtin_amdgcn_exp2f(-1.4426950408889634f * x)); }
;     __device__ __forceinline__ void operator()(const f32x4 (&acc)[2][2][4][2], const Unit& u, int wr, int wc, int fr, int fq) const {
;     ...
;                 for (int bj = 0; bj < 2; ++bj) { const int row = row0 + ai * HALF + m * 16, col = col0 + bj * HALF; const u32x4 g4 = gv[m][bj];
;                     const f32x4 a0 = acc[ai][bj][m][0], a1 = acc[ai][bj][m][1];
;                     float f0 = a0[0] * bf_lo(g4.x), f1 = a0[1] * bf_hi(g4.x), f2 = a0[2] * bf_lo(g4.y), f3 = a0[3] * bf_hi(g4.y);
;                     float f4 = a1[0] * bf_lo(g4.z), f5 = a1[1] * bf_hi(g4.z), f6 = a1[2] * bf_lo(g4.w), f7 = a1[3] * bf_hi(g4.w);
;                     if (br > 0) {
;                         const unsigned p0 = (unsigned)q0[m][bj], p1 = (unsigned)(q0[m][bj] >> 32), p2 = (unsigned)q1[m][bj], p3 = (unsigned)(q1[m][bj] >> 32);
;                         f0 += bf_lo(p0); f1 += bf_hi(p0); f2 += bf_lo(p1); f3 += bf_hi(p1); f4 += bf_lo(p2); f5 += bf_hi(p2); f6 += bf_lo(p3); f7 += bf_hi(p3);
;                     }
;                     u32x4 w; w.x = cvt_pk_bf16(f0, f1); w.y = cvt_pk_bf16(f2, f3); w.z = cvt_pk_bf16(f4, f5); w.w = cvt_pk_bf16(f6, f7);
;                     *(u32x4*)(Mg + (size_t)row * DM + col) = w; }
;             asm volatile("" ::: "memory"); }
	v_lshlrev_b32_e32 v218, 16, v138
	v_and_b32_e32 v219, 0xffff0000, v138
	v_max_f32_e32 v218, 0xc2700000, v218
	v_max_f32_e32 v219, 0xc2700000, v219
	v_mul_f32_e32 v218, 0xbfb8aa3b, v218
	v_mul_f32_e32 v219, 0xbfb8aa3b, v219
	v_exp_f32_e32 v218, v218
	v_exp_f32_e32 v219, v219
	v_add_f32_e32 v218, 1.0, v218
	v_add_f32_e32 v219, 1.0, v219
	v_rcp_f32_e32 v218, v218
	v_rcp_f32_e32 v219, v219
	s_nop 0
	v_pk_mul_f32 v[110:111], v[110:111], v[218:219]
	v_lshlrev_b32_e32 v242, 16, v139
	v_and_b32_e32 v243, 0xffff0000, v139
	v_max_f32_e32 v242, 0xc2700000, v242
	v_max_f32_e32 v243, 0xc2700000, v243
	v_mul_f32_e32 v242, 0xbfb8aa3b, v242
	v_mul_f32_e32 v243, 0xbfb8aa3b, v243
	v_exp_f32_e32 v242, v242
	v_exp_f32_e32 v243, v243
	v_add_f32_e32 v242, 1.0, v242
	v_add_f32_e32 v243, 1.0, v243
	v_rcp_f32_e32 v242, v242
	v_rcp_f32_e32 v243, v243
	s_nop 0
	v_pk_mul_f32 v[112:113], v[112:113], v[242:243]
	v_lshlrev_b32_e32 v218, 16, v140
	v_and_b32_e32 v219, 0xffff0000, v140
	v_max_f32_e32 v218, 0xc2700000, v218
	v_max_f32_e32 v219, 0xc2700000, v219
	v_mul_f32_e32 v218, 0xbfb8aa3b, v218
	v_mul_f32_e32 v219, 0xbfb8aa3b, v219
	v_exp_f32_e32 v218, v218
	v_exp_f32_e32 v219, v219
	v_add_f32_e32 v218, 1.0, v218
	v_add_f32_e32 v219, 1.0, v219
	v_rcp_f32_e32 v218, v218
	v_rcp_f32_e32 v219, v219
	s_nop 0
	v_pk_mul_f32 v[106:107], v[106:107], v[218:219]
	v_lshlrev_b32_e32 v242, 16, v141
	v_and_b32_e32 v243, 0xffff0000, v141
	v_max_f32_e32 v242, 0xc2700000, v242
	v_max_f32_e32 v243, 0xc2700000, v243
	v_mul_f32_e32 v242, 0xbfb8aa3b, v242
	v_mul_f32_e32 v243, 0xbfb8aa3b, v243
	v_exp_f32_e32 v242, v242
	v_exp_f32_e32 v243, v243
	v_add_f32_e32 v242, 1.0, v242
	v_add_f32_e32 v243, 1.0, v243
	v_rcp_f32_e32 v242, v242
	v_rcp_f32_e32 v243, v243
	s_nop 0
	v_pk_mul_f32 v[108:109], v[108:109], v[242:243]
	v_cvt_pk_bf16_f32 v110, v110, v111
	v_cvt_pk_bf16_f32 v111, v112, v113
	v_cvt_pk_bf16_f32 v112, v106, v107
	v_cvt_pk_bf16_f32 v113, v108, v109
	v_lshl_add_u64 v[226:227], v[226:227], 0, s[46:47]
	global_store_dwordx4 v[226:227], v[110:113], off
	s_waitcnt vmcnt(15)
	v_lshlrev_b32_e32 v218, 16, v142
	v_and_b32_e32 v219, 0xffff0000, v142
	v_max_f32_e32 v218, 0xc2700000, v218
	v_max_f32_e32 v219, 0xc2700000, v219
	v_mul_f32_e32 v218, 0xbfb8aa3b, v218
	v_mul_f32_e32 v219, 0xbfb8aa3b, v219
	v_exp_f32_e32 v218, v218
	v_exp_f32_e32 v219, v219
	v_add_f32_e32 v218, 1.0, v218
	v_add_f32_e32 v219, 1.0, v219
	v_rcp_f32_e32 v218, v218
	v_rcp_f32_e32 v219, v219
	s_nop 0
	v_pk_mul_f32 v[102:103], v[102:103], v[218:219]
	v_lshlrev_b32_e32 v242, 16, v143
	v_and_b32_e32 v243, 0xffff0000, v143
	v_max_f32_e32 v242, 0xc2700000, v242
	v_max_f32_e32 v243, 0xc2700000, v243
	v_mul_f32_e32 v242, 0xbfb8aa3b, v242
	v_mul_f32_e32 v243, 0xbfb8aa3b, v243
	v_exp_f32_e32 v242, v242
	v_exp_f32_e32 v243, v243
	v_add_f32_e32 v242, 1.0, v242
	v_add_f32_e32 v243, 1.0, v243
	v_rcp_f32_e32 v242, v242
	v_rcp_f32_e32 v243, v243
	s_nop 0
	v_pk_mul_f32 v[104:105], v[104:105], v[242:243]
	v_lshlrev_b32_e32 v218, 16, v144
	v_and_b32_e32 v219, 0xffff0000, v144
	v_max_f32_e32 v218, 0xc2700000, v218
	v_max_f32_e32 v219, 0xc2700000, v219
	v_mul_f32_e32 v218, 0xbfb8aa3b, v218
	v_mul_f32_e32 v219, 0xbfb8aa3b, v219
	v_exp_f32_e32 v218, v218
	v_exp_f32_e32 v219, v219
	v_add_f32_e32 v218, 1.0, v218
	v_add_f32_e32 v219, 1.0, v219
	v_rcp_f32_e32 v218, v218
	v_rcp_f32_e32 v219, v219
	s_nop 0
	v_pk_mul_f32 v[98:99], v[98:99], v[218:219]
	v_lshlrev_b32_e32 v242, 16, v145
	v_and_b32_e32 v243, 0xffff0000, v145
	v_max_f32_e32 v242, 0xc2700000, v242
	v_max_f32_e32 v243, 0xc2700000, v243
	v_mul_f32_e32 v242, 0xbfb8aa3b, v242
	v_mul_f32_e32 v243, 0xbfb8aa3b, v243
	v_exp_f32_e32 v242, v242
	v_exp_f32_e32 v243, v243
	v_add_f32_e32 v242, 1.0, v242
	v_add_f32_e32 v243, 1.0, v243
	v_rcp_f32_e32 v242, v242
	v_rcp_f32_e32 v243, v243
	s_nop 0
	v_pk_mul_f32 v[100:101], v[100:101], v[242:243]
	v_cvt_pk_bf16_f32 v102, v102, v103
	v_cvt_pk_bf16_f32 v103, v104, v105
	v_cvt_pk_bf16_f32 v104, v98, v99
	v_cvt_pk_bf16_f32 v105, v100, v101
	global_store_dwordx4 v[226:227], v[102:105], off offset:256
	s_waitcnt vmcnt(15)
	v_lshlrev_b32_e32 v218, 16, v146
	v_and_b32_e32 v219, 0xffff0000, v146
	v_max_f32_e32 v218, 0xc2700000, v218
	v_max_f32_e32 v219, 0xc2700000, v219
	v_mul_f32_e32 v218, 0xbfb8aa3b, v218
	v_mul_f32_e32 v219, 0xbfb8aa3b, v219
	v_exp_f32_e32 v218, v218
	v_exp_f32_e32 v219, v219
	v_add_f32_e32 v218, 1.0, v218
	v_add_f32_e32 v219, 1.0, v219
	v_rcp_f32_e32 v218, v218
	v_rcp_f32_e32 v219, v219
	s_nop 0
	v_pk_mul_f32 v[94:95], v[94:95], v[218:219]
	v_lshlrev_b32_e32 v242, 16, v147
	v_and_b32_e32 v243, 0xffff0000, v147
	v_max_f32_e32 v242, 0xc2700000, v242
	v_max_f32_e32 v243, 0xc2700000, v243
	v_mul_f32_e32 v242, 0xbfb8aa3b, v242
	v_mul_f32_e32 v243, 0xbfb8aa3b, v243
	v_exp_f32_e32 v242, v242
	v_exp_f32_e32 v243, v243
	v_add_f32_e32 v242, 1.0, v242
	v_add_f32_e32 v243, 1.0, v243
	v_rcp_f32_e32 v242, v242
	v_rcp_f32_e32 v243, v243
	s_nop 0
	v_pk_mul_f32 v[96:97], v[96:97], v[242:243]
	v_lshlrev_b32_e32 v218, 16, v148
	v_and_b32_e32 v219, 0xffff0000, v148
	v_max_f32_e32 v218, 0xc2700000, v218
	v_max_f32_e32 v219, 0xc2700000, v219
	v_mul_f32_e32 v218, 0xbfb8aa3b, v218
	v_mul_f32_e32 v219, 0xbfb8aa3b, v219
	v_exp_f32_e32 v218, v218
	v_exp_f32_e32 v219, v219
	v_add_f32_e32 v218, 1.0, v218
	v_add_f32_e32 v219, 1.0, v219
	v_rcp_f32_e32 v218, v218
	v_rcp_f32_e32 v219, v219
	s_nop 0
	v_pk_mul_f32 v[90:91], v[90:91], v[218:219]
	v_lshlrev_b32_e32 v242, 16, v149
	v_and_b32_e32 v243, 0xffff0000, v149
	v_max_f32_e32 v242, 0xc2700000, v242
	v_max_f32_e32 v243, 0xc2700000, v243
	v_mul_f32_e32 v242, 0xbfb8aa3b, v242
	v_mul_f32_e32 v243, 0xbfb8aa3b, v243
	v_exp_f32_e32 v242, v242
	v_exp_f32_e32 v243, v243
	v_add_f32_e32 v242, 1.0, v242
	v_add_f32_e32 v243, 1.0, v243
	v_rcp_f32_e32 v242, v242
	v_rcp_f32_e32 v243, v243
	s_nop 0
	v_pk_mul_f32 v[92:93], v[92:93], v[242:243]
	v_cvt_pk_bf16_f32 v94, v94, v95
	v_cvt_pk_bf16_f32 v95, v96, v97
	v_cvt_pk_bf16_f32 v96, v90, v91
	v_cvt_pk_bf16_f32 v97, v92, v93
	v_lshl_add_u64 v[226:227], v[226:227], 0, s[46:47]
	global_store_dwordx4 v[226:227], v[94:97], off
	s_waitcnt vmcnt(15)
; __device__ __forceinline__ unsigned cvt_pk_bf16(float lo, float hi) { unsigned r; asm volatile("v_cvt_pk_bf16_f32 %0, %1, %2" : "=v"(r) : "v"(lo), "v"(hi)); return r; }
; __device__ __forceinline__ float bf_lo(unsigned w) { return __uint_as_float(w << 16); }
; __device__ __forceinline__ float bf_hi(unsigned w) { return __uint_as_float(w & 0xffff0000u); }
; __device__ __forceinline__ float sigm(float x) { return __builtin_amdgcn_rcpf(1.f + __builtin_amdgcn_exp2f(-1.4426950408889634f * x)); }
;     __device__ __forceinline__ void operator()(const f32x4 (&acc)[2][2][4][2], const Unit& u, int wr, int wc, int fr, int fq) const {
;     ...
;                 for (int bj = 0; bj < 2; ++bj) { const int row = row0 + ai * HALF + m * 16, col = col0 + bj * HALF; const u32x4 g4 = gv[m][bj];
;                     const f32x4 a0 = acc[ai][bj][m][0], a1 = acc[ai][bj][m][1];
;                     float f0 = a0[0] * bf_lo(g4.x), f1 = a0[1] * bf_hi(g4.x), f2 = a0[2] * bf_lo(g4.y), f3 = a0[3] * bf_hi(g4.y);
;                     float f4 = a1[0] * bf_lo(g4.z), f5 = a1[1] * bf_hi(g4.z), f6 = a1[2] * bf_lo(g4.w), f7 = a1[3] * bf_hi(g4.w);
;                     if (br > 0) {
;                         const unsigned p0 = (unsigned)q0[m][bj], p1 = (unsigned)(q0[m][bj] >> 32), p2 = (unsigned)q1[m][bj], p3 = (unsigned)(q1[m][bj] >> 32);
;                         f0 += bf_lo(p0); f1 += bf_hi(p0); f2 += bf_lo(p1); f3 += bf_hi(p1); f4 += bf_lo(p2); f5 += bf_hi(p2); f6 += bf_lo(p3); f7 += bf_hi(p3);
;                     }
;                     u32x4 w; w.x = cvt_pk_bf16(f0, f1); w.y = cvt_pk_bf16(f2, f3); w.z = cvt_pk_bf16(f4, f5); w.w = cvt_pk_bf16(f6, f7);
;                     *(u32x4*)(Mg + (size_t)row * DM + col) = w; }
;             asm volatile("" ::: "memory"); }
	v_lshlrev_b32_e32 v218, 16, v150
	v_and_b32_e32 v219, 0xffff0000, v150
	v_max_f32_e32 v218, 0xc2700000, v218
	v_max_f32_e32 v219, 0xc2700000, v219
	v_mul_f32_e32 v218, 0xbfb8aa3b, v218
	v_mul_f32_e32 v219, 0xbfb8aa3b, v219
	v_exp_f32_e32 v218, v218
	v_exp_f32_e32 v219, v219
	v_add_f32_e32 v218, 1.0, v218
	v_add_f32_e32 v219, 1.0, v219
	v_rcp_f32_e32 v218, v218
	v_rcp_f32_e32 v219, v219
	s_nop 0
	v_pk_mul_f32 v[86:87], v[86:87], v[218:219]
	v_lshlrev_b32_e32 v242, 16, v151
	v_and_b32_e32 v243, 0xffff0000, v151
	v_max_f32_e32 v242, 0xc2700000, v242
	v_max_f32_e32 v243, 0xc2700000, v243
	v_mul_f32_e32 v242, 0xbfb8aa3b, v242
	v_mul_f32_e32 v243, 0xbfb8aa3b, v243
	v_exp_f32_e32 v242, v242
	v_exp_f32_e32 v243, v243
	v_add_f32_e32 v242, 1.0, v242
	v_add_f32_e32 v243, 1.0, v243
	v_rcp_f32_e32 v242, v242
	v_rcp_f32_e32 v243, v243
	s_nop 0
	v_pk_mul_f32 v[88:89], v[88:89], v[242:243]
	v_lshlrev_b32_e32 v218, 16, v152
	v_and_b32_e32 v219, 0xffff0000, v152
	v_max_f32_e32 v218, 0xc2700000, v218
	v_max_f32_e32 v219, 0xc2700000, v219
	v_mul_f32_e32 v218, 0xbfb8aa3b, v218
	v_mul_f32_e32 v219, 0xbfb8aa3b, v219
	v_exp_f32_e32 v218, v218
	v_exp_f32_e32 v219, v219
	v_add_f32_e32 v218, 1.0, v218
	v_add_f32_e32 v219, 1.0, v219
	v_rcp_f32_e32 v218, v218
	v_rcp_f32_e32 v219, v219
	s_nop 0
	v_pk_mul_f32 v[82:83], v[82:83], v[218:219]
	v_lshlrev_b32_e32 v242, 16, v153
	v_and_b32_e32 v243, 0xffff0000, v153
	v_max_f32_e32 v242, 0xc2700000, v242
	v_max_f32_e32 v243, 0xc2700000, v243
	v_mul_f32_e32 v242, 0xbfb8aa3b, v242
	v_mul_f32_e32 v243, 0xbfb8aa3b, v243
	v_exp_f32_e32 v242, v242
	v_exp_f32_e32 v243, v243
	v_add_f32_e32 v242, 1.0, v242
	v_add_f32_e32 v243, 1.0, v243
	v_rcp_f32_e32 v242, v242
	v_rcp_f32_e32 v243, v243
	s_nop 0
	v_pk_mul_f32 v[84:85], v[84:85], v[242:243]
	v_cvt_pk_bf16_f32 v86, v86, v87
	v_cvt_pk_bf16_f32 v87, v88, v89
	v_cvt_pk_bf16_f32 v88, v82, v83
	v_cvt_pk_bf16_f32 v89, v84, v85
	global_store_dwordx4 v[226:227], v[86:89], off offset:256
	s_waitcnt vmcnt(15)
	v_lshlrev_b32_e32 v218, 16, v154
	v_and_b32_e32 v219, 0xffff0000, v154
	v_max_f32_e32 v218, 0xc2700000, v218
	v_max_f32_e32 v219, 0xc2700000, v219
	v_mul_f32_e32 v218, 0xbfb8aa3b, v218
	v_mul_f32_e32 v219, 0xbfb8aa3b, v219
	v_exp_f32_e32 v218, v218
	v_exp_f32_e32 v219, v219
	v_add_f32_e32 v218, 1.0, v218
	v_add_f32_e32 v219, 1.0, v219
	v_rcp_f32_e32 v218, v218
	v_rcp_f32_e32 v219, v219
	s_nop 0
	v_pk_mul_f32 v[78:79], v[78:79], v[218:219]
	v_lshlrev_b32_e32 v242, 16, v155
	v_and_b32_e32 v243, 0xffff0000, v155
	v_max_f32_e32 v242, 0xc2700000, v242
	v_max_f32_e32 v243, 0xc2700000, v243
	v_mul_f32_e32 v242, 0xbfb8aa3b, v242
	v_mul_f32_e32 v243, 0xbfb8aa3b, v243
	v_exp_f32_e32 v242, v242
	v_exp_f32_e32 v243, v243
	v_add_f32_e32 v242, 1.0, v242
	v_add_f32_e32 v243, 1.0, v243
	v_rcp_f32_e32 v242, v242
	v_rcp_f32_e32 v243, v243
	s_nop 0
	v_pk_mul_f32 v[80:81], v[80:81], v[242:243]
	v_lshlrev_b32_e32 v218, 16, v156
	v_and_b32_e32 v219, 0xffff0000, v156
	v_max_f32_e32 v218, 0xc2700000, v218
	v_max_f32_e32 v219, 0xc2700000, v219
	v_mul_f32_e32 v218, 0xbfb8aa3b, v218
	v_mul_f32_e32 v219, 0xbfb8aa3b, v219
	v_exp_f32_e32 v218, v218
	v_exp_f32_e32 v219, v219
	v_add_f32_e32 v218, 1.0, v218
	v_add_f32_e32 v219, 1.0, v219
	v_rcp_f32_e32 v218, v218
	v_rcp_f32_e32 v219, v219
	s_nop 0
	v_pk_mul_f32 v[74:75], v[74:75], v[218:219]
	v_lshlrev_b32_e32 v242, 16, v157
	v_and_b32_e32 v243, 0xffff0000, v157
	v_max_f32_e32 v242, 0xc2700000, v242
	v_max_f32_e32 v243, 0xc2700000, v243
	v_mul_f32_e32 v242, 0xbfb8aa3b, v242
	v_mul_f32_e32 v243, 0xbfb8aa3b, v243
	v_exp_f32_e32 v242, v242
	v_exp_f32_e32 v243, v243
	v_add_f32_e32 v242, 1.0, v242
	v_add_f32_e32 v243, 1.0, v243
	v_rcp_f32_e32 v242, v242
	v_rcp_f32_e32 v243, v243
	s_nop 0
	v_pk_mul_f32 v[76:77], v[76:77], v[242:243]
	v_cvt_pk_bf16_f32 v78, v78, v79
	v_cvt_pk_bf16_f32 v79, v80, v81
	v_cvt_pk_bf16_f32 v80, v74, v75
	v_cvt_pk_bf16_f32 v81, v76, v77
	v_lshl_add_u64 v[226:227], v[226:227], 0, s[46:47]
	global_store_dwordx4 v[226:227], v[78:81], off
	s_waitcnt vmcnt(15)
	v_lshlrev_b32_e32 v218, 16, v158
	v_and_b32_e32 v219, 0xffff0000, v158
	v_max_f32_e32 v218, 0xc2700000, v218
	v_max_f32_e32 v219, 0xc2700000, v219
	v_mul_f32_e32 v218, 0xbfb8aa3b, v218
	v_mul_f32_e32 v219, 0xbfb8aa3b, v219
	v_exp_f32_e32 v218, v218
	v_exp_f32_e32 v219, v219
	v_add_f32_e32 v218, 1.0, v218
	v_add_f32_e32 v219, 1.0, v219
	v_rcp_f32_e32 v218, v218
	v_rcp_f32_e32 v219, v219
	s_nop 0
	v_pk_mul_f32 v[70:71], v[70:71], v[218:219]
	v_lshlrev_b32_e32 v242, 16, v159
	v_and_b32_e32 v243, 0xffff0000, v159
	v_max_f32_e32 v242, 0xc2700000, v242
	v_max_f32_e32 v243, 0xc2700000, v243
	v_mul_f32_e32 v242, 0xbfb8aa3b, v242
	v_mul_f32_e32 v243, 0xbfb8aa3b, v243
	v_exp_f32_e32 v242, v242
	v_exp_f32_e32 v243, v243
	v_add_f32_e32 v242, 1.0, v242
	v_add_f32_e32 v243, 1.0, v243
	v_rcp_f32_e32 v242, v242
	v_rcp_f32_e32 v243, v243
	s_nop 0
	v_pk_mul_f32 v[72:73], v[72:73], v[242:243]
	v_lshlrev_b32_e32 v218, 16, v160
	v_and_b32_e32 v219, 0xffff0000, v160
	v_max_f32_e32 v218, 0xc2700000, v218
	v_max_f32_e32 v219, 0xc2700000, v219
	v_mul_f32_e32 v218, 0xbfb8aa3b, v218
	v_mul_f32_e32 v219, 0xbfb8aa3b, v219
	v_exp_f32_e32 v218, v218
	v_exp_f32_e32 v219, v219
	v_add_f32_e32 v218, 1.0, v218
	v_add_f32_e32 v219, 1.0, v219
	v_rcp_f32_e32 v218, v218
	v_rcp_f32_e32 v219, v219
	s_nop 0
	v_pk_mul_f32 v[66:67], v[66:67], v[218:219]
	v_lshlrev_b32_e32 v242, 16, v161
	v_and_b32_e32 v243, 0xffff0000, v161
	v_max_f32_e32 v242, 0xc2700000, v242
	v_max_f32_e32 v243, 0xc2700000, v243
	v_mul_f32_e32 v242, 0xbfb8aa3b, v242
	v_mul_f32_e32 v243, 0xbfb8aa3b, v243
	v_exp_f32_e32 v242, v242
	v_exp_f32_e32 v243, v243
	v_add_f32_e32 v242, 1.0, v242
	v_add_f32_e32 v243, 1.0, v243
	v_rcp_f32_e32 v242, v242
	v_rcp_f32_e32 v243, v243
	s_nop 0
	v_pk_mul_f32 v[68:69], v[68:69], v[242:243]
	v_cvt_pk_bf16_f32 v70, v70, v71
	v_cvt_pk_bf16_f32 v71, v72, v73
	v_cvt_pk_bf16_f32 v72, v66, v67
	v_cvt_pk_bf16_f32 v73, v68, v69
	global_store_dwordx4 v[226:227], v[70:73], off offset:256
	v_lshl_add_u64 v[226:227], v[226:227], 0, s[42:43]
	s_waitcnt vmcnt(15)
; __device__ __forceinline__ unsigned cvt_pk_bf16(float lo, float hi) { unsigned r; asm volatile("v_cvt_pk_bf16_f32 %0, %1, %2" : "=v"(r) : "v"(lo), "v"(hi)); return r; }
; __device__ __forceinline__ float bf_lo(unsigned w) { return __uint_as_float(w << 16); }
; __device__ __forceinline__ float bf_hi(unsigned w) { return __uint_as_float(w & 0xffff0000u); }
; __device__ __forceinline__ float sigm(float x) { return __builtin_amdgcn_rcpf(1.f + __builtin_amdgcn_exp2f(-1.4426950408889634f * x)); }
;     __device__ __forceinline__ void operator()(const f32x4 (&acc)[2][2][4][2], const Unit& u, int wr, int wc, int fr, int fq) const {
;     ...
;                 for (int bj = 0; bj < 2; ++bj) { const int row = row0 + ai * HALF + m * 16, col = col0 + bj * HALF; const u32x4 g4 = gv[m][bj];
;                     const f32x4 a0 = acc[ai][bj][m][0], a1 = acc[ai][bj][m][1];
;                     float f0 = a0[0] * bf_lo(g4.x), f1 = a0[1] * bf_hi(g4.x), f2 = a0[2] * bf_lo(g4.y), f3 = a0[3] * bf_hi(g4.y);
;                     float f4 = a1[0] * bf_lo(g4.z), f5 = a1[1] * bf_hi(g4.z), f6 = a1[2] * bf_lo(g4.w), f7 = a1[3] * bf_hi(g4.w);
;                     if (br > 0) {
;                         const unsigned p0 = (unsigned)q0[m][bj], p1 = (unsigned)(q0[m][bj] >> 32), p2 = (unsigned)q1[m][bj], p3 = (unsigned)(q1[m][bj] >> 32);
;                         f0 += bf_lo(p0); f1 += bf_hi(p0); f2 += bf_lo(p1); f3 += bf_hi(p1); f4 += bf_lo(p2); f5 += bf_hi(p2); f6 += bf_lo(p3); f7 += bf_hi(p3);
;                     }
;                     u32x4 w; w.x = cvt_pk_bf16(f0, f1); w.y = cvt_pk_bf16(f2, f3); w.z = cvt_pk_bf16(f4, f5); w.w = cvt_pk_bf16(f6, f7);
;                     *(u32x4*)(Mg + (size_t)row * DM + col) = w; }
;             asm volatile("" ::: "memory"); }
	v_lshlrev_b32_e32 v218, 16, v186
	v_and_b32_e32 v219, 0xffff0000, v186
	v_max_f32_e32 v218, 0xc2700000, v218
	v_max_f32_e32 v219, 0xc2700000, v219
	v_mul_f32_e32 v218, 0xbfb8aa3b, v218
	v_mul_f32_e32 v219, 0xbfb8aa3b, v219
	v_exp_f32_e32 v218, v218
	v_exp_f32_e32 v219, v219
	v_add_f32_e32 v218, 1.0, v218
	v_add_f32_e32 v219, 1.0, v219
	v_rcp_f32_e32 v218, v218
	v_rcp_f32_e32 v219, v219
	s_nop 0
	v_pk_mul_f32 v[62:63], v[62:63], v[218:219]
	v_lshlrev_b32_e32 v242, 16, v187
	v_and_b32_e32 v243, 0xffff0000, v187
	v_max_f32_e32 v242, 0xc2700000, v242
	v_max_f32_e32 v243, 0xc2700000, v243
	v_mul_f32_e32 v242, 0xbfb8aa3b, v242
	v_mul_f32_e32 v243, 0xbfb8aa3b, v243
	v_exp_f32_e32 v242, v242
	v_exp_f32_e32 v243, v243
	v_add_f32_e32 v242, 1.0, v242
	v_add_f32_e32 v243, 1.0, v243
	v_rcp_f32_e32 v242, v242
	v_rcp_f32_e32 v243, v243
	s_nop 0
	v_pk_mul_f32 v[64:65], v[64:65], v[242:243]
	v_lshlrev_b32_e32 v218, 16, v188
	v_and_b32_e32 v219, 0xffff0000, v188
	v_max_f32_e32 v218, 0xc2700000, v218
	v_max_f32_e32 v219, 0xc2700000, v219
	v_mul_f32_e32 v218, 0xbfb8aa3b, v218
	v_mul_f32_e32 v219, 0xbfb8aa3b, v219
	v_exp_f32_e32 v218, v218
	v_exp_f32_e32 v219, v219
	v_add_f32_e32 v218, 1.0, v218
	v_add_f32_e32 v219, 1.0, v219
	v_rcp_f32_e32 v218, v218
	v_rcp_f32_e32 v219, v219
	s_nop 0
	v_pk_mul_f32 v[58:59], v[58:59], v[218:219]
	v_lshlrev_b32_e32 v242, 16, v189
	v_and_b32_e32 v243, 0xffff0000, v189
	v_max_f32_e32 v242, 0xc2700000, v242
	v_max_f32_e32 v243, 0xc2700000, v243
	v_mul_f32_e32 v242, 0xbfb8aa3b, v242
	v_mul_f32_e32 v243, 0xbfb8aa3b, v243
	v_exp_f32_e32 v242, v242
	v_exp_f32_e32 v243, v243
	v_add_f32_e32 v242, 1.0, v242
	v_add_f32_e32 v243, 1.0, v243
	v_rcp_f32_e32 v242, v242
	v_rcp_f32_e32 v243, v243
	s_nop 0
	v_pk_mul_f32 v[60:61], v[60:61], v[242:243]
	v_cvt_pk_bf16_f32 v62, v62, v63
	v_cvt_pk_bf16_f32 v63, v64, v65
	v_cvt_pk_bf16_f32 v64, v58, v59
	v_cvt_pk_bf16_f32 v65, v60, v61
	global_store_dwordx4 v[226:227], v[62:65], off
	s_waitcnt vmcnt(15)
	v_lshlrev_b32_e32 v218, 16, v190
	v_and_b32_e32 v219, 0xffff0000, v190
	v_max_f32_e32 v218, 0xc2700000, v218
	v_max_f32_e32 v219, 0xc2700000, v219
	v_mul_f32_e32 v218, 0xbfb8aa3b, v218
	v_mul_f32_e32 v219, 0xbfb8aa3b, v219
	v_exp_f32_e32 v218, v218
	v_exp_f32_e32 v219, v219
	v_add_f32_e32 v218, 1.0, v218
	v_add_f32_e32 v219, 1.0, v219
	v_rcp_f32_e32 v218, v218
	v_rcp_f32_e32 v219, v219
	s_nop 0
	v_pk_mul_f32 v[54:55], v[54:55], v[218:219]
	v_lshlrev_b32_e32 v242, 16, v191
	v_and_b32_e32 v243, 0xffff0000, v191
	v_max_f32_e32 v242, 0xc2700000, v242
	v_max_f32_e32 v243, 0xc2700000, v243
	v_mul_f32_e32 v242, 0xbfb8aa3b, v242
	v_mul_f32_e32 v243, 0xbfb8aa3b, v243
	v_exp_f32_e32 v242, v242
	v_exp_f32_e32 v243, v243
	v_add_f32_e32 v242, 1.0, v242
	v_add_f32_e32 v243, 1.0, v243
	v_rcp_f32_e32 v242, v242
	v_rcp_f32_e32 v243, v243
	s_nop 0
	v_pk_mul_f32 v[56:57], v[56:57], v[242:243]
	v_lshlrev_b32_e32 v218, 16, v192
	v_and_b32_e32 v219, 0xffff0000, v192
	v_max_f32_e32 v218, 0xc2700000, v218
	v_max_f32_e32 v219, 0xc2700000, v219
	v_mul_f32_e32 v218, 0xbfb8aa3b, v218
	v_mul_f32_e32 v219, 0xbfb8aa3b, v219
	v_exp_f32_e32 v218, v218
	v_exp_f32_e32 v219, v219
	v_add_f32_e32 v218, 1.0, v218
	v_add_f32_e32 v219, 1.0, v219
	v_rcp_f32_e32 v218, v218
	v_rcp_f32_e32 v219, v219
	s_nop 0
	v_pk_mul_f32 v[50:51], v[50:51], v[218:219]
	v_lshlrev_b32_e32 v242, 16, v193
	v_and_b32_e32 v243, 0xffff0000, v193
	v_max_f32_e32 v242, 0xc2700000, v242
	v_max_f32_e32 v243, 0xc2700000, v243
	v_mul_f32_e32 v242, 0xbfb8aa3b, v242
	v_mul_f32_e32 v243, 0xbfb8aa3b, v243
	v_exp_f32_e32 v242, v242
	v_exp_f32_e32 v243, v243
	v_add_f32_e32 v242, 1.0, v242
	v_add_f32_e32 v243, 1.0, v243
	v_rcp_f32_e32 v242, v242
	v_rcp_f32_e32 v243, v243
	s_nop 0
	v_pk_mul_f32 v[52:53], v[52:53], v[242:243]
	v_cvt_pk_bf16_f32 v54, v54, v55
	v_cvt_pk_bf16_f32 v55, v56, v57
	v_cvt_pk_bf16_f32 v56, v50, v51
	v_cvt_pk_bf16_f32 v57, v52, v53
	global_store_dwordx4 v[226:227], v[54:57], off offset:256
	s_waitcnt vmcnt(15)
	v_lshlrev_b32_e32 v218, 16, v194
	v_and_b32_e32 v219, 0xffff0000, v194
	v_max_f32_e32 v218, 0xc2700000, v218
	v_max_f32_e32 v219, 0xc2700000, v219
	v_mul_f32_e32 v218, 0xbfb8aa3b, v218
	v_mul_f32_e32 v219, 0xbfb8aa3b, v219
	v_exp_f32_e32 v218, v218
	v_exp_f32_e32 v219, v219
	v_add_f32_e32 v218, 1.0, v218
	v_add_f32_e32 v219, 1.0, v219
	v_rcp_f32_e32 v218, v218
	v_rcp_f32_e32 v219, v219
	s_nop 0
	v_pk_mul_f32 v[46:47], v[46:47], v[218:219]
	v_lshlrev_b32_e32 v242, 16, v195
	v_and_b32_e32 v243, 0xffff0000, v195
	v_max_f32_e32 v242, 0xc2700000, v242
	v_max_f32_e32 v243, 0xc2700000, v243
	v_mul_f32_e32 v242, 0xbfb8aa3b, v242
	v_mul_f32_e32 v243, 0xbfb8aa3b, v243
	v_exp_f32_e32 v242, v242
	v_exp_f32_e32 v243, v243
	v_add_f32_e32 v242, 1.0, v242
	v_add_f32_e32 v243, 1.0, v243
	v_rcp_f32_e32 v242, v242
	v_rcp_f32_e32 v243, v243
	s_nop 0
	v_pk_mul_f32 v[48:49], v[48:49], v[242:243]
	v_lshlrev_b32_e32 v218, 16, v196
	v_and_b32_e32 v219, 0xffff0000, v196
	v_max_f32_e32 v218, 0xc2700000, v218
	v_max_f32_e32 v219, 0xc2700000, v219
	v_mul_f32_e32 v218, 0xbfb8aa3b, v218
	v_mul_f32_e32 v219, 0xbfb8aa3b, v219
	v_exp_f32_e32 v218, v218
	v_exp_f32_e32 v219, v219
	v_add_f32_e32 v218, 1.0, v218
	v_add_f32_e32 v219, 1.0, v219
	v_rcp_f32_e32 v218, v218
	v_rcp_f32_e32 v219, v219
	s_nop 0
	v_pk_mul_f32 v[42:43], v[42:43], v[218:219]
	v_lshlrev_b32_e32 v242, 16, v197
	v_and_b32_e32 v243, 0xffff0000, v197
	v_max_f32_e32 v242, 0xc2700000, v242
	v_max_f32_e32 v243, 0xc2700000, v243
	v_mul_f32_e32 v242, 0xbfb8aa3b, v242
	v_mul_f32_e32 v243, 0xbfb8aa3b, v243
	v_exp_f32_e32 v242, v242
	v_exp_f32_e32 v243, v243
	v_add_f32_e32 v242, 1.0, v242
	v_add_f32_e32 v243, 1.0, v243
	v_rcp_f32_e32 v242, v242
	v_rcp_f32_e32 v243, v243
	s_nop 0
	v_pk_mul_f32 v[44:45], v[44:45], v[242:243]
	v_cvt_pk_bf16_f32 v46, v46, v47
	v_cvt_pk_bf16_f32 v47, v48, v49
	v_cvt_pk_bf16_f32 v48, v42, v43
	v_cvt_pk_bf16_f32 v49, v44, v45
	v_lshl_add_u64 v[226:227], v[226:227], 0, s[46:47]
	global_store_dwordx4 v[226:227], v[46:49], off
	s_waitcnt vmcnt(15)
; __device__ __forceinline__ unsigned cvt_pk_bf16(float lo, float hi) { unsigned r; asm volatile("v_cvt_pk_bf16_f32 %0, %1, %2" : "=v"(r) : "v"(lo), "v"(hi)); return r; }
; __device__ __forceinline__ float bf_lo(unsigned w) { return __uint_as_float(w << 16); }
; __device__ __forceinline__ float bf_hi(unsigned w) { return __uint_as_float(w & 0xffff0000u); }
; __device__ __forceinline__ float sigm(float x) { return __builtin_amdgcn_rcpf(1.f + __builtin_amdgcn_exp2f(-1.4426950408889634f * x)); }
;     __device__ __forceinline__ void operator()(const f32x4 (&acc)[2][2][4][2], const Unit& u, int wr, int wc, int fr, int fq) const {
;     ...
;                 for (int bj = 0; bj < 2; ++bj) { const int row = row0 + ai * HALF + m * 16, col = col0 + bj * HALF; const u32x4 g4 = gv[m][bj];
;                     const f32x4 a0 = acc[ai][bj][m][0], a1 = acc[ai][bj][m][1];
;                     float f0 = a0[0] * bf_lo(g4.x), f1 = a0[1] * bf_hi(g4.x), f2 = a0[2] * bf_lo(g4.y), f3 = a0[3] * bf_hi(g4.y);
;                     float f4 = a1[0] * bf_lo(g4.z), f5 = a1[1] * bf_hi(g4.z), f6 = a1[2] * bf_lo(g4.w), f7 = a1[3] * bf_hi(g4.w);
;                     if (br > 0) {
;                         const unsigned p0 = (unsigned)q0[m][bj], p1 = (unsigned)(q0[m][bj] >> 32), p2 = (unsigned)q1[m][bj], p3 = (unsigned)(q1[m][bj] >> 32);
;                         f0 += bf_lo(p0); f1 += bf_hi(p0); f2 += bf_lo(p1); f3 += bf_hi(p1); f4 += bf_lo(p2); f5 += bf_hi(p2); f6 += bf_lo(p3); f7 += bf_hi(p3);
;                     }
;                     u32x4 w; w.x = cvt_pk_bf16(f0, f1); w.y = cvt_pk_bf16(f2, f3); w.z = cvt_pk_bf16(f4, f5); w.w = cvt_pk_bf16(f6, f7);
;                     *(u32x4*)(Mg + (size_t)row * DM + col) = w; }
;             asm volatile("" ::: "memory"); }
	v_lshlrev_b32_e32 v218, 16, v198
	v_and_b32_e32 v219, 0xffff0000, v198
	v_max_f32_e32 v218, 0xc2700000, v218
	v_max_f32_e32 v219, 0xc2700000, v219
	v_mul_f32_e32 v218, 0xbfb8aa3b, v218
	v_mul_f32_e32 v219, 0xbfb8aa3b, v219
	v_exp_f32_e32 v218, v218
	v_exp_f32_e32 v219, v219
	v_add_f32_e32 v218, 1.0, v218
	v_add_f32_e32 v219, 1.0, v219
	v_rcp_f32_e32 v218, v218
	v_rcp_f32_e32 v219, v219
	s_nop 0
	v_pk_mul_f32 v[38:39], v[38:39], v[218:219]
	v_lshlrev_b32_e32 v242, 16, v199
	v_and_b32_e32 v243, 0xffff0000, v199
	v_max_f32_e32 v242, 0xc2700000, v242
	v_max_f32_e32 v243, 0xc2700000, v243
	v_mul_f32_e32 v242, 0xbfb8aa3b, v242
	v_mul_f32_e32 v243, 0xbfb8aa3b, v243
	v_exp_f32_e32 v242, v242
	v_exp_f32_e32 v243, v243
	v_add_f32_e32 v242, 1.0, v242
	v_add_f32_e32 v243, 1.0, v243
	v_rcp_f32_e32 v242, v242
	v_rcp_f32_e32 v243, v243
	s_nop 0
	v_pk_mul_f32 v[40:41], v[40:41], v[242:243]
	v_lshlrev_b32_e32 v218, 16, v200
	v_and_b32_e32 v219, 0xffff0000, v200
	v_max_f32_e32 v218, 0xc2700000, v218
	v_max_f32_e32 v219, 0xc2700000, v219
	v_mul_f32_e32 v218, 0xbfb8aa3b, v218
	v_mul_f32_e32 v219, 0xbfb8aa3b, v219
	v_exp_f32_e32 v218, v218
	v_exp_f32_e32 v219, v219
	v_add_f32_e32 v218, 1.0, v218
	v_add_f32_e32 v219, 1.0, v219
	v_rcp_f32_e32 v218, v218
	v_rcp_f32_e32 v219, v219
	s_nop 0
	v_pk_mul_f32 v[34:35], v[34:35], v[218:219]
	v_lshlrev_b32_e32 v242, 16, v201
	v_and_b32_e32 v243, 0xffff0000, v201
	v_max_f32_e32 v242, 0xc2700000, v242
	v_max_f32_e32 v243, 0xc2700000, v243
	v_mul_f32_e32 v242, 0xbfb8aa3b, v242
	v_mul_f32_e32 v243, 0xbfb8aa3b, v243
	v_exp_f32_e32 v242, v242
	v_exp_f32_e32 v243, v243
	v_add_f32_e32 v242, 1.0, v242
	v_add_f32_e32 v243, 1.0, v243
	v_rcp_f32_e32 v242, v242
	v_rcp_f32_e32 v243, v243
	s_nop 0
	v_pk_mul_f32 v[36:37], v[36:37], v[242:243]
	v_cvt_pk_bf16_f32 v38, v38, v39
	v_cvt_pk_bf16_f32 v39, v40, v41
	v_cvt_pk_bf16_f32 v40, v34, v35
	v_cvt_pk_bf16_f32 v41, v36, v37
	global_store_dwordx4 v[226:227], v[38:41], off offset:256
	s_waitcnt vmcnt(15)
	v_lshlrev_b32_e32 v218, 16, v202
	v_and_b32_e32 v219, 0xffff0000, v202
	v_max_f32_e32 v218, 0xc2700000, v218
	v_max_f32_e32 v219, 0xc2700000, v219
	v_mul_f32_e32 v218, 0xbfb8aa3b, v218
	v_mul_f32_e32 v219, 0xbfb8aa3b, v219
	v_exp_f32_e32 v218, v218
	v_exp_f32_e32 v219, v219
	v_add_f32_e32 v218, 1.0, v218
	v_add_f32_e32 v219, 1.0, v219
	v_rcp_f32_e32 v218, v218
	v_rcp_f32_e32 v219, v219
	s_nop 0
	v_pk_mul_f32 v[30:31], v[30:31], v[218:219]
	v_lshlrev_b32_e32 v242, 16, v203
	v_and_b32_e32 v243, 0xffff0000, v203
	v_max_f32_e32 v242, 0xc2700000, v242
	v_max_f32_e32 v243, 0xc2700000, v243
	v_mul_f32_e32 v242, 0xbfb8aa3b, v242
	v_mul_f32_e32 v243, 0xbfb8aa3b, v243
	v_exp_f32_e32 v242, v242
	v_exp_f32_e32 v243, v243
	v_add_f32_e32 v242, 1.0, v242
	v_add_f32_e32 v243, 1.0, v243
	v_rcp_f32_e32 v242, v242
	v_rcp_f32_e32 v243, v243
	s_nop 0
	v_pk_mul_f32 v[32:33], v[32:33], v[242:243]
	v_lshlrev_b32_e32 v218, 16, v204
	v_and_b32_e32 v219, 0xffff0000, v204
	v_max_f32_e32 v218, 0xc2700000, v218
	v_max_f32_e32 v219, 0xc2700000, v219
	v_mul_f32_e32 v218, 0xbfb8aa3b, v218
	v_mul_f32_e32 v219, 0xbfb8aa3b, v219
	v_exp_f32_e32 v218, v218
	v_exp_f32_e32 v219, v219
	v_add_f32_e32 v218, 1.0, v218
	v_add_f32_e32 v219, 1.0, v219
	v_rcp_f32_e32 v218, v218
	v_rcp_f32_e32 v219, v219
	s_nop 0
	v_pk_mul_f32 v[26:27], v[26:27], v[218:219]
	v_lshlrev_b32_e32 v242, 16, v205
	v_and_b32_e32 v243, 0xffff0000, v205
	v_max_f32_e32 v242, 0xc2700000, v242
	v_max_f32_e32 v243, 0xc2700000, v243
	v_mul_f32_e32 v242, 0xbfb8aa3b, v242
	v_mul_f32_e32 v243, 0xbfb8aa3b, v243
	v_exp_f32_e32 v242, v242
	v_exp_f32_e32 v243, v243
	v_add_f32_e32 v242, 1.0, v242
	v_add_f32_e32 v243, 1.0, v243
	v_rcp_f32_e32 v242, v242
	v_rcp_f32_e32 v243, v243
	s_nop 0
	v_pk_mul_f32 v[28:29], v[28:29], v[242:243]
	v_cvt_pk_bf16_f32 v30, v30, v31
	v_cvt_pk_bf16_f32 v31, v32, v33
	v_cvt_pk_bf16_f32 v32, v26, v27
	v_cvt_pk_bf16_f32 v33, v28, v29
	v_lshl_add_u64 v[226:227], v[226:227], 0, s[46:47]
	global_store_dwordx4 v[226:227], v[30:33], off
	s_waitcnt vmcnt(15)
; __device__ __forceinline__ unsigned cvt_pk_bf16(float lo, float hi) { unsigned r; asm volatile("v_cvt_pk_bf16_f32 %0, %1, %2" : "=v"(r) : "v"(lo), "v"(hi)); return r; }
; __device__ __forceinline__ float bf_lo(unsigned w) { return __uint_as_float(w << 16); }
; __device__ __forceinline__ float bf_hi(unsigned w) { return __uint_as_float(w & 0xffff0000u); }
; __device__ __forceinline__ float sigm(float x) { return __builtin_amdgcn_rcpf(1.f + __builtin_amdgcn_exp2f(-1.4426950408889634f * x)); }
;     __device__ __forceinline__ void operator()(const f32x4 (&acc)[2][2][4][2], const Unit& u, int wr, int wc, int fr, int fq) const {
;     ...
;                 for (int bj = 0; bj < 2; ++bj) { const int row = row0 + ai * HALF + m * 16, col = col0 + bj * HALF; const u32x4 g4 = gv[m][bj];
;                     const f32x4 a0 = acc[ai][bj][m][0], a1 = acc[ai][bj][m][1];
;                     float f0 = a0[0] * bf_lo(g4.x), f1 = a0[1] * bf_hi(g4.x), f2 = a0[2] * bf_lo(g4.y), f3 = a0[3] * bf_hi(g4.y);
;                     float f4 = a1[0] * bf_lo(g4.z), f5 = a1[1] * bf_hi(g4.z), f6 = a1[2] * bf_lo(g4.w), f7 = a1[3] * bf_hi(g4.w);
;                     if (br > 0) {
;                         const unsigned p0 = (unsigned)q0[m][bj], p1 = (unsigned)(q0[m][bj] >> 32), p2 = (unsigned)q1[m][bj], p3 = (unsigned)(q1[m][bj] >> 32);
;                         f0 += bf_lo(p0); f1 += bf_hi(p0); f2 += bf_lo(p1); f3 += bf_hi(p1); f4 += bf_lo(p2); f5 += bf_hi(p2); f6 += bf_lo(p3); f7 += bf_hi(p3);
;                     }
;                     u32x4 w; w.x = cvt_pk_bf16(f0, f1); w.y = cvt_pk_bf16(f2, f3); w.z = cvt_pk_bf16(f4, f5); w.w = cvt_pk_bf16(f6, f7);
;                     *(u32x4*)(Mg + (size_t)row * DM + col) = w; }
;             asm volatile("" ::: "memory"); }
	v_lshlrev_b32_e32 v218, 16, v206
	v_and_b32_e32 v219, 0xffff0000, v206
	v_max_f32_e32 v218, 0xc2700000, v218
	v_max_f32_e32 v219, 0xc2700000, v219
	v_mul_f32_e32 v218, 0xbfb8aa3b, v218
	v_mul_f32_e32 v219, 0xbfb8aa3b, v219
	v_exp_f32_e32 v218, v218
	v_exp_f32_e32 v219, v219
	v_add_f32_e32 v218, 1.0, v218
	v_add_f32_e32 v219, 1.0, v219
	v_rcp_f32_e32 v218, v218
	v_rcp_f32_e32 v219, v219
	s_nop 0
	v_pk_mul_f32 v[22:23], v[22:23], v[218:219]
	v_lshlrev_b32_e32 v242, 16, v207
	v_and_b32_e32 v243, 0xffff0000, v207
	v_max_f32_e32 v242, 0xc2700000, v242
	v_max_f32_e32 v243, 0xc2700000, v243
	v_mul_f32_e32 v242, 0xbfb8aa3b, v242
	v_mul_f32_e32 v243, 0xbfb8aa3b, v243
	v_exp_f32_e32 v242, v242
	v_exp_f32_e32 v243, v243
	v_add_f32_e32 v242, 1.0, v242
	v_add_f32_e32 v243, 1.0, v243
	v_rcp_f32_e32 v242, v242
	v_rcp_f32_e32 v243, v243
	s_nop 0
	v_pk_mul_f32 v[24:25], v[24:25], v[242:243]
	v_lshlrev_b32_e32 v218, 16, v208
	v_and_b32_e32 v219, 0xffff0000, v208
	v_max_f32_e32 v218, 0xc2700000, v218
	v_max_f32_e32 v219, 0xc2700000, v219
	v_mul_f32_e32 v218, 0xbfb8aa3b, v218
	v_mul_f32_e32 v219, 0xbfb8aa3b, v219
	v_exp_f32_e32 v218, v218
	v_exp_f32_e32 v219, v219
	v_add_f32_e32 v218, 1.0, v218
	v_add_f32_e32 v219, 1.0, v219
	v_rcp_f32_e32 v218, v218
	v_rcp_f32_e32 v219, v219
	s_nop 0
	v_pk_mul_f32 v[18:19], v[18:19], v[218:219]
	v_lshlrev_b32_e32 v242, 16, v209
	v_and_b32_e32 v243, 0xffff0000, v209
	v_max_f32_e32 v242, 0xc2700000, v242
	v_max_f32_e32 v243, 0xc2700000, v243
	v_mul_f32_e32 v242, 0xbfb8aa3b, v242
	v_mul_f32_e32 v243, 0xbfb8aa3b, v243
	v_exp_f32_e32 v242, v242
	v_exp_f32_e32 v243, v243
	v_add_f32_e32 v242, 1.0, v242
	v_add_f32_e32 v243, 1.0, v243
	v_rcp_f32_e32 v242, v242
	v_rcp_f32_e32 v243, v243
	s_nop 0
	v_pk_mul_f32 v[20:21], v[20:21], v[242:243]
	v_cvt_pk_bf16_f32 v22, v22, v23
	v_cvt_pk_bf16_f32 v23, v24, v25
	v_cvt_pk_bf16_f32 v24, v18, v19
	v_cvt_pk_bf16_f32 v25, v20, v21
	global_store_dwordx4 v[226:227], v[22:25], off offset:256
	s_waitcnt vmcnt(15)
	v_lshlrev_b32_e32 v218, 16, v210
	v_and_b32_e32 v219, 0xffff0000, v210
	v_max_f32_e32 v218, 0xc2700000, v218
	v_max_f32_e32 v219, 0xc2700000, v219
	v_mul_f32_e32 v218, 0xbfb8aa3b, v218
	v_mul_f32_e32 v219, 0xbfb8aa3b, v219
	v_exp_f32_e32 v218, v218
	v_exp_f32_e32 v219, v219
	v_add_f32_e32 v218, 1.0, v218
	v_add_f32_e32 v219, 1.0, v219
	v_rcp_f32_e32 v218, v218
	v_rcp_f32_e32 v219, v219
	s_nop 0
	v_pk_mul_f32 v[14:15], v[14:15], v[218:219]
	v_lshlrev_b32_e32 v242, 16, v211
	v_and_b32_e32 v243, 0xffff0000, v211
	v_max_f32_e32 v242, 0xc2700000, v242
	v_max_f32_e32 v243, 0xc2700000, v243
	v_mul_f32_e32 v242, 0xbfb8aa3b, v242
	v_mul_f32_e32 v243, 0xbfb8aa3b, v243
	v_exp_f32_e32 v242, v242
	v_exp_f32_e32 v243, v243
	v_add_f32_e32 v242, 1.0, v242
	v_add_f32_e32 v243, 1.0, v243
	v_rcp_f32_e32 v242, v242
	v_rcp_f32_e32 v243, v243
	s_nop 0
	v_pk_mul_f32 v[16:17], v[16:17], v[242:243]
	v_lshlrev_b32_e32 v218, 16, v212
	v_and_b32_e32 v219, 0xffff0000, v212
	v_max_f32_e32 v218, 0xc2700000, v218
	v_max_f32_e32 v219, 0xc2700000, v219
	v_mul_f32_e32 v218, 0xbfb8aa3b, v218
	v_mul_f32_e32 v219, 0xbfb8aa3b, v219
	v_exp_f32_e32 v218, v218
	v_exp_f32_e32 v219, v219
	v_add_f32_e32 v218, 1.0, v218
	v_add_f32_e32 v219, 1.0, v219
	v_rcp_f32_e32 v218, v218
	v_rcp_f32_e32 v219, v219
	s_nop 0
	v_pk_mul_f32 v[10:11], v[10:11], v[218:219]
	v_lshlrev_b32_e32 v242, 16, v213
	v_and_b32_e32 v243, 0xffff0000, v213
	v_max_f32_e32 v242, 0xc2700000, v242
	v_max_f32_e32 v243, 0xc2700000, v243
	v_mul_f32_e32 v242, 0xbfb8aa3b, v242
	v_mul_f32_e32 v243, 0xbfb8aa3b, v243
	v_exp_f32_e32 v242, v242
	v_exp_f32_e32 v243, v243
	v_add_f32_e32 v242, 1.0, v242
	v_add_f32_e32 v243, 1.0, v243
	v_rcp_f32_e32 v242, v242
	v_rcp_f32_e32 v243, v243
	s_nop 0
	v_pk_mul_f32 v[12:13], v[12:13], v[242:243]
	v_cvt_pk_bf16_f32 v14, v14, v15
	v_cvt_pk_bf16_f32 v15, v16, v17
	v_cvt_pk_bf16_f32 v16, v10, v11
	v_cvt_pk_bf16_f32 v17, v12, v13
	v_lshl_add_u64 v[226:227], v[226:227], 0, s[46:47]
	global_store_dwordx4 v[226:227], v[14:17], off
	s_waitcnt vmcnt(15)
	v_lshlrev_b32_e32 v218, 16, v214
	v_and_b32_e32 v219, 0xffff0000, v214
	v_max_f32_e32 v218, 0xc2700000, v218
	v_max_f32_e32 v219, 0xc2700000, v219
	v_mul_f32_e32 v218, 0xbfb8aa3b, v218
	v_mul_f32_e32 v219, 0xbfb8aa3b, v219
	v_exp_f32_e32 v218, v218
	v_exp_f32_e32 v219, v219
	v_add_f32_e32 v218, 1.0, v218
	v_add_f32_e32 v219, 1.0, v219
	v_rcp_f32_e32 v218, v218
	v_rcp_f32_e32 v219, v219
	s_nop 0
	v_pk_mul_f32 v[6:7], v[6:7], v[218:219]
	v_lshlrev_b32_e32 v242, 16, v215
	v_and_b32_e32 v243, 0xffff0000, v215
	v_max_f32_e32 v242, 0xc2700000, v242
	v_max_f32_e32 v243, 0xc2700000, v243
	v_mul_f32_e32 v242, 0xbfb8aa3b, v242
	v_mul_f32_e32 v243, 0xbfb8aa3b, v243
	v_exp_f32_e32 v242, v242
	v_exp_f32_e32 v243, v243
	v_add_f32_e32 v242, 1.0, v242
	v_add_f32_e32 v243, 1.0, v243
	v_rcp_f32_e32 v242, v242
	v_rcp_f32_e32 v243, v243
	s_nop 0
	v_pk_mul_f32 v[8:9], v[8:9], v[242:243]
	v_lshlrev_b32_e32 v218, 16, v216
	v_and_b32_e32 v219, 0xffff0000, v216
	v_max_f32_e32 v218, 0xc2700000, v218
	v_max_f32_e32 v219, 0xc2700000, v219
	v_mul_f32_e32 v218, 0xbfb8aa3b, v218
	v_mul_f32_e32 v219, 0xbfb8aa3b, v219
	v_exp_f32_e32 v218, v218
	v_exp_f32_e32 v219, v219
	v_add_f32_e32 v218, 1.0, v218
	v_add_f32_e32 v219, 1.0, v219
	v_rcp_f32_e32 v218, v218
	v_rcp_f32_e32 v219, v219
	s_nop 0
	v_pk_mul_f32 v[2:3], v[2:3], v[218:219]
	v_lshlrev_b32_e32 v242, 16, v217
	v_and_b32_e32 v243, 0xffff0000, v217
	v_max_f32_e32 v242, 0xc2700000, v242
	v_max_f32_e32 v243, 0xc2700000, v243
	v_mul_f32_e32 v242, 0xbfb8aa3b, v242
	v_mul_f32_e32 v243, 0xbfb8aa3b, v243
	v_exp_f32_e32 v242, v242
	v_exp_f32_e32 v243, v243
	v_add_f32_e32 v242, 1.0, v242
	v_add_f32_e32 v243, 1.0, v243
	v_rcp_f32_e32 v242, v242
	v_rcp_f32_e32 v243, v243
	s_nop 0
	v_pk_mul_f32 v[4:5], v[4:5], v[242:243]
	v_cvt_pk_bf16_f32 v6, v6, v7
	v_cvt_pk_bf16_f32 v7, v8, v9
	v_cvt_pk_bf16_f32 v8, v2, v3
	v_cvt_pk_bf16_f32 v9, v4, v5
	global_store_dwordx4 v[226:227], v[6:9], off offset:256

; __device__ __forceinline__ unsigned cvt_pk_bf16(float lo, float hi) { unsigned r; asm volatile("v_cvt_pk_bf16_f32 %0, %1, %2" : "=v"(r) : "v"(lo), "v"(hi)); return r; }
; __device__ __forceinline__ float sigm(float x) { return __builtin_amdgcn_rcpf(1.f + __builtin_amdgcn_exp2f(-1.4426950408889634f * x)); }
;     __device__ __forceinline__ void operator()(const f32x4 (&acc)[2][2][4][2], const Unit& u, int wr, int wc, int fr, int fq) const {
;     ...
;             const bool sg = u.pn >= 15;
;             bf16_t* base = sg ? G : P; const int ldc = sg ? NGATE : PP; const int colt = sg ? (u.pn - 15) * 256 : u.pn * 256;
; #pragma unroll
;             for (int ai = 0; ai < 2; ++ai)
; #pragma unroll
;                 for (int m = 0; m < 4; ++m) { bf16_t* rowp = base + (size_t)(row0 + ai * HALF + m * 16) * ldc + colt + cl0;
; #pragma unroll
;                     for (int bj = 0; bj < 2; ++bj) { f32x4 v0 = acc[ai][bj][m][0], v1 = acc[ai][bj][m][1];
;                         if (sg) { v0 = (f32x4){sigm(v0[0]), sigm(v0[1]), sigm(v0[2]), sigm(v0[3])}; v1 = (f32x4){sigm(v1[0]), sigm(v1[1]), sigm(v1[2]), sigm(v1[3])}; }
;                         u32x4 w; w.x = cvt_pk_bf16(v0[0], v0[1]); w.y = cvt_pk_bf16(v0[2], v0[3]); w.z = cvt_pk_bf16(v1[0], v1[1]); w.w = cvt_pk_bf16(v1[2], v1[3]);
;                         *(u32x4*)(rowp + bj * HALF) = w; }
;                     asm volatile("" ::: "memory"); }
.LBB0_1192:
	s_cmp_gt_i32 s42, 14
	s_cselect_b64 s[44:45], -1, 0
	s_cmp_lt_i32 s42, 15
	v_mov_b32_e32 v153, v126
	v_mov_b32_e32 v154, v127
	v_mov_b32_e32 v155, v128
	v_mov_b32_e32 v156, v129
	v_mov_b32_e32 v157, v122
	v_mov_b32_e32 v158, v123
	v_mov_b32_e32 v159, v124
	v_mov_b32_e32 v160, v125
	s_branch .LBB0_1194
	v_mul_f32_e32 v143, 0xbfb8aa3b, v126
	v_exp_f32_e32 v143, v143
	v_mul_f32_e32 v144, 0xbfb8aa3b, v127
	v_exp_f32_e32 v144, v144
	v_mul_f32_e32 v145, 0xbfb8aa3b, v129
	v_add_f32_e32 v143, 1.0, v143
	v_rcp_f32_e32 v153, v143
	v_mul_f32_e32 v143, 0xbfb8aa3b, v128
	v_exp_f32_e32 v143, v143
	v_exp_f32_e32 v145, v145
	v_add_f32_e32 v144, 1.0, v144
	v_rcp_f32_e32 v154, v144
	v_add_f32_e32 v143, 1.0, v143
	v_mul_f32_e32 v144, 0xbfb8aa3b, v122
	v_rcp_f32_e32 v155, v143
	v_add_f32_e32 v143, 1.0, v145
	v_exp_f32_e32 v144, v144
	v_mul_f32_e32 v145, 0xbfb8aa3b, v123
	v_exp_f32_e32 v145, v145
	v_rcp_f32_e32 v156, v143
	v_add_f32_e32 v143, 1.0, v144
	v_mul_f32_e32 v144, 0xbfb8aa3b, v124
	v_rcp_f32_e32 v157, v143
	v_add_f32_e32 v143, 1.0, v145
	v_exp_f32_e32 v144, v144
	v_mul_f32_e32 v145, 0xbfb8aa3b, v125
	v_exp_f32_e32 v145, v145
	v_rcp_f32_e32 v158, v143
	v_add_f32_e32 v143, 1.0, v144
	v_rcp_f32_e32 v159, v143
	v_add_f32_e32 v143, 1.0, v145
	v_rcp_f32_e32 v160, v143
.LBB0_1194:
	s_and_b64 s[8:9], s[44:45], exec
	s_movk_i32 s8, 0xb00
	s_cselect_b32 s27, 0x1800, s8
	s_mov_b32 s8, 0x13200000
	s_cselect_b32 s8, s8, 0xba00000
	s_add_u32 s37, s10, s8
	s_addc_u32 s46, s11, 0
	s_lshl_b32 s47, s42, 8
	s_add_i32 s48, s47, 0xfffff100
	s_and_b64 s[8:9], s[44:45], exec
	s_cselect_b32 s8, s48, s47
	s_ashr_i32 s9, s8, 31
	s_lshl_b64 s[8:9], s[8:9], 1
	s_add_u32 s8, s37, s8
	s_addc_u32 s9, s46, s9
	v_ashrrev_i32_e32 v143, 31, v142
	v_lshl_add_u64 v[144:145], v[142:143], 1, s[8:9]
	v_mad_i64_i32 v[146:147], s[8:9], s27, v152, 0
	v_lshl_add_u64 v[146:147], v[146:147], 1, v[144:145]
	v_cvt_pk_bf16_f32 v154, v153, v154
	v_cvt_pk_bf16_f32 v155, v155, v156
	v_cvt_pk_bf16_f32 v156, v157, v158
	v_cvt_pk_bf16_f32 v157, v159, v160
	v_cndmask_b32_e64 v143, 0, 1, s[44:45]
	global_store_dwordx4 v[146:147], v[154:157], off
	v_cmp_ne_u32_e64 s[8:9], 1, v143
	s_andn2_b64 vcc, exec, s[44:45]
	v_mov_b32_e32 v143, v118
	v_mov_b32_e32 v153, v119
	v_mov_b32_e32 v154, v120
	v_mov_b32_e32 v155, v121
	v_mov_b32_e32 v156, v110
	v_mov_b32_e32 v157, v111
	v_mov_b32_e32 v158, v112
	v_mov_b32_e32 v159, v113
	s_branch .LBB0_1196
	v_mul_f32_e32 v143, 0xbfb8aa3b, v118
	v_mul_f32_e32 v153, 0xbfb8aa3b, v119
	v_mul_f32_e32 v154, 0xbfb8aa3b, v120
	v_mul_f32_e32 v155, 0xbfb8aa3b, v121
	v_mul_f32_e32 v156, 0xbfb8aa3b, v110
	v_mul_f32_e32 v157, 0xbfb8aa3b, v111
	v_mul_f32_e32 v158, 0xbfb8aa3b, v112
	v_mul_f32_e32 v159, 0xbfb8aa3b, v113
	v_exp_f32_e32 v143, v143
	v_exp_f32_e32 v153, v153
	v_exp_f32_e32 v154, v154
	v_exp_f32_e32 v155, v155
	v_exp_f32_e32 v156, v156
	v_exp_f32_e32 v157, v157
	v_exp_f32_e32 v158, v158
	v_exp_f32_e32 v159, v159
	v_add_f32_e32 v143, 1.0, v143
	v_add_f32_e32 v153, 1.0, v153
	v_add_f32_e32 v154, 1.0, v154
	v_add_f32_e32 v155, 1.0, v155
	v_add_f32_e32 v156, 1.0, v156
	v_add_f32_e32 v157, 1.0, v157
	v_add_f32_e32 v158, 1.0, v158
	v_add_f32_e32 v159, 1.0, v159
	v_rcp_f32_e32 v143, v143
	v_rcp_f32_e32 v153, v153
	v_rcp_f32_e32 v154, v154
	v_rcp_f32_e32 v155, v155
	v_rcp_f32_e32 v156, v156
	v_rcp_f32_e32 v157, v157
	v_rcp_f32_e32 v158, v158
	v_rcp_f32_e32 v159, v159
.LBB0_1196:
	v_cvt_pk_bf16_f32 v176, v143, v153
	v_cvt_pk_bf16_f32 v177, v154, v155
	v_cvt_pk_bf16_f32 v178, v156, v157
	v_cvt_pk_bf16_f32 v179, v158, v159
	global_store_dwordx4 v[146:147], v[176:179], off offset:256
	s_and_b64 vcc, exec, s[8:9]
	v_mov_b32_e32 v143, v114
	v_mov_b32_e32 v153, v115
	v_mov_b32_e32 v154, v116
	v_mov_b32_e32 v155, v117
	v_mov_b32_e32 v156, v106
	v_mov_b32_e32 v157, v107
	v_mov_b32_e32 v158, v108
	v_mov_b32_e32 v159, v109
	s_branch .LBB0_1198
	v_mul_f32_e32 v146, 0xbfb8aa3b, v115
	v_exp_f32_e32 v146, v146
	v_mul_f32_e32 v147, 0xbfb8aa3b, v116
	v_exp_f32_e32 v147, v147
	v_mul_f32_e32 v153, 0xbfb8aa3b, v117
	v_exp_f32_e32 v155, v153
	v_add_f32_e32 v146, 1.0, v146
	v_rcp_f32_e32 v153, v146
	v_add_f32_e32 v146, 1.0, v147
	v_mul_f32_e32 v147, 0xbfb8aa3b, v106
	v_rcp_f32_e32 v154, v146
	v_add_f32_e32 v146, 1.0, v155
	v_exp_f32_e32 v147, v147
	v_mul_f32_e32 v155, 0xbfb8aa3b, v107
	v_exp_f32_e32 v157, v155
	v_rcp_f32_e32 v155, v146
	v_add_f32_e32 v146, 1.0, v147
	v_mul_f32_e32 v147, 0xbfb8aa3b, v108
	v_mul_f32_e32 v143, 0xbfb8aa3b, v114
	v_rcp_f32_e32 v156, v146
	v_add_f32_e32 v146, 1.0, v157
	v_exp_f32_e32 v147, v147
	v_mul_f32_e32 v157, 0xbfb8aa3b, v109
	v_exp_f32_e32 v143, v143
	v_exp_f32_e32 v159, v157
	v_rcp_f32_e32 v157, v146
	v_add_f32_e32 v146, 1.0, v147
	v_add_f32_e32 v143, 1.0, v143
	v_rcp_f32_e32 v158, v146
	v_add_f32_e32 v146, 1.0, v159
	v_rcp_f32_e32 v143, v143
	v_rcp_f32_e32 v159, v146
.LBB0_1198:
	v_add_u32_e32 v146, 16, v152
	v_mad_i64_i32 v[146:147], s[44:45], s27, v146, 0
	v_lshl_add_u64 v[146:147], v[146:147], 1, v[144:145]
	v_cvt_pk_bf16_f32 v176, v143, v153
	v_cvt_pk_bf16_f32 v177, v154, v155
	v_cvt_pk_bf16_f32 v178, v156, v157
	v_cvt_pk_bf16_f32 v179, v158, v159
	s_and_b64 vcc, exec, s[8:9]
	v_mov_b32_e32 v143, v102
	v_mov_b32_e32 v153, v103
	v_mov_b32_e32 v154, v104
	v_mov_b32_e32 v155, v105
	v_mov_b32_e32 v156, v94
	v_mov_b32_e32 v157, v95
	v_mov_b32_e32 v158, v96
	v_mov_b32_e32 v159, v97
	global_store_dwordx4 v[146:147], v[176:179], off
	s_branch .LBB0_1200
	v_mul_f32_e32 v143, 0xbfb8aa3b, v102
	v_mul_f32_e32 v153, 0xbfb8aa3b, v103
	v_mul_f32_e32 v154, 0xbfb8aa3b, v104
	v_mul_f32_e32 v155, 0xbfb8aa3b, v105
	v_mul_f32_e32 v156, 0xbfb8aa3b, v94
	v_mul_f32_e32 v157, 0xbfb8aa3b, v95
	v_mul_f32_e32 v158, 0xbfb8aa3b, v96
	v_mul_f32_e32 v159, 0xbfb8aa3b, v97
	v_exp_f32_e32 v143, v143
	v_exp_f32_e32 v153, v153
	v_exp_f32_e32 v154, v154
	v_exp_f32_e32 v155, v155
	v_exp_f32_e32 v156, v156
	v_exp_f32_e32 v157, v157
	v_exp_f32_e32 v158, v158
	v_exp_f32_e32 v159, v159
	v_add_f32_e32 v143, 1.0, v143
	v_add_f32_e32 v153, 1.0, v153
	v_add_f32_e32 v154, 1.0, v154
	v_add_f32_e32 v155, 1.0, v155
	v_add_f32_e32 v156, 1.0, v156
	v_add_f32_e32 v157, 1.0, v157
	v_add_f32_e32 v158, 1.0, v158
	v_add_f32_e32 v159, 1.0, v159
	v_rcp_f32_e32 v143, v143
	v_rcp_f32_e32 v153, v153
	v_rcp_f32_e32 v154, v154
	v_rcp_f32_e32 v155, v155
	v_rcp_f32_e32 v156, v156
	v_rcp_f32_e32 v157, v157
	v_rcp_f32_e32 v158, v158
	v_rcp_f32_e32 v159, v159
; __device__ __forceinline__ unsigned cvt_pk_bf16(float lo, float hi) { unsigned r; asm volatile("v_cvt_pk_bf16_f32 %0, %1, %2" : "=v"(r) : "v"(lo), "v"(hi)); return r; }
; __device__ __forceinline__ float sigm(float x) { return __builtin_amdgcn_rcpf(1.f + __builtin_amdgcn_exp2f(-1.4426950408889634f * x)); }
;     __device__ __forceinline__ void operator()(const f32x4 (&acc)[2][2][4][2], const Unit& u, int wr, int wc, int fr, int fq) const {
;     ...
;             const bool sg = u.pn >= 15;
;             bf16_t* base = sg ? G : P; const int ldc = sg ? NGATE : PP; const int colt = sg ? (u.pn - 15) * 256 : u.pn * 256;
; #pragma unroll
;             for (int ai = 0; ai < 2; ++ai)
; #pragma unroll
;                 for (int m = 0; m < 4; ++m) { bf16_t* rowp = base + (size_t)(row0 + ai * HALF + m * 16) * ldc + colt + cl0;
; #pragma unroll
;                     for (int bj = 0; bj < 2; ++bj) { f32x4 v0 = acc[ai][bj][m][0], v1 = acc[ai][bj][m][1];
;                         if (sg) { v0 = (f32x4){sigm(v0[0]), sigm(v0[1]), sigm(v0[2]), sigm(v0[3])}; v1 = (f32x4){sigm(v1[0]), sigm(v1[1]), sigm(v1[2]), sigm(v1[3])}; }
;                         u32x4 w; w.x = cvt_pk_bf16(v0[0], v0[1]); w.y = cvt_pk_bf16(v0[2], v0[3]); w.z = cvt_pk_bf16(v1[0], v1[1]); w.w = cvt_pk_bf16(v1[2], v1[3]);
;                         *(u32x4*)(rowp + bj * HALF) = w; }
;                     asm volatile("" ::: "memory"); }
.LBB0_1200:
	s_nop 0
	v_cvt_pk_bf16_f32 v176, v143, v153
	v_cvt_pk_bf16_f32 v177, v154, v155
	v_cvt_pk_bf16_f32 v178, v156, v157
	v_cvt_pk_bf16_f32 v179, v158, v159
	global_store_dwordx4 v[146:147], v[176:179], off offset:256
	s_and_b64 vcc, exec, s[8:9]
	v_mov_b32_e32 v143, v98
	v_mov_b32_e32 v153, v99
	v_mov_b32_e32 v154, v100
	v_mov_b32_e32 v155, v101
	v_mov_b32_e32 v156, v90
	v_mov_b32_e32 v157, v91
	v_mov_b32_e32 v158, v92
	v_mov_b32_e32 v159, v93
	s_branch .LBB0_1202
	v_mul_f32_e32 v146, 0xbfb8aa3b, v99
	v_exp_f32_e32 v146, v146
	v_mul_f32_e32 v147, 0xbfb8aa3b, v100
	v_exp_f32_e32 v147, v147
	v_mul_f32_e32 v153, 0xbfb8aa3b, v101
	v_exp_f32_e32 v155, v153
	v_add_f32_e32 v146, 1.0, v146
	v_rcp_f32_e32 v153, v146
	v_add_f32_e32 v146, 1.0, v147
	v_mul_f32_e32 v147, 0xbfb8aa3b, v90
	v_rcp_f32_e32 v154, v146
	v_add_f32_e32 v146, 1.0, v155
	v_exp_f32_e32 v147, v147
	v_mul_f32_e32 v155, 0xbfb8aa3b, v91
	v_exp_f32_e32 v157, v155
	v_rcp_f32_e32 v155, v146
	v_add_f32_e32 v146, 1.0, v147
	v_mul_f32_e32 v147, 0xbfb8aa3b, v92
	v_mul_f32_e32 v143, 0xbfb8aa3b, v98
	v_rcp_f32_e32 v156, v146
	v_add_f32_e32 v146, 1.0, v157
	v_exp_f32_e32 v147, v147
	v_mul_f32_e32 v157, 0xbfb8aa3b, v93
	v_exp_f32_e32 v143, v143
	v_exp_f32_e32 v159, v157
	v_rcp_f32_e32 v157, v146
	v_add_f32_e32 v146, 1.0, v147
	v_add_f32_e32 v143, 1.0, v143
	v_rcp_f32_e32 v158, v146
	v_add_f32_e32 v146, 1.0, v159
	v_rcp_f32_e32 v143, v143
	v_rcp_f32_e32 v159, v146
.LBB0_1202:
	v_add_u32_e32 v146, 32, v152
	v_mad_i64_i32 v[146:147], s[44:45], s27, v146, 0
	v_lshl_add_u64 v[146:147], v[146:147], 1, v[144:145]
	v_cvt_pk_bf16_f32 v176, v143, v153
	v_cvt_pk_bf16_f32 v177, v154, v155
	v_cvt_pk_bf16_f32 v178, v156, v157
	v_cvt_pk_bf16_f32 v179, v158, v159
	s_and_b64 vcc, exec, s[8:9]
	v_mov_b32_e32 v143, v86
	v_mov_b32_e32 v153, v87
	v_mov_b32_e32 v154, v88
	v_mov_b32_e32 v155, v89
	v_mov_b32_e32 v156, v78
	v_mov_b32_e32 v157, v79
	v_mov_b32_e32 v158, v80
	v_mov_b32_e32 v159, v81
	global_store_dwordx4 v[146:147], v[176:179], off
	s_branch .LBB0_1204
	v_mul_f32_e32 v143, 0xbfb8aa3b, v86
	v_mul_f32_e32 v153, 0xbfb8aa3b, v87
	v_mul_f32_e32 v154, 0xbfb8aa3b, v88
	v_mul_f32_e32 v155, 0xbfb8aa3b, v89
	v_mul_f32_e32 v156, 0xbfb8aa3b, v78
	v_mul_f32_e32 v157, 0xbfb8aa3b, v79
	v_mul_f32_e32 v158, 0xbfb8aa3b, v80
	v_mul_f32_e32 v159, 0xbfb8aa3b, v81
	v_exp_f32_e32 v143, v143
	v_exp_f32_e32 v153, v153
	v_exp_f32_e32 v154, v154
	v_exp_f32_e32 v155, v155
	v_exp_f32_e32 v156, v156
	v_exp_f32_e32 v157, v157
	v_exp_f32_e32 v158, v158
	v_exp_f32_e32 v159, v159
	v_add_f32_e32 v143, 1.0, v143
	v_add_f32_e32 v153, 1.0, v153
	v_add_f32_e32 v154, 1.0, v154
	v_add_f32_e32 v155, 1.0, v155
	v_add_f32_e32 v156, 1.0, v156
	v_add_f32_e32 v157, 1.0, v157
	v_add_f32_e32 v158, 1.0, v158
	v_add_f32_e32 v159, 1.0, v159
	v_rcp_f32_e32 v143, v143
	v_rcp_f32_e32 v153, v153
	v_rcp_f32_e32 v154, v154
	v_rcp_f32_e32 v155, v155
	v_rcp_f32_e32 v156, v156
	v_rcp_f32_e32 v157, v157
	v_rcp_f32_e32 v158, v158
	v_rcp_f32_e32 v159, v159
.LBB0_1204:
	s_nop 0
	v_cvt_pk_bf16_f32 v176, v143, v153
	v_cvt_pk_bf16_f32 v177, v154, v155
	v_cvt_pk_bf16_f32 v178, v156, v157
	v_cvt_pk_bf16_f32 v179, v158, v159
	global_store_dwordx4 v[146:147], v[176:179], off offset:256
	s_and_b64 vcc, exec, s[8:9]
	v_mov_b32_e32 v143, v82
	v_mov_b32_e32 v153, v83
	v_mov_b32_e32 v154, v84
	v_mov_b32_e32 v155, v85
	v_mov_b32_e32 v156, v74
	v_mov_b32_e32 v157, v75
	v_mov_b32_e32 v158, v76
	v_mov_b32_e32 v159, v77
	s_branch .LBB0_1206
	v_mul_f32_e32 v146, 0xbfb8aa3b, v83
	v_exp_f32_e32 v146, v146
	v_mul_f32_e32 v147, 0xbfb8aa3b, v84
	v_exp_f32_e32 v147, v147
	v_mul_f32_e32 v153, 0xbfb8aa3b, v85
	v_exp_f32_e32 v155, v153
	v_add_f32_e32 v146, 1.0, v146
	v_rcp_f32_e32 v153, v146
	v_add_f32_e32 v146, 1.0, v147
	v_mul_f32_e32 v147, 0xbfb8aa3b, v74
	v_rcp_f32_e32 v154, v146
	v_add_f32_e32 v146, 1.0, v155
	v_exp_f32_e32 v147, v147
	v_mul_f32_e32 v155, 0xbfb8aa3b, v75
	v_exp_f32_e32 v157, v155
	v_rcp_f32_e32 v155, v146
	v_add_f32_e32 v146, 1.0, v147
	v_mul_f32_e32 v147, 0xbfb8aa3b, v76
	v_mul_f32_e32 v143, 0xbfb8aa3b, v82
	v_rcp_f32_e32 v156, v146
	v_add_f32_e32 v146, 1.0, v157
	v_exp_f32_e32 v147, v147
	v_mul_f32_e32 v157, 0xbfb8aa3b, v77
	v_exp_f32_e32 v143, v143
	v_exp_f32_e32 v159, v157
	v_rcp_f32_e32 v157, v146
	v_add_f32_e32 v146, 1.0, v147
	v_add_f32_e32 v143, 1.0, v143
	v_rcp_f32_e32 v158, v146
	v_add_f32_e32 v146, 1.0, v159
	v_rcp_f32_e32 v143, v143
	v_rcp_f32_e32 v159, v146
.LBB0_1206:
	v_add_u32_e32 v146, 48, v152
	v_mad_i64_i32 v[146:147], s[44:45], s27, v146, 0
	v_lshl_add_u64 v[146:147], v[146:147], 1, v[144:145]
	v_cvt_pk_bf16_f32 v176, v143, v153
	v_cvt_pk_bf16_f32 v177, v154, v155
	v_cvt_pk_bf16_f32 v178, v156, v157
	v_cvt_pk_bf16_f32 v179, v158, v159
	s_and_b64 vcc, exec, s[8:9]
	v_mov_b32_e32 v143, v70
	v_mov_b32_e32 v153, v71
	v_mov_b32_e32 v154, v72
	v_mov_b32_e32 v155, v73
	v_mov_b32_e32 v156, v66
	v_mov_b32_e32 v157, v67
	v_mov_b32_e32 v158, v68
	v_mov_b32_e32 v159, v69
	global_store_dwordx4 v[146:147], v[176:179], off
	s_branch .LBB0_1208
	v_mul_f32_e32 v143, 0xbfb8aa3b, v70
	v_mul_f32_e32 v153, 0xbfb8aa3b, v71
	v_mul_f32_e32 v154, 0xbfb8aa3b, v72
	v_mul_f32_e32 v155, 0xbfb8aa3b, v73
	v_mul_f32_e32 v156, 0xbfb8aa3b, v66
	v_mul_f32_e32 v157, 0xbfb8aa3b, v67
	v_mul_f32_e32 v158, 0xbfb8aa3b, v68
	v_mul_f32_e32 v159, 0xbfb8aa3b, v69
	v_exp_f32_e32 v143, v143
	v_exp_f32_e32 v153, v153
	v_exp_f32_e32 v154, v154
	v_exp_f32_e32 v155, v155
	v_exp_f32_e32 v156, v156
	v_exp_f32_e32 v157, v157
	v_exp_f32_e32 v158, v158
	v_exp_f32_e32 v159, v159
	v_add_f32_e32 v143, 1.0, v143
	v_add_f32_e32 v153, 1.0, v153
	v_add_f32_e32 v154, 1.0, v154
	v_add_f32_e32 v155, 1.0, v155
	v_add_f32_e32 v156, 1.0, v156
	v_add_f32_e32 v157, 1.0, v157
	v_add_f32_e32 v158, 1.0, v158
	v_add_f32_e32 v159, 1.0, v159
	v_rcp_f32_e32 v143, v143
	v_rcp_f32_e32 v153, v153
	v_rcp_f32_e32 v154, v154
	v_rcp_f32_e32 v155, v155
	v_rcp_f32_e32 v156, v156
	v_rcp_f32_e32 v157, v157
	v_rcp_f32_e32 v158, v158
	v_rcp_f32_e32 v159, v159
; __device__ __forceinline__ unsigned cvt_pk_bf16(float lo, float hi) { unsigned r; asm volatile("v_cvt_pk_bf16_f32 %0, %1, %2" : "=v"(r) : "v"(lo), "v"(hi)); return r; }
; __device__ __forceinline__ float sigm(float x) { return __builtin_amdgcn_rcpf(1.f + __builtin_amdgcn_exp2f(-1.4426950408889634f * x)); }
;     __device__ __forceinline__ void operator()(const f32x4 (&acc)[2][2][4][2], const Unit& u, int wr, int wc, int fr, int fq) const {
;     ...
;             const bool sg = u.pn >= 15;
;             bf16_t* base = sg ? G : P; const int ldc = sg ? NGATE : PP; const int colt = sg ? (u.pn - 15) * 256 : u.pn * 256;
; #pragma unroll
;             for (int ai = 0; ai < 2; ++ai)
; #pragma unroll
;                 for (int m = 0; m < 4; ++m) { bf16_t* rowp = base + (size_t)(row0 + ai * HALF + m * 16) * ldc + colt + cl0;
; #pragma unroll
;                     for (int bj = 0; bj < 2; ++bj) { f32x4 v0 = acc[ai][bj][m][0], v1 = acc[ai][bj][m][1];
;                         if (sg) { v0 = (f32x4){sigm(v0[0]), sigm(v0[1]), sigm(v0[2]), sigm(v0[3])}; v1 = (f32x4){sigm(v1[0]), sigm(v1[1]), sigm(v1[2]), sigm(v1[3])}; }
;                         u32x4 w; w.x = cvt_pk_bf16(v0[0], v0[1]); w.y = cvt_pk_bf16(v0[2], v0[3]); w.z = cvt_pk_bf16(v1[0], v1[1]); w.w = cvt_pk_bf16(v1[2], v1[3]);
;                         *(u32x4*)(rowp + bj * HALF) = w; }
;                     asm volatile("" ::: "memory"); }
.LBB0_1208:
	s_nop 0
	v_cvt_pk_bf16_f32 v176, v143, v153
	v_cvt_pk_bf16_f32 v177, v154, v155
	v_cvt_pk_bf16_f32 v178, v156, v157
	v_cvt_pk_bf16_f32 v179, v158, v159
	global_store_dwordx4 v[146:147], v[176:179], off offset:256
	s_and_b64 vcc, exec, s[8:9]
	v_mov_b32_e32 v143, v62
	v_mov_b32_e32 v153, v63
	v_mov_b32_e32 v154, v64
	v_mov_b32_e32 v155, v65
	v_mov_b32_e32 v156, v58
	v_mov_b32_e32 v157, v59
	v_mov_b32_e32 v158, v60
	v_mov_b32_e32 v159, v61
	s_branch .LBB0_1210
	v_mul_f32_e32 v146, 0xbfb8aa3b, v63
	v_exp_f32_e32 v146, v146
	v_mul_f32_e32 v147, 0xbfb8aa3b, v64
	v_exp_f32_e32 v147, v147
	v_mul_f32_e32 v153, 0xbfb8aa3b, v65
	v_exp_f32_e32 v155, v153
	v_add_f32_e32 v146, 1.0, v146
	v_rcp_f32_e32 v153, v146
	v_add_f32_e32 v146, 1.0, v147
	v_mul_f32_e32 v147, 0xbfb8aa3b, v58
	v_rcp_f32_e32 v154, v146
	v_add_f32_e32 v146, 1.0, v155
	v_exp_f32_e32 v147, v147
	v_mul_f32_e32 v155, 0xbfb8aa3b, v59
	v_exp_f32_e32 v157, v155
	v_rcp_f32_e32 v155, v146
	v_add_f32_e32 v146, 1.0, v147
	v_mul_f32_e32 v147, 0xbfb8aa3b, v60
	v_mul_f32_e32 v143, 0xbfb8aa3b, v62
	v_rcp_f32_e32 v156, v146
	v_add_f32_e32 v146, 1.0, v157
	v_exp_f32_e32 v147, v147
	v_mul_f32_e32 v157, 0xbfb8aa3b, v61
	v_exp_f32_e32 v143, v143
	v_exp_f32_e32 v159, v157
	v_rcp_f32_e32 v157, v146
	v_add_f32_e32 v146, 1.0, v147
	v_add_f32_e32 v143, 1.0, v143
	v_rcp_f32_e32 v158, v146
	v_add_f32_e32 v146, 1.0, v159
	v_rcp_f32_e32 v143, v143
	v_rcp_f32_e32 v159, v146
.LBB0_1210:
	v_add_u32_e32 v146, 0x80, v152
	v_mad_i64_i32 v[146:147], s[44:45], s27, v146, 0
	v_lshl_add_u64 v[146:147], v[146:147], 1, v[144:145]
	v_cvt_pk_bf16_f32 v176, v143, v153
	v_cvt_pk_bf16_f32 v177, v154, v155
	v_cvt_pk_bf16_f32 v178, v156, v157
	v_cvt_pk_bf16_f32 v179, v158, v159
	s_and_b64 vcc, exec, s[8:9]
	v_mov_b32_e32 v143, v54
	v_mov_b32_e32 v153, v55
	v_mov_b32_e32 v154, v56
	v_mov_b32_e32 v155, v57
	v_mov_b32_e32 v156, v46
	v_mov_b32_e32 v157, v47
	v_mov_b32_e32 v158, v48
	v_mov_b32_e32 v159, v49
	global_store_dwordx4 v[146:147], v[176:179], off
	s_branch .LBB0_1212
	v_mul_f32_e32 v143, 0xbfb8aa3b, v54
	v_mul_f32_e32 v153, 0xbfb8aa3b, v55
	v_mul_f32_e32 v154, 0xbfb8aa3b, v56
	v_mul_f32_e32 v155, 0xbfb8aa3b, v57
	v_mul_f32_e32 v156, 0xbfb8aa3b, v46
	v_mul_f32_e32 v157, 0xbfb8aa3b, v47
	v_mul_f32_e32 v158, 0xbfb8aa3b, v48
	v_mul_f32_e32 v159, 0xbfb8aa3b, v49
	v_exp_f32_e32 v143, v143
	v_exp_f32_e32 v153, v153
	v_exp_f32_e32 v154, v154
	v_exp_f32_e32 v155, v155
	v_exp_f32_e32 v156, v156
	v_exp_f32_e32 v157, v157
	v_exp_f32_e32 v158, v158
	v_exp_f32_e32 v159, v159
	v_add_f32_e32 v143, 1.0, v143
	v_add_f32_e32 v153, 1.0, v153
	v_add_f32_e32 v154, 1.0, v154
	v_add_f32_e32 v155, 1.0, v155
	v_add_f32_e32 v156, 1.0, v156
	v_add_f32_e32 v157, 1.0, v157
	v_add_f32_e32 v158, 1.0, v158
	v_add_f32_e32 v159, 1.0, v159
	v_rcp_f32_e32 v143, v143
	v_rcp_f32_e32 v153, v153
	v_rcp_f32_e32 v154, v154
	v_rcp_f32_e32 v155, v155
	v_rcp_f32_e32 v156, v156
	v_rcp_f32_e32 v157, v157
	v_rcp_f32_e32 v158, v158
	v_rcp_f32_e32 v159, v159
.LBB0_1212:
	s_nop 0
	v_cvt_pk_bf16_f32 v176, v143, v153
	v_cvt_pk_bf16_f32 v177, v154, v155
	v_cvt_pk_bf16_f32 v178, v156, v157
	v_cvt_pk_bf16_f32 v179, v158, v159
	global_store_dwordx4 v[146:147], v[176:179], off offset:256
	s_and_b64 vcc, exec, s[8:9]
	v_mov_b32_e32 v143, v50
	v_mov_b32_e32 v153, v51
	v_mov_b32_e32 v154, v52
	v_mov_b32_e32 v155, v53
	v_mov_b32_e32 v156, v42
	v_mov_b32_e32 v157, v43
	v_mov_b32_e32 v158, v44
	v_mov_b32_e32 v159, v45
	s_branch .LBB0_1214
	v_mul_f32_e32 v146, 0xbfb8aa3b, v51
	v_exp_f32_e32 v146, v146
	v_mul_f32_e32 v147, 0xbfb8aa3b, v52
	v_exp_f32_e32 v147, v147
	v_mul_f32_e32 v153, 0xbfb8aa3b, v53
	v_exp_f32_e32 v155, v153
	v_add_f32_e32 v146, 1.0, v146
	v_rcp_f32_e32 v153, v146
	v_add_f32_e32 v146, 1.0, v147
	v_mul_f32_e32 v147, 0xbfb8aa3b, v42
	v_rcp_f32_e32 v154, v146
	v_add_f32_e32 v146, 1.0, v155
	v_exp_f32_e32 v147, v147
	v_mul_f32_e32 v155, 0xbfb8aa3b, v43
	v_exp_f32_e32 v157, v155
	v_rcp_f32_e32 v155, v146
	v_add_f32_e32 v146, 1.0, v147
	v_mul_f32_e32 v147, 0xbfb8aa3b, v44
	v_mul_f32_e32 v143, 0xbfb8aa3b, v50
	v_rcp_f32_e32 v156, v146
	v_add_f32_e32 v146, 1.0, v157
	v_exp_f32_e32 v147, v147
	v_mul_f32_e32 v157, 0xbfb8aa3b, v45
	v_exp_f32_e32 v143, v143
	v_exp_f32_e32 v159, v157
	v_rcp_f32_e32 v157, v146
	v_add_f32_e32 v146, 1.0, v147
	v_add_f32_e32 v143, 1.0, v143
	v_rcp_f32_e32 v158, v146
	v_add_f32_e32 v146, 1.0, v159
	v_rcp_f32_e32 v143, v143
	v_rcp_f32_e32 v159, v146
.LBB0_1214:
	v_add_u32_e32 v146, 0x90, v152
	v_mad_i64_i32 v[146:147], s[44:45], s27, v146, 0
	v_lshl_add_u64 v[146:147], v[146:147], 1, v[144:145]
	v_cvt_pk_bf16_f32 v176, v143, v153
	v_cvt_pk_bf16_f32 v177, v154, v155
	v_cvt_pk_bf16_f32 v178, v156, v157
	v_cvt_pk_bf16_f32 v179, v158, v159
	s_and_b64 vcc, exec, s[8:9]
	v_mov_b32_e32 v143, v38
	v_mov_b32_e32 v153, v39
	v_mov_b32_e32 v154, v40
	v_mov_b32_e32 v155, v41
	v_mov_b32_e32 v156, v30
	v_mov_b32_e32 v157, v31
	v_mov_b32_e32 v158, v32
	v_mov_b32_e32 v159, v33
	global_store_dwordx4 v[146:147], v[176:179], off
	s_branch .LBB0_1216
	v_mul_f32_e32 v143, 0xbfb8aa3b, v38
	v_mul_f32_e32 v153, 0xbfb8aa3b, v39
	v_mul_f32_e32 v154, 0xbfb8aa3b, v40
	v_mul_f32_e32 v155, 0xbfb8aa3b, v41
	v_mul_f32_e32 v156, 0xbfb8aa3b, v30
	v_mul_f32_e32 v157, 0xbfb8aa3b, v31
	v_mul_f32_e32 v158, 0xbfb8aa3b, v32
	v_mul_f32_e32 v159, 0xbfb8aa3b, v33
	v_exp_f32_e32 v143, v143
	v_exp_f32_e32 v153, v153
	v_exp_f32_e32 v154, v154
	v_exp_f32_e32 v155, v155
	v_exp_f32_e32 v156, v156
	v_exp_f32_e32 v157, v157
	v_exp_f32_e32 v158, v158
	v_exp_f32_e32 v159, v159
	v_add_f32_e32 v143, 1.0, v143
	v_add_f32_e32 v153, 1.0, v153
	v_add_f32_e32 v154, 1.0, v154
	v_add_f32_e32 v155, 1.0, v155
	v_add_f32_e32 v156, 1.0, v156
	v_add_f32_e32 v157, 1.0, v157
	v_add_f32_e32 v158, 1.0, v158
	v_add_f32_e32 v159, 1.0, v159
	v_rcp_f32_e32 v143, v143
	v_rcp_f32_e32 v153, v153
	v_rcp_f32_e32 v154, v154
	v_rcp_f32_e32 v155, v155
	v_rcp_f32_e32 v156, v156
	v_rcp_f32_e32 v157, v157
	v_rcp_f32_e32 v158, v158
	v_rcp_f32_e32 v159, v159
; __device__ __forceinline__ unsigned cvt_pk_bf16(float lo, float hi) { unsigned r; asm volatile("v_cvt_pk_bf16_f32 %0, %1, %2" : "=v"(r) : "v"(lo), "v"(hi)); return r; }
; __device__ __forceinline__ float sigm(float x) { return __builtin_amdgcn_rcpf(1.f + __builtin_amdgcn_exp2f(-1.4426950408889634f * x)); }
;     __device__ __forceinline__ void operator()(const f32x4 (&acc)[2][2][4][2], const Unit& u, int wr, int wc, int fr, int fq) const {
;     ...
;             const bool sg = u.pn >= 15;
;             bf16_t* base = sg ? G : P; const int ldc = sg ? NGATE : PP; const int colt = sg ? (u.pn - 15) * 256 : u.pn * 256;
; #pragma unroll
;             for (int ai = 0; ai < 2; ++ai)
; #pragma unroll
;                 for (int m = 0; m < 4; ++m) { bf16_t* rowp = base + (size_t)(row0 + ai * HALF + m * 16) * ldc + colt + cl0;
; #pragma unroll
;                     for (int bj = 0; bj < 2; ++bj) { f32x4 v0 = acc[ai][bj][m][0], v1 = acc[ai][bj][m][1];
;                         if (sg) { v0 = (f32x4){sigm(v0[0]), sigm(v0[1]), sigm(v0[2]), sigm(v0[3])}; v1 = (f32x4){sigm(v1[0]), sigm(v1[1]), sigm(v1[2]), sigm(v1[3])}; }
;                         u32x4 w; w.x = cvt_pk_bf16(v0[0], v0[1]); w.y = cvt_pk_bf16(v0[2], v0[3]); w.z = cvt_pk_bf16(v1[0], v1[1]); w.w = cvt_pk_bf16(v1[2], v1[3]);
;                         *(u32x4*)(rowp + bj * HALF) = w; }
;                     asm volatile("" ::: "memory"); }
.LBB0_1216:
	s_nop 0
	v_cvt_pk_bf16_f32 v176, v143, v153
	v_cvt_pk_bf16_f32 v177, v154, v155
	v_cvt_pk_bf16_f32 v178, v156, v157
	v_cvt_pk_bf16_f32 v179, v158, v159
	global_store_dwordx4 v[146:147], v[176:179], off offset:256
	s_and_b64 vcc, exec, s[8:9]
	v_mov_b32_e32 v143, v34
	v_mov_b32_e32 v153, v35
	v_mov_b32_e32 v154, v36
	v_mov_b32_e32 v155, v37
	v_mov_b32_e32 v156, v26
	v_mov_b32_e32 v157, v27
	v_mov_b32_e32 v158, v28
	v_mov_b32_e32 v159, v29
	s_branch .LBB0_1218
	v_mul_f32_e32 v146, 0xbfb8aa3b, v35
	v_exp_f32_e32 v146, v146
	v_mul_f32_e32 v147, 0xbfb8aa3b, v36
	v_exp_f32_e32 v147, v147
	v_mul_f32_e32 v153, 0xbfb8aa3b, v37
	v_exp_f32_e32 v155, v153
	v_add_f32_e32 v146, 1.0, v146
	v_rcp_f32_e32 v153, v146
	v_add_f32_e32 v146, 1.0, v147
	v_mul_f32_e32 v147, 0xbfb8aa3b, v26
	v_rcp_f32_e32 v154, v146
	v_add_f32_e32 v146, 1.0, v155
	v_exp_f32_e32 v147, v147
	v_mul_f32_e32 v155, 0xbfb8aa3b, v27
	v_exp_f32_e32 v157, v155
	v_rcp_f32_e32 v155, v146
	v_add_f32_e32 v146, 1.0, v147
	v_mul_f32_e32 v147, 0xbfb8aa3b, v28
	v_mul_f32_e32 v143, 0xbfb8aa3b, v34
	v_rcp_f32_e32 v156, v146
	v_add_f32_e32 v146, 1.0, v157
	v_exp_f32_e32 v147, v147
	v_mul_f32_e32 v157, 0xbfb8aa3b, v29
	v_exp_f32_e32 v143, v143
	v_exp_f32_e32 v159, v157
	v_rcp_f32_e32 v157, v146
	v_add_f32_e32 v146, 1.0, v147
	v_add_f32_e32 v143, 1.0, v143
	v_rcp_f32_e32 v158, v146
	v_add_f32_e32 v146, 1.0, v159
	v_rcp_f32_e32 v143, v143
	v_rcp_f32_e32 v159, v146
.LBB0_1218:
	v_add_u32_e32 v146, 0xa0, v152
	v_mad_i64_i32 v[146:147], s[44:45], s27, v146, 0
	v_lshl_add_u64 v[146:147], v[146:147], 1, v[144:145]
	v_cvt_pk_bf16_f32 v176, v143, v153
	v_cvt_pk_bf16_f32 v177, v154, v155
	v_cvt_pk_bf16_f32 v178, v156, v157
	v_cvt_pk_bf16_f32 v179, v158, v159
	s_and_b64 vcc, exec, s[8:9]
	v_mov_b32_e32 v143, v22
	v_mov_b32_e32 v153, v23
	v_mov_b32_e32 v154, v24
	v_mov_b32_e32 v155, v25
	v_mov_b32_e32 v156, v14
	v_mov_b32_e32 v157, v15
	v_mov_b32_e32 v158, v16
	v_mov_b32_e32 v159, v17
	global_store_dwordx4 v[146:147], v[176:179], off
	s_branch .LBB0_1220
	v_mul_f32_e32 v143, 0xbfb8aa3b, v22
	v_mul_f32_e32 v153, 0xbfb8aa3b, v23
	v_mul_f32_e32 v154, 0xbfb8aa3b, v24
	v_mul_f32_e32 v155, 0xbfb8aa3b, v25
	v_mul_f32_e32 v156, 0xbfb8aa3b, v14
	v_mul_f32_e32 v157, 0xbfb8aa3b, v15
	v_mul_f32_e32 v158, 0xbfb8aa3b, v16
	v_mul_f32_e32 v159, 0xbfb8aa3b, v17
	v_exp_f32_e32 v143, v143
	v_exp_f32_e32 v153, v153
	v_exp_f32_e32 v154, v154
	v_exp_f32_e32 v155, v155
	v_exp_f32_e32 v156, v156
	v_exp_f32_e32 v157, v157
	v_exp_f32_e32 v158, v158
	v_exp_f32_e32 v159, v159
	v_add_f32_e32 v143, 1.0, v143
	v_add_f32_e32 v153, 1.0, v153
	v_add_f32_e32 v154, 1.0, v154
	v_add_f32_e32 v155, 1.0, v155
	v_add_f32_e32 v156, 1.0, v156
	v_add_f32_e32 v157, 1.0, v157
	v_add_f32_e32 v158, 1.0, v158
	v_add_f32_e32 v159, 1.0, v159
	v_rcp_f32_e32 v143, v143
	v_rcp_f32_e32 v153, v153
	v_rcp_f32_e32 v154, v154
	v_rcp_f32_e32 v155, v155
	v_rcp_f32_e32 v156, v156
	v_rcp_f32_e32 v157, v157
	v_rcp_f32_e32 v158, v158
	v_rcp_f32_e32 v159, v159
.LBB0_1220:
	s_nop 0
	v_cvt_pk_bf16_f32 v176, v143, v153
	v_cvt_pk_bf16_f32 v177, v154, v155
	v_cvt_pk_bf16_f32 v178, v156, v157
	v_cvt_pk_bf16_f32 v179, v158, v159
	global_store_dwordx4 v[146:147], v[176:179], off offset:256
	s_and_b64 vcc, exec, s[8:9]
	v_mov_b32_e32 v143, v18
	v_mov_b32_e32 v146, v19
	v_mov_b32_e32 v147, v20
	v_mov_b32_e32 v153, v21
	v_mov_b32_e32 v154, v10
	v_mov_b32_e32 v155, v11
	v_mov_b32_e32 v156, v12
	v_mov_b32_e32 v157, v13
	s_branch .LBB0_1222
	v_mul_f32_e32 v143, 0xbfb8aa3b, v18
	v_mul_f32_e32 v146, 0xbfb8aa3b, v19
	v_mul_f32_e32 v147, 0xbfb8aa3b, v20
	v_mul_f32_e32 v153, 0xbfb8aa3b, v21
	v_mul_f32_e32 v154, 0xbfb8aa3b, v10
	v_mul_f32_e32 v155, 0xbfb8aa3b, v11
	v_mul_f32_e32 v156, 0xbfb8aa3b, v12
	v_mul_f32_e32 v157, 0xbfb8aa3b, v13
	v_exp_f32_e32 v143, v143
	v_exp_f32_e32 v146, v146
	v_exp_f32_e32 v147, v147
	v_exp_f32_e32 v153, v153
	v_exp_f32_e32 v154, v154
	v_exp_f32_e32 v155, v155
	v_exp_f32_e32 v156, v156
	v_exp_f32_e32 v157, v157
	v_add_f32_e32 v143, 1.0, v143
	v_add_f32_e32 v146, 1.0, v146
	v_add_f32_e32 v147, 1.0, v147
	v_add_f32_e32 v153, 1.0, v153
	v_add_f32_e32 v154, 1.0, v154
	v_add_f32_e32 v155, 1.0, v155
	v_add_f32_e32 v156, 1.0, v156
	v_add_f32_e32 v157, 1.0, v157
	v_rcp_f32_e32 v143, v143
	v_rcp_f32_e32 v146, v146
	v_rcp_f32_e32 v147, v147
	v_rcp_f32_e32 v153, v153
	v_rcp_f32_e32 v154, v154
	v_rcp_f32_e32 v155, v155
	v_rcp_f32_e32 v156, v156
	v_rcp_f32_e32 v157, v157
.LBB0_1222:
	v_add_u32_e32 v158, 0xb0, v152
	v_mad_i64_i32 v[158:159], s[44:45], s27, v158, 0
	v_lshl_add_u64 v[144:145], v[158:159], 1, v[144:145]
	v_cvt_pk_bf16_f32 v158, v143, v146
	v_cvt_pk_bf16_f32 v159, v147, v153
	v_cvt_pk_bf16_f32 v160, v154, v155
	v_cvt_pk_bf16_f32 v161, v156, v157
	s_and_b64 vcc, exec, s[8:9]
	v_mov_b32_e32 v143, v6
	v_mov_b32_e32 v146, v7
	v_mov_b32_e32 v147, v8
	v_mov_b32_e32 v153, v9
	v_mov_b32_e32 v154, v2
	v_mov_b32_e32 v156, v3
	v_mov_b32_e32 v155, v4
	v_mov_b32_e32 v157, v5
	global_store_dwordx4 v[144:145], v[158:161], off
	s_branch .LBB0_1224
	v_mul_f32_e32 v155, 0xbfb8aa3b, v3
	v_mul_f32_e32 v156, 0xbfb8aa3b, v4
	v_mul_f32_e32 v143, 0xbfb8aa3b, v6
	v_mul_f32_e32 v146, 0xbfb8aa3b, v7
	v_mul_f32_e32 v147, 0xbfb8aa3b, v8
	v_mul_f32_e32 v153, 0xbfb8aa3b, v9
	v_mul_f32_e32 v154, 0xbfb8aa3b, v2
	v_exp_f32_e32 v155, v155
	v_exp_f32_e32 v157, v156
	v_mul_f32_e32 v156, 0xbfb8aa3b, v5
	v_exp_f32_e32 v143, v143
	v_exp_f32_e32 v146, v146
	v_exp_f32_e32 v147, v147
	v_exp_f32_e32 v153, v153
	v_exp_f32_e32 v154, v154
	v_exp_f32_e32 v158, v156
	v_add_f32_e32 v155, 1.0, v155
	v_add_f32_e32 v143, 1.0, v143
	v_add_f32_e32 v146, 1.0, v146
	v_add_f32_e32 v147, 1.0, v147
	v_add_f32_e32 v153, 1.0, v153
	v_add_f32_e32 v154, 1.0, v154
	v_rcp_f32_e32 v156, v155
	v_add_f32_e32 v155, 1.0, v157
	v_add_f32_e32 v157, 1.0, v158
	v_rcp_f32_e32 v143, v143
	v_rcp_f32_e32 v146, v146
	v_rcp_f32_e32 v147, v147
	v_rcp_f32_e32 v153, v153
	v_rcp_f32_e32 v154, v154
	v_rcp_f32_e32 v155, v155
	v_rcp_f32_e32 v157, v157
